# v23 + deleted the per-MFMA-block s_setprio 1/0 flips in all 9 GEMM main loops (both wave halves stay at priority 0)
# baseline (speedup 1.0000x reference)
; #define PG8_STAGE(bufoff, gbase, voff) do { _Pragma("unroll") for (int _i = 0; _i < 2; ++_i) \
;         __builtin_amdgcn_global_load_lds((const unsigned*)((const char*)(gbase) + (voff)[_i]), (LAS unsigned*)(lds + (bufoff) + ldsw + _i * 8192), 16, 0, 0); } while (0)
; #define PG8_LDA(dst, b, h) do { _Pragma("unroll") for (int m = 0; m < 4; ++m) _Pragma("unroll") for (int k = 0; k < 2; ++k) dst[m][k] = *(const LAS bf16x8*)(lds + PG8_SA(b, h) + aoff + m * 2048 + k * 1024); } while (0)
; #define PG8_LDB(dst, b, h) do { _Pragma("unroll") for (int n = 0; n < 2; ++n) _Pragma("unroll") for (int k = 0; k < 2; ++k) dst[n][k] = *(const LAS bf16x8*)(lds + PG8_SB(b, h) + boff + n * 2048 + k * 1024); } while (0)
; #define PG8_MMA(ai, bj, At, Bt) do { __builtin_amdgcn_s_setprio(1); _Pragma("unroll") for (int m = 0; m < 4; ++m) _Pragma("unroll") for (int n = 0; n < 2; ++n) _Pragma("unroll") for (int k = 0; k < 2; ++k) \
;         acc[ai][bj][m][n] = __builtin_amdgcn_mfma_f32_16x16x32_bf16(Bt[n][k], At[m][k], acc[ai][bj][m][n], 0, 0, 0); __builtin_amdgcn_s_setprio(0); } while (0)
; #define PG8_WAIT_V(n) asm volatile("s_waitcnt vmcnt(" #n ")" ::: "memory")
; #define PG8_BAR __builtin_amdgcn_s_barrier()
; template <class Epi, class Sched>
; __device__ __forceinline__ void gemm_phase(LAS unsigned char* lds, const Gemm g, const Sched& S, const Epi& E) {
;     ...
;             PG8_LDB(B0, 0, 0); PG8_LDB(B1, 0, 1); PG8_SCHED; PG8_LDA(At, 0, 0); PG8_STAGE(PG8_SA(1, 1), a1 + hsA, voffA);
;             PG8_WAIT_V(8); PG8_WAIT_L(0); PG8_BAR; PG8_MMA(0, 0, At, B0); PG8_MMA(0, 1, At, B1); PG8_BAR; PG8_SCHED;
;             PG8_LDA(At, 0, 1); PG8_STAGE(PG8_SB(0, 0), b2, voffB); PG8_STAGE(PG8_SB(0, 1), b2 + hsB, voffB); PG8_STAGE(PG8_SA(0, 0), a2, voffA);
;             PG8_WAIT_V(8); PG8_WAIT_L(0); PG8_BAR; PG8_MMA(1, 0, At, B0); PG8_MMA(1, 1, At, B1); PG8_BAR; PG8_SCHED;
;             PG8_LDB(B0, 1, 0); PG8_LDB(B1, 1, 1); PG8_SCHED; PG8_LDA(At, 1, 0); PG8_STAGE(PG8_SA(0, 1), a2 + hsA, voffA);
;             PG8_WAIT_V(8); PG8_WAIT_L(0); PG8_BAR; PG8_MMA(0, 0, At, B0); PG8_MMA(0, 1, At, B1); PG8_BAR; PG8_SCHED;
;             PG8_LDA(At, 1, 1); PG8_STAGE(PG8_SB(1, 0), b3, voffB); PG8_STAGE(PG8_SB(1, 1), b3 + hsB, voffB); PG8_STAGE(PG8_SA(1, 0), a3, voffA);
;             PG8_WAIT_V(8); PG8_WAIT_L(0); PG8_BAR; PG8_MMA(1, 0, At, B0); PG8_MMA(1, 1, At, B1); PG8_BAR; PG8_SCHED;
.LBB0_222:
	s_add_i32 s96, s9, 2
	s_add_u32 s20, s0, 0xfffc0080
	s_addc_u32 s21, s1, -1
	s_add_i32 s74, 0, 0x10000
	s_cmp_eq_u32 s82, s9
	s_cselect_b32 s85, s10, s21
	s_cselect_b32 s84, s43, s20
	s_cselect_b32 s39, s45, s8
	s_cselect_b32 s38, vcc_lo, vcc_hi
	s_add_i32 s9, 0, 0x14000
	v_add_u32_e32 v154, s74, v160
	v_add_u32_e32 v174, s9, v160
	ds_read_b128 v[142:145], v154
	ds_read_b128 v[146:149], v154 offset:1024
	ds_read_b128 v[150:153], v154 offset:2048
	ds_read_b128 v[154:157], v154 offset:3072
	ds_read_b128 v[162:165], v174
	ds_read_b128 v[166:169], v174 offset:1024
	ds_read_b128 v[170:173], v174 offset:2048
	ds_read_b128 v[174:177], v174 offset:3072
	v_lshl_add_u64 v[190:191], s[0:1], 0, v[138:139]
	s_add_i32 m0, s16, 0xc000
	ds_read_b128 v[178:181], v161
	ds_read_b128 v[182:185], v161 offset:1024
	ds_read_b128 v[186:189], v161 offset:2048
	ds_read_b128 v[208:211], v161 offset:3072
	ds_read_b128 v[212:215], v161 offset:4096
	ds_read_b128 v[216:219], v161 offset:5120
	ds_read_b128 v[220:223], v161 offset:6144
	ds_read_b128 v[224:227], v161 offset:7168
	global_load_lds_dwordx4 v[190:191], off
	v_lshl_add_u64 v[190:191], s[0:1], 0, v[140:141]
	s_add_i32 m0, s16, 0xe000
	s_nop 0
	global_load_lds_dwordx4 v[190:191], off
	s_waitcnt vmcnt(8)
	s_waitcnt lgkmcnt(0)
	s_barrier
	s_waitcnt lgkmcnt(0)
	v_mfma_f32_16x16x32_bf16 v[122:125], v[142:145], v[178:181], v[122:125]
	v_mfma_f32_16x16x32_bf16 v[114:117], v[150:153], v[178:181], v[114:117]
	v_mfma_f32_16x16x32_bf16 v[106:109], v[142:145], v[186:189], v[106:109]
	v_mfma_f32_16x16x32_bf16 v[98:101], v[150:153], v[186:189], v[98:101]
	v_mfma_f32_16x16x32_bf16 v[90:93], v[142:145], v[212:215], v[90:93]
	v_mfma_f32_16x16x32_bf16 v[82:85], v[150:153], v[212:215], v[82:85]
	v_mfma_f32_16x16x32_bf16 v[74:77], v[142:145], v[220:223], v[74:77]
	v_mfma_f32_16x16x32_bf16 v[66:69], v[150:153], v[220:223], v[66:69]
	v_mfma_f32_16x16x32_bf16 v[122:125], v[146:149], v[182:185], v[122:125]
	v_mfma_f32_16x16x32_bf16 v[114:117], v[154:157], v[182:185], v[114:117]
	v_mfma_f32_16x16x32_bf16 v[106:109], v[146:149], v[208:211], v[106:109]
	v_mfma_f32_16x16x32_bf16 v[98:101], v[154:157], v[208:211], v[98:101]
	v_mfma_f32_16x16x32_bf16 v[90:93], v[146:149], v[216:219], v[90:93]
	v_mfma_f32_16x16x32_bf16 v[82:85], v[154:157], v[216:219], v[82:85]
	v_mfma_f32_16x16x32_bf16 v[74:77], v[146:149], v[224:227], v[74:77]
	v_mfma_f32_16x16x32_bf16 v[66:69], v[154:157], v[224:227], v[66:69]
	v_mfma_f32_16x16x32_bf16 v[126:129], v[162:165], v[178:181], v[126:129]
	v_mfma_f32_16x16x32_bf16 v[118:121], v[170:173], v[178:181], v[118:121]
	v_mfma_f32_16x16x32_bf16 v[110:113], v[162:165], v[186:189], v[110:113]
	v_mfma_f32_16x16x32_bf16 v[102:105], v[170:173], v[186:189], v[102:105]
	v_mfma_f32_16x16x32_bf16 v[94:97], v[162:165], v[212:215], v[94:97]
	v_mfma_f32_16x16x32_bf16 v[86:89], v[170:173], v[212:215], v[86:89]
	v_mfma_f32_16x16x32_bf16 v[78:81], v[162:165], v[220:223], v[78:81]
	v_mfma_f32_16x16x32_bf16 v[70:73], v[170:173], v[220:223], v[70:73]
	v_mfma_f32_16x16x32_bf16 v[126:129], v[166:169], v[182:185], v[126:129]
	v_mfma_f32_16x16x32_bf16 v[118:121], v[174:177], v[182:185], v[118:121]
	v_mfma_f32_16x16x32_bf16 v[110:113], v[166:169], v[208:211], v[110:113]
	v_mfma_f32_16x16x32_bf16 v[102:105], v[174:177], v[208:211], v[102:105]
	v_mfma_f32_16x16x32_bf16 v[94:97], v[166:169], v[216:219], v[94:97]
	v_mfma_f32_16x16x32_bf16 v[86:89], v[174:177], v[216:219], v[86:89]
	v_mfma_f32_16x16x32_bf16 v[78:81], v[166:169], v[224:227], v[78:81]
	v_mfma_f32_16x16x32_bf16 v[70:73], v[174:177], v[224:227], v[70:73]
	s_barrier
	s_add_i32 s20, s74, s12
	v_lshl_add_u64 v[190:191], s[38:39], 0, v[0:1]
	s_mov_b32 m0, s20
	ds_read_b128 v[178:181], v161 offset:16384
	ds_read_b128 v[182:185], v161 offset:17408
	ds_read_b128 v[186:189], v161 offset:18432
	ds_read_b128 v[208:211], v161 offset:19456
	ds_read_b128 v[212:215], v161 offset:20480
	ds_read_b128 v[216:219], v161 offset:21504
	ds_read_b128 v[220:223], v161 offset:22528
	ds_read_b128 v[224:227], v161 offset:23552
	global_load_lds_dwordx4 v[190:191], off
	s_add_i32 m0, s20, 0x2000
	s_add_u32 s20, s38, 0x40000
	v_lshl_add_u64 v[228:229], s[38:39], 0, v[130:131]
	s_addc_u32 s21, s39, 0
	s_add_i32 s9, s9, s12
	global_load_lds_dwordx4 v[228:229], off
	v_lshl_add_u64 v[230:231], s[20:21], 0, v[0:1]
	s_mov_b32 m0, s9
	v_lshl_add_u64 v[232:233], s[84:85], 0, v[132:133]
	global_load_lds_dwordx4 v[230:231], off
	v_lshl_add_u64 v[230:231], s[20:21], 0, v[130:131]
	s_add_i32 m0, s9, 0x2000
	s_nop 0
	global_load_lds_dwordx4 v[230:231], off
	v_lshl_add_u64 v[230:231], s[84:85], 0, v[134:135]
	s_mov_b32 m0, s16
	s_nop 0
	global_load_lds_dwordx4 v[230:231], off
	s_mov_b32 m0, s30
	s_nop 0
	global_load_lds_dwordx4 v[232:233], off
	s_waitcnt vmcnt(8)
	s_waitcnt lgkmcnt(0)
	s_barrier
; #define PG8_STAGE(bufoff, gbase, voff) do { _Pragma("unroll") for (int _i = 0; _i < 2; ++_i) \
;         __builtin_amdgcn_global_load_lds((const unsigned*)((const char*)(gbase) + (voff)[_i]), (LAS unsigned*)(lds + (bufoff) + ldsw + _i * 8192), 16, 0, 0); } while (0)
; #define PG8_LDA(dst, b, h) do { _Pragma("unroll") for (int m = 0; m < 4; ++m) _Pragma("unroll") for (int k = 0; k < 2; ++k) dst[m][k] = *(const LAS bf16x8*)(lds + PG8_SA(b, h) + aoff + m * 2048 + k * 1024); } while (0)
; #define PG8_LDB(dst, b, h) do { _Pragma("unroll") for (int n = 0; n < 2; ++n) _Pragma("unroll") for (int k = 0; k < 2; ++k) dst[n][k] = *(const LAS bf16x8*)(lds + PG8_SB(b, h) + boff + n * 2048 + k * 1024); } while (0)
; #define PG8_MMA(ai, bj, At, Bt) do { __builtin_amdgcn_s_setprio(1); _Pragma("unroll") for (int m = 0; m < 4; ++m) _Pragma("unroll") for (int n = 0; n < 2; ++n) _Pragma("unroll") for (int k = 0; k < 2; ++k) \
;         acc[ai][bj][m][n] = __builtin_amdgcn_mfma_f32_16x16x32_bf16(Bt[n][k], At[m][k], acc[ai][bj][m][n], 0, 0, 0); __builtin_amdgcn_s_setprio(0); } while (0)
; #define PG8_WAIT_V(n) asm volatile("s_waitcnt vmcnt(" #n ")" ::: "memory")
; #define PG8_BAR __builtin_amdgcn_s_barrier()
; template <class Epi, class Sched>
; __device__ __forceinline__ void gemm_phase(LAS unsigned char* lds, const Gemm g, const Sched& S, const Epi& E) {
;     ...
;             PG8_LDB(B0, 0, 0); PG8_LDB(B1, 0, 1); PG8_SCHED; PG8_LDA(At, 0, 0); PG8_STAGE(PG8_SA(1, 1), a1 + hsA, voffA);
;             PG8_WAIT_V(8); PG8_WAIT_L(0); PG8_BAR; PG8_MMA(0, 0, At, B0); PG8_MMA(0, 1, At, B1); PG8_BAR; PG8_SCHED;
;             PG8_LDA(At, 0, 1); PG8_STAGE(PG8_SB(0, 0), b2, voffB); PG8_STAGE(PG8_SB(0, 1), b2 + hsB, voffB); PG8_STAGE(PG8_SA(0, 0), a2, voffA);
;             PG8_WAIT_V(8); PG8_WAIT_L(0); PG8_BAR; PG8_MMA(1, 0, At, B0); PG8_MMA(1, 1, At, B1); PG8_BAR; PG8_SCHED;
;             PG8_LDB(B0, 1, 0); PG8_LDB(B1, 1, 1); PG8_SCHED; PG8_LDA(At, 1, 0); PG8_STAGE(PG8_SA(0, 1), a2 + hsA, voffA);
;             PG8_WAIT_V(8); PG8_WAIT_L(0); PG8_BAR; PG8_MMA(0, 0, At, B0); PG8_MMA(0, 1, At, B1); PG8_BAR; PG8_SCHED;
;             PG8_LDA(At, 1, 1); PG8_STAGE(PG8_SB(1, 0), b3, voffB); PG8_STAGE(PG8_SB(1, 1), b3 + hsB, voffB); PG8_STAGE(PG8_SA(1, 0), a3, voffA);
;             PG8_WAIT_V(8); PG8_WAIT_L(0); PG8_BAR; PG8_MMA(1, 0, At, B0); PG8_MMA(1, 1, At, B1); PG8_BAR; PG8_SCHED;
	s_waitcnt lgkmcnt(0)
	v_mfma_f32_16x16x32_bf16 v[58:61], v[142:145], v[178:181], v[58:61]
	v_mfma_f32_16x16x32_bf16 v[50:53], v[150:153], v[178:181], v[50:53]
	v_mfma_f32_16x16x32_bf16 v[42:45], v[142:145], v[186:189], v[42:45]
	v_mfma_f32_16x16x32_bf16 v[34:37], v[150:153], v[186:189], v[34:37]
	v_mfma_f32_16x16x32_bf16 v[26:29], v[142:145], v[212:215], v[26:29]
	v_mfma_f32_16x16x32_bf16 v[18:21], v[150:153], v[212:215], v[18:21]
	v_mfma_f32_16x16x32_bf16 v[10:13], v[142:145], v[220:223], v[10:13]
	v_mfma_f32_16x16x32_bf16 v[2:5], v[150:153], v[220:223], v[2:5]
	v_mfma_f32_16x16x32_bf16 v[58:61], v[146:149], v[182:185], v[58:61]
	v_mfma_f32_16x16x32_bf16 v[50:53], v[154:157], v[182:185], v[50:53]
	v_mfma_f32_16x16x32_bf16 v[42:45], v[146:149], v[208:211], v[42:45]
	v_mfma_f32_16x16x32_bf16 v[34:37], v[154:157], v[208:211], v[34:37]
	v_mfma_f32_16x16x32_bf16 v[26:29], v[146:149], v[216:219], v[26:29]
	v_mfma_f32_16x16x32_bf16 v[18:21], v[154:157], v[216:219], v[18:21]
	v_mfma_f32_16x16x32_bf16 v[10:13], v[146:149], v[224:227], v[10:13]
	v_mfma_f32_16x16x32_bf16 v[2:5], v[154:157], v[224:227], v[2:5]
	v_mfma_f32_16x16x32_bf16 v[62:65], v[162:165], v[178:181], v[62:65]
	v_mfma_f32_16x16x32_bf16 v[54:57], v[170:173], v[178:181], v[54:57]
	v_mfma_f32_16x16x32_bf16 v[46:49], v[162:165], v[186:189], v[46:49]
	v_mfma_f32_16x16x32_bf16 v[38:41], v[170:173], v[186:189], v[38:41]
	v_mfma_f32_16x16x32_bf16 v[30:33], v[162:165], v[212:215], v[30:33]
	v_mfma_f32_16x16x32_bf16 v[22:25], v[170:173], v[212:215], v[22:25]
	v_mfma_f32_16x16x32_bf16 v[14:17], v[162:165], v[220:223], v[14:17]
	v_mfma_f32_16x16x32_bf16 v[6:9], v[170:173], v[220:223], v[6:9]
	v_mfma_f32_16x16x32_bf16 v[62:65], v[166:169], v[182:185], v[62:65]
	v_mfma_f32_16x16x32_bf16 v[54:57], v[174:177], v[182:185], v[54:57]
	v_mfma_f32_16x16x32_bf16 v[46:49], v[166:169], v[208:211], v[46:49]
	v_mfma_f32_16x16x32_bf16 v[38:41], v[174:177], v[208:211], v[38:41]
	v_mfma_f32_16x16x32_bf16 v[30:33], v[166:169], v[216:219], v[30:33]
	v_mfma_f32_16x16x32_bf16 v[22:25], v[174:177], v[216:219], v[22:25]
	v_mfma_f32_16x16x32_bf16 v[14:17], v[166:169], v[224:227], v[14:17]
	v_mfma_f32_16x16x32_bf16 v[6:9], v[174:177], v[224:227], v[6:9]
	s_barrier
	s_add_i32 s9, 0, 0x18000
	s_add_i32 s74, 0, 0x1c000
	v_add_u32_e32 v154, s9, v160
	v_add_u32_e32 v174, s74, v160
	ds_read_b128 v[142:145], v154
	ds_read_b128 v[146:149], v154 offset:1024
	ds_read_b128 v[150:153], v154 offset:2048
	ds_read_b128 v[154:157], v154 offset:3072
	ds_read_b128 v[162:165], v174
	ds_read_b128 v[166:169], v174 offset:1024
	ds_read_b128 v[170:173], v174 offset:2048
	ds_read_b128 v[174:177], v174 offset:3072
	s_add_u32 s20, s84, 0x40000
	s_addc_u32 s21, s85, 0
	s_mov_b32 m0, s52
	v_lshl_add_u64 v[238:239], s[20:21], 0, v[134:135]
	ds_read_b128 v[178:181], v161 offset:32768
	ds_read_b128 v[182:185], v161 offset:33792
	ds_read_b128 v[186:189], v161 offset:34816
	ds_read_b128 v[208:211], v161 offset:35840
	ds_read_b128 v[212:215], v161 offset:36864
	ds_read_b128 v[216:219], v161 offset:37888
	ds_read_b128 v[220:223], v161 offset:38912
	ds_read_b128 v[224:227], v161 offset:39936
	global_load_lds_dwordx4 v[238:239], off
	v_lshl_add_u64 v[238:239], s[20:21], 0, v[132:133]
	s_mov_b32 m0, s56
	s_nop 0
	global_load_lds_dwordx4 v[238:239], off
	s_waitcnt vmcnt(8)
	s_waitcnt lgkmcnt(0)
	s_barrier
	s_waitcnt lgkmcnt(0)
	v_mfma_f32_16x16x32_bf16 v[122:125], v[142:145], v[178:181], v[122:125]
	v_mfma_f32_16x16x32_bf16 v[114:117], v[150:153], v[178:181], v[114:117]
	v_mfma_f32_16x16x32_bf16 v[106:109], v[142:145], v[186:189], v[106:109]
	v_mfma_f32_16x16x32_bf16 v[98:101], v[150:153], v[186:189], v[98:101]
	v_mfma_f32_16x16x32_bf16 v[90:93], v[142:145], v[212:215], v[90:93]
	v_mfma_f32_16x16x32_bf16 v[82:85], v[150:153], v[212:215], v[82:85]
	v_mfma_f32_16x16x32_bf16 v[74:77], v[142:145], v[220:223], v[74:77]
	v_mfma_f32_16x16x32_bf16 v[66:69], v[150:153], v[220:223], v[66:69]
	v_mfma_f32_16x16x32_bf16 v[122:125], v[146:149], v[182:185], v[122:125]
	v_mfma_f32_16x16x32_bf16 v[114:117], v[154:157], v[182:185], v[114:117]
	v_mfma_f32_16x16x32_bf16 v[106:109], v[146:149], v[208:211], v[106:109]
	v_mfma_f32_16x16x32_bf16 v[98:101], v[154:157], v[208:211], v[98:101]
	v_mfma_f32_16x16x32_bf16 v[90:93], v[146:149], v[216:219], v[90:93]
	v_mfma_f32_16x16x32_bf16 v[82:85], v[154:157], v[216:219], v[82:85]
	v_mfma_f32_16x16x32_bf16 v[74:77], v[146:149], v[224:227], v[74:77]
	v_mfma_f32_16x16x32_bf16 v[66:69], v[154:157], v[224:227], v[66:69]
	v_mfma_f32_16x16x32_bf16 v[126:129], v[162:165], v[178:181], v[126:129]
	v_mfma_f32_16x16x32_bf16 v[118:121], v[170:173], v[178:181], v[118:121]
	v_mfma_f32_16x16x32_bf16 v[110:113], v[162:165], v[186:189], v[110:113]
	v_mfma_f32_16x16x32_bf16 v[102:105], v[170:173], v[186:189], v[102:105]
	v_mfma_f32_16x16x32_bf16 v[94:97], v[162:165], v[212:215], v[94:97]
	v_mfma_f32_16x16x32_bf16 v[86:89], v[170:173], v[212:215], v[86:89]
	v_mfma_f32_16x16x32_bf16 v[78:81], v[162:165], v[220:223], v[78:81]
	v_mfma_f32_16x16x32_bf16 v[70:73], v[170:173], v[220:223], v[70:73]
	v_mfma_f32_16x16x32_bf16 v[126:129], v[166:169], v[182:185], v[126:129]
	v_mfma_f32_16x16x32_bf16 v[118:121], v[174:177], v[182:185], v[118:121]
	v_mfma_f32_16x16x32_bf16 v[110:113], v[166:169], v[208:211], v[110:113]
	v_mfma_f32_16x16x32_bf16 v[102:105], v[174:177], v[208:211], v[102:105]
	v_mfma_f32_16x16x32_bf16 v[94:97], v[166:169], v[216:219], v[94:97]
	v_mfma_f32_16x16x32_bf16 v[86:89], v[174:177], v[216:219], v[86:89]
	v_mfma_f32_16x16x32_bf16 v[78:81], v[166:169], v[224:227], v[78:81]
	v_mfma_f32_16x16x32_bf16 v[70:73], v[174:177], v[224:227], v[70:73]
	s_barrier
; #define PG8_STAGE(bufoff, gbase, voff) do { _Pragma("unroll") for (int _i = 0; _i < 2; ++_i) \
;         __builtin_amdgcn_global_load_lds((const unsigned*)((const char*)(gbase) + (voff)[_i]), (LAS unsigned*)(lds + (bufoff) + ldsw + _i * 8192), 16, 0, 0); } while (0)
; #define PG8_LDA(dst, b, h) do { _Pragma("unroll") for (int m = 0; m < 4; ++m) _Pragma("unroll") for (int k = 0; k < 2; ++k) dst[m][k] = *(const LAS bf16x8*)(lds + PG8_SA(b, h) + aoff + m * 2048 + k * 1024); } while (0)
; #define PG8_WAIT_V(n) asm volatile("s_waitcnt vmcnt(" #n ")" ::: "memory")
; #define PG8_WAIT_L(n) asm volatile("s_waitcnt lgkmcnt(" #n ")" ::: "memory")
; #define PG8_BAR __builtin_amdgcn_s_barrier()
; template <class Epi, class Sched>
; __device__ __forceinline__ void gemm_phase(LAS unsigned char* lds, const Gemm g, const Sched& S, const Epi& E) {
;     ...
;         for (int t = 0; t < nt; t += 2) {
;             const bool last = (t == nt - 2);
;             const char* a1 = cA + (size_t)(t + 1) * kstep;
;             const char* a2 = last ? nA : cA + (size_t)(t + 2) * kstep; const char* b2 = last ? nB : cB + (size_t)(t + 2) * kstep;
;             const char* a3 = a2 + kstep; const char* b3 = b2 + kstep;
;             if constexpr (Epi::MIDK) { if (t == (nt >> 1)) { int fr_ = fr, fq_ = fq; asm volatile("" : "+v"(fr_), "+v"(fq_)); E.mid(acc, cur, wr, wc, fr_, fq_); } }
;             PG8_LDB(B0, 0, 0); PG8_LDB(B1, 0, 1); PG8_SCHED; PG8_LDA(At, 0, 0); PG8_STAGE(PG8_SA(1, 1), a1 + hsA, voffA);
;             PG8_WAIT_V(8); PG8_WAIT_L(0); PG8_BAR; PG8_MMA(0, 0, At, B0); PG8_MMA(0, 1, At, B1); PG8_BAR; PG8_SCHED;
;             PG8_LDA(At, 0, 1); PG8_STAGE(PG8_SB(0, 0), b2, voffB); PG8_STAGE(PG8_SB(0, 1), b2 + hsB, voffB); PG8_STAGE(PG8_SA(0, 0), a2, voffA);
;             PG8_WAIT_V(8); PG8_WAIT_L(0); PG8_BAR; PG8_MMA(1, 0, At, B0); PG8_MMA(1, 1, At, B1); PG8_BAR; PG8_SCHED;
;             PG8_LDB(B0, 1, 0); PG8_LDB(B1, 1, 1); PG8_SCHED; PG8_LDA(At, 1, 0); PG8_STAGE(PG8_SA(0, 1), a2 + hsA, voffA);
;             PG8_WAIT_V(8); PG8_WAIT_L(0); PG8_BAR; PG8_MMA(0, 0, At, B0); PG8_MMA(0, 1, At, B1); PG8_BAR; PG8_SCHED;
;             PG8_LDA(At, 1, 1); PG8_STAGE(PG8_SB(1, 0), b3, voffB); PG8_STAGE(PG8_SB(1, 1), b3 + hsB, voffB); PG8_STAGE(PG8_SA(1, 0), a3, voffA);
;             PG8_WAIT_V(8); PG8_WAIT_L(0); PG8_BAR; PG8_MMA(1, 0, At, B0); PG8_MMA(1, 1, At, B1); PG8_BAR; PG8_SCHED;
;         }
	s_add_i32 s9, s9, s12
	v_lshl_add_u64 v[190:191], v[190:191], 0, s[18:19]
	s_mov_b32 m0, s9
	ds_read_b128 v[178:181], v161 offset:49152
	ds_read_b128 v[182:185], v161 offset:50176
	ds_read_b128 v[186:189], v161 offset:51200
	ds_read_b128 v[208:211], v161 offset:52224
	ds_read_b128 v[212:215], v161 offset:53248
	ds_read_b128 v[216:219], v161 offset:54272
	ds_read_b128 v[220:223], v161 offset:55296
	ds_read_b128 v[224:227], v161 offset:56320
	global_load_lds_dwordx4 v[190:191], off
	s_add_i32 m0, s9, 0x2000
	s_add_u32 s20, s38, 0x40080
	v_lshl_add_u64 v[190:191], v[228:229], 0, s[18:19]
	s_addc_u32 s21, s39, 0
	s_add_i32 s9, s74, s12
	global_load_lds_dwordx4 v[190:191], off
	v_lshl_add_u64 v[190:191], s[20:21], 0, v[0:1]
	s_mov_b32 m0, s9
	s_nop 0
	global_load_lds_dwordx4 v[190:191], off
	v_lshl_add_u64 v[190:191], s[20:21], 0, v[130:131]
	s_add_i32 m0, s9, 0x2000
	s_nop 0
	global_load_lds_dwordx4 v[190:191], off
	v_lshl_add_u64 v[190:191], v[230:231], 0, s[18:19]
	s_mov_b32 m0, s78
	s_nop 0
	global_load_lds_dwordx4 v[190:191], off
	v_lshl_add_u64 v[190:191], v[232:233], 0, s[18:19]
	s_mov_b32 m0, s80
	s_nop 0
	global_load_lds_dwordx4 v[190:191], off
	s_waitcnt vmcnt(8)
	s_waitcnt lgkmcnt(0)
	s_barrier
	s_waitcnt lgkmcnt(0)
	v_mfma_f32_16x16x32_bf16 v[58:61], v[142:145], v[178:181], v[58:61]
	v_mfma_f32_16x16x32_bf16 v[50:53], v[150:153], v[178:181], v[50:53]
	v_mfma_f32_16x16x32_bf16 v[42:45], v[142:145], v[186:189], v[42:45]
	v_mfma_f32_16x16x32_bf16 v[34:37], v[150:153], v[186:189], v[34:37]
	v_mfma_f32_16x16x32_bf16 v[26:29], v[142:145], v[212:215], v[26:29]
	v_mfma_f32_16x16x32_bf16 v[18:21], v[150:153], v[212:215], v[18:21]
	v_mfma_f32_16x16x32_bf16 v[10:13], v[142:145], v[220:223], v[10:13]
	v_mfma_f32_16x16x32_bf16 v[2:5], v[150:153], v[220:223], v[2:5]
	v_mfma_f32_16x16x32_bf16 v[58:61], v[146:149], v[182:185], v[58:61]
	v_mfma_f32_16x16x32_bf16 v[50:53], v[154:157], v[182:185], v[50:53]
	v_mfma_f32_16x16x32_bf16 v[42:45], v[146:149], v[208:211], v[42:45]
	v_mfma_f32_16x16x32_bf16 v[34:37], v[154:157], v[208:211], v[34:37]
	v_mfma_f32_16x16x32_bf16 v[26:29], v[146:149], v[216:219], v[26:29]
	v_mfma_f32_16x16x32_bf16 v[18:21], v[154:157], v[216:219], v[18:21]
	v_mfma_f32_16x16x32_bf16 v[10:13], v[146:149], v[224:227], v[10:13]
	v_mfma_f32_16x16x32_bf16 v[2:5], v[154:157], v[224:227], v[2:5]
	v_mfma_f32_16x16x32_bf16 v[62:65], v[162:165], v[178:181], v[62:65]
	v_mfma_f32_16x16x32_bf16 v[54:57], v[170:173], v[178:181], v[54:57]
	v_mfma_f32_16x16x32_bf16 v[46:49], v[162:165], v[186:189], v[46:49]
	v_mfma_f32_16x16x32_bf16 v[38:41], v[170:173], v[186:189], v[38:41]
	v_mfma_f32_16x16x32_bf16 v[30:33], v[162:165], v[212:215], v[30:33]
	v_mfma_f32_16x16x32_bf16 v[22:25], v[170:173], v[212:215], v[22:25]
	v_mfma_f32_16x16x32_bf16 v[14:17], v[162:165], v[220:223], v[14:17]
	v_mfma_f32_16x16x32_bf16 v[6:9], v[170:173], v[220:223], v[6:9]
	v_mfma_f32_16x16x32_bf16 v[62:65], v[166:169], v[182:185], v[62:65]
	v_mfma_f32_16x16x32_bf16 v[54:57], v[174:177], v[182:185], v[54:57]
	v_mfma_f32_16x16x32_bf16 v[46:49], v[166:169], v[208:211], v[46:49]
	v_mfma_f32_16x16x32_bf16 v[38:41], v[174:177], v[208:211], v[38:41]
	v_mfma_f32_16x16x32_bf16 v[30:33], v[166:169], v[216:219], v[30:33]
	v_mfma_f32_16x16x32_bf16 v[22:25], v[174:177], v[216:219], v[22:25]
	v_mfma_f32_16x16x32_bf16 v[14:17], v[166:169], v[224:227], v[14:17]
	v_mfma_f32_16x16x32_bf16 v[6:9], v[174:177], v[224:227], v[6:9]
	s_barrier
	s_add_u32 s0, s0, 0x100
	s_addc_u32 s1, s1, 0
	s_add_u32 vcc_hi, vcc_hi, 0x100
	s_addc_u32 s8, s8, 0
	s_cmp_ge_i32 s96, s57
	s_mov_b32 s9, s96
	s_cbranch_scc0 .LBB0_222
	v_readlane_b32 s96, v250, 43
	s_mov_b64 s[74:75], s[22:23]

; #define PG8_STAGE(bufoff, gbase, voff) do { _Pragma("unroll") for (int _i = 0; _i < 2; ++_i) \
;         __builtin_amdgcn_global_load_lds((const unsigned*)((const char*)(gbase) + (voff)[_i]), (LAS unsigned*)(lds + (bufoff) + ldsw + _i * 8192), 16, 0, 0); } while (0)
; #define PG8_LDA(dst, b, h) do { _Pragma("unroll") for (int m = 0; m < 4; ++m) _Pragma("unroll") for (int k = 0; k < 2; ++k) dst[m][k] = *(const LAS bf16x8*)(lds + PG8_SA(b, h) + aoff + m * 2048 + k * 1024); } while (0)
; #define PG8_LDB(dst, b, h) do { _Pragma("unroll") for (int n = 0; n < 2; ++n) _Pragma("unroll") for (int k = 0; k < 2; ++k) dst[n][k] = *(const LAS bf16x8*)(lds + PG8_SB(b, h) + boff + n * 2048 + k * 1024); } while (0)
; #define PG8_MMA(ai, bj, At, Bt) do { __builtin_amdgcn_s_setprio(1); _Pragma("unroll") for (int m = 0; m < 4; ++m) _Pragma("unroll") for (int n = 0; n < 2; ++n) _Pragma("unroll") for (int k = 0; k < 2; ++k) \
;         acc[ai][bj][m][n] = __builtin_amdgcn_mfma_f32_16x16x32_bf16(Bt[n][k], At[m][k], acc[ai][bj][m][n], 0, 0, 0); __builtin_amdgcn_s_setprio(0); } while (0)
; #define PG8_WAIT_V(n) asm volatile("s_waitcnt vmcnt(" #n ")" ::: "memory")
; #define PG8_BAR __builtin_amdgcn_s_barrier()
; template <class Epi, class Sched>
; __device__ __forceinline__ void gemm_phase(LAS unsigned char* lds, const Gemm g, const Sched& S, const Epi& E) {
;     ...
;             PG8_LDB(B0, 0, 0); PG8_LDB(B1, 0, 1); PG8_SCHED; PG8_LDA(At, 0, 0); PG8_STAGE(PG8_SA(1, 1), a1 + hsA, voffA);
;             PG8_WAIT_V(8); PG8_WAIT_L(0); PG8_BAR; PG8_MMA(0, 0, At, B0); PG8_MMA(0, 1, At, B1); PG8_BAR; PG8_SCHED;
;             PG8_LDA(At, 0, 1); PG8_STAGE(PG8_SB(0, 0), b2, voffB); PG8_STAGE(PG8_SB(0, 1), b2 + hsB, voffB); PG8_STAGE(PG8_SA(0, 0), a2, voffA);
;             PG8_WAIT_V(8); PG8_WAIT_L(0); PG8_BAR; PG8_MMA(1, 0, At, B0); PG8_MMA(1, 1, At, B1); PG8_BAR; PG8_SCHED;
;             PG8_LDB(B0, 1, 0); PG8_LDB(B1, 1, 1); PG8_SCHED; PG8_LDA(At, 1, 0); PG8_STAGE(PG8_SA(0, 1), a2 + hsA, voffA);
;             PG8_WAIT_V(8); PG8_WAIT_L(0); PG8_BAR; PG8_MMA(0, 0, At, B0); PG8_MMA(0, 1, At, B1); PG8_BAR; PG8_SCHED;
;             PG8_LDA(At, 1, 1); PG8_STAGE(PG8_SB(1, 0), b3, voffB); PG8_STAGE(PG8_SB(1, 1), b3 + hsB, voffB); PG8_STAGE(PG8_SA(1, 0), a3, voffA);
;             PG8_WAIT_V(8); PG8_WAIT_L(0); PG8_BAR; PG8_MMA(1, 0, At, B0); PG8_MMA(1, 1, At, B1); PG8_BAR; PG8_SCHED;
.LBB0_298:
	s_add_i32 s96, s38, 2
	s_add_u32 s20, s8, 0x100
	s_addc_u32 s21, s9, 0
	s_add_i32 s74, 0, 0x10000
	s_cmp_eq_u32 s26, s38
	s_cselect_b32 s41, s43, s21
	s_cselect_b32 s40, s73, s20
	s_cselect_b32 s39, s82, s85
	s_cselect_b32 s38, s83, s84
	s_add_i32 s75, 0, 0x14000
	v_add_u32_e32 v152, s74, v206
	v_add_u32_e32 v168, s75, v206
	ds_read_b128 v[140:143], v152
	ds_read_b128 v[144:147], v152 offset:1024
	ds_read_b128 v[148:151], v152 offset:2048
	ds_read_b128 v[152:155], v152 offset:3072
	ds_read_b128 v[156:159], v168
	ds_read_b128 v[160:163], v168 offset:1024
	ds_read_b128 v[164:167], v168 offset:2048
	ds_read_b128 v[168:171], v168 offset:3072
	v_lshl_add_u64 v[208:209], s[8:9], 0, v[136:137]
	s_add_i32 m0, s30, 0xc000
	ds_read_b128 v[172:175], v210
	ds_read_b128 v[176:179], v210 offset:1024
	ds_read_b128 v[180:183], v210 offset:2048
	ds_read_b128 v[184:187], v210 offset:3072
	ds_read_b128 v[188:191], v210 offset:4096
	ds_read_b128 v[212:215], v210 offset:5120
	ds_read_b128 v[216:219], v210 offset:6144
	ds_read_b128 v[220:223], v210 offset:7168
	global_load_lds_dwordx4 v[208:209], off
	v_lshl_add_u64 v[208:209], s[8:9], 0, v[138:139]
	s_add_i32 m0, s30, 0xe000
	s_nop 0
	global_load_lds_dwordx4 v[208:209], off
	s_waitcnt vmcnt(8)
	s_waitcnt lgkmcnt(0)
	s_barrier
	s_waitcnt lgkmcnt(0)
	v_mfma_f32_16x16x32_bf16 v[126:129], v[140:143], v[172:175], v[126:129]
	v_mfma_f32_16x16x32_bf16 v[122:125], v[148:151], v[172:175], v[122:125]
	v_mfma_f32_16x16x32_bf16 v[118:121], v[140:143], v[180:183], v[118:121]
	v_mfma_f32_16x16x32_bf16 v[114:117], v[148:151], v[180:183], v[114:117]
	v_mfma_f32_16x16x32_bf16 v[106:109], v[140:143], v[188:191], v[106:109]
	v_mfma_f32_16x16x32_bf16 v[98:101], v[148:151], v[188:191], v[98:101]
	v_mfma_f32_16x16x32_bf16 v[90:93], v[140:143], v[216:219], v[90:93]
	v_mfma_f32_16x16x32_bf16 v[82:85], v[148:151], v[216:219], v[82:85]
	v_mfma_f32_16x16x32_bf16 v[126:129], v[144:147], v[176:179], v[126:129]
	v_mfma_f32_16x16x32_bf16 v[122:125], v[152:155], v[176:179], v[122:125]
	v_mfma_f32_16x16x32_bf16 v[118:121], v[144:147], v[184:187], v[118:121]
	v_mfma_f32_16x16x32_bf16 v[114:117], v[152:155], v[184:187], v[114:117]
	v_mfma_f32_16x16x32_bf16 v[106:109], v[144:147], v[212:215], v[106:109]
	v_mfma_f32_16x16x32_bf16 v[98:101], v[152:155], v[212:215], v[98:101]
	v_mfma_f32_16x16x32_bf16 v[90:93], v[144:147], v[220:223], v[90:93]
	v_mfma_f32_16x16x32_bf16 v[82:85], v[152:155], v[220:223], v[82:85]
	v_mfma_f32_16x16x32_bf16 v[110:113], v[156:159], v[172:175], v[110:113]
	v_mfma_f32_16x16x32_bf16 v[102:105], v[164:167], v[172:175], v[102:105]
	v_mfma_f32_16x16x32_bf16 v[94:97], v[156:159], v[180:183], v[94:97]
	v_mfma_f32_16x16x32_bf16 v[86:89], v[164:167], v[180:183], v[86:89]
	v_mfma_f32_16x16x32_bf16 v[78:81], v[156:159], v[188:191], v[78:81]
	v_mfma_f32_16x16x32_bf16 v[74:77], v[164:167], v[188:191], v[74:77]
	v_mfma_f32_16x16x32_bf16 v[70:73], v[156:159], v[216:219], v[70:73]
	v_mfma_f32_16x16x32_bf16 v[66:69], v[164:167], v[216:219], v[66:69]
	v_mfma_f32_16x16x32_bf16 v[110:113], v[160:163], v[176:179], v[110:113]
	v_mfma_f32_16x16x32_bf16 v[102:105], v[168:171], v[176:179], v[102:105]
	v_mfma_f32_16x16x32_bf16 v[94:97], v[160:163], v[184:187], v[94:97]
	v_mfma_f32_16x16x32_bf16 v[86:89], v[168:171], v[184:187], v[86:89]
	v_mfma_f32_16x16x32_bf16 v[78:81], v[160:163], v[212:215], v[78:81]
	v_mfma_f32_16x16x32_bf16 v[74:77], v[168:171], v[212:215], v[74:77]
	v_mfma_f32_16x16x32_bf16 v[70:73], v[160:163], v[220:223], v[70:73]
	v_mfma_f32_16x16x32_bf16 v[66:69], v[168:171], v[220:223], v[66:69]
	s_barrier
	s_add_i32 s8, s74, s24
	v_lshl_add_u64 v[208:209], s[38:39], 0, v[0:1]
	s_mov_b32 m0, s8
	ds_read_b128 v[172:175], v210 offset:16384
	ds_read_b128 v[176:179], v210 offset:17408
	ds_read_b128 v[180:183], v210 offset:18432
	ds_read_b128 v[184:187], v210 offset:19456
	ds_read_b128 v[188:191], v210 offset:20480
	ds_read_b128 v[212:215], v210 offset:21504
	ds_read_b128 v[216:219], v210 offset:22528
	ds_read_b128 v[220:223], v210 offset:23552
	global_load_lds_dwordx4 v[208:209], off
	s_add_i32 m0, s8, 0x2000
	s_add_u32 s8, s38, 0xb0000
	v_lshl_add_u64 v[224:225], s[38:39], 0, v[130:131]
	s_addc_u32 s9, s39, 0
	s_add_i32 s74, s75, s24
	global_load_lds_dwordx4 v[224:225], off
	v_lshl_add_u64 v[226:227], s[8:9], 0, v[0:1]
	s_mov_b32 m0, s74
	v_lshl_add_u64 v[228:229], s[40:41], 0, v[132:133]
	global_load_lds_dwordx4 v[226:227], off
	v_lshl_add_u64 v[226:227], s[8:9], 0, v[130:131]
	s_add_i32 m0, s74, 0x2000
	s_nop 0
	global_load_lds_dwordx4 v[226:227], off
	v_lshl_add_u64 v[226:227], s[40:41], 0, v[134:135]
	s_mov_b32 m0, s30
	s_nop 0
	global_load_lds_dwordx4 v[226:227], off
	s_mov_b32 m0, s52
	s_nop 0
	global_load_lds_dwordx4 v[228:229], off
	s_waitcnt vmcnt(8)
	s_waitcnt lgkmcnt(0)
	s_barrier
; #define PG8_STAGE(bufoff, gbase, voff) do { _Pragma("unroll") for (int _i = 0; _i < 2; ++_i) \
;         __builtin_amdgcn_global_load_lds((const unsigned*)((const char*)(gbase) + (voff)[_i]), (LAS unsigned*)(lds + (bufoff) + ldsw + _i * 8192), 16, 0, 0); } while (0)
; #define PG8_LDA(dst, b, h) do { _Pragma("unroll") for (int m = 0; m < 4; ++m) _Pragma("unroll") for (int k = 0; k < 2; ++k) dst[m][k] = *(const LAS bf16x8*)(lds + PG8_SA(b, h) + aoff + m * 2048 + k * 1024); } while (0)
; #define PG8_LDB(dst, b, h) do { _Pragma("unroll") for (int n = 0; n < 2; ++n) _Pragma("unroll") for (int k = 0; k < 2; ++k) dst[n][k] = *(const LAS bf16x8*)(lds + PG8_SB(b, h) + boff + n * 2048 + k * 1024); } while (0)
; #define PG8_MMA(ai, bj, At, Bt) do { __builtin_amdgcn_s_setprio(1); _Pragma("unroll") for (int m = 0; m < 4; ++m) _Pragma("unroll") for (int n = 0; n < 2; ++n) _Pragma("unroll") for (int k = 0; k < 2; ++k) \
;         acc[ai][bj][m][n] = __builtin_amdgcn_mfma_f32_16x16x32_bf16(Bt[n][k], At[m][k], acc[ai][bj][m][n], 0, 0, 0); __builtin_amdgcn_s_setprio(0); } while (0)
; #define PG8_WAIT_V(n) asm volatile("s_waitcnt vmcnt(" #n ")" ::: "memory")
; #define PG8_BAR __builtin_amdgcn_s_barrier()
; template <class Epi, class Sched>
; __device__ __forceinline__ void gemm_phase(LAS unsigned char* lds, const Gemm g, const Sched& S, const Epi& E) {
;     ...
;             PG8_LDB(B0, 0, 0); PG8_LDB(B1, 0, 1); PG8_SCHED; PG8_LDA(At, 0, 0); PG8_STAGE(PG8_SA(1, 1), a1 + hsA, voffA);
;             PG8_WAIT_V(8); PG8_WAIT_L(0); PG8_BAR; PG8_MMA(0, 0, At, B0); PG8_MMA(0, 1, At, B1); PG8_BAR; PG8_SCHED;
;             PG8_LDA(At, 0, 1); PG8_STAGE(PG8_SB(0, 0), b2, voffB); PG8_STAGE(PG8_SB(0, 1), b2 + hsB, voffB); PG8_STAGE(PG8_SA(0, 0), a2, voffA);
;             PG8_WAIT_V(8); PG8_WAIT_L(0); PG8_BAR; PG8_MMA(1, 0, At, B0); PG8_MMA(1, 1, At, B1); PG8_BAR; PG8_SCHED;
;             PG8_LDB(B0, 1, 0); PG8_LDB(B1, 1, 1); PG8_SCHED; PG8_LDA(At, 1, 0); PG8_STAGE(PG8_SA(0, 1), a2 + hsA, voffA);
;             PG8_WAIT_V(8); PG8_WAIT_L(0); PG8_BAR; PG8_MMA(0, 0, At, B0); PG8_MMA(0, 1, At, B1); PG8_BAR; PG8_SCHED;
;             PG8_LDA(At, 1, 1); PG8_STAGE(PG8_SB(1, 0), b3, voffB); PG8_STAGE(PG8_SB(1, 1), b3 + hsB, voffB); PG8_STAGE(PG8_SA(1, 0), a3, voffA);
;             PG8_WAIT_V(8); PG8_WAIT_L(0); PG8_BAR; PG8_MMA(1, 0, At, B0); PG8_MMA(1, 1, At, B1); PG8_BAR; PG8_SCHED;
	s_waitcnt lgkmcnt(0)
	v_mfma_f32_16x16x32_bf16 v[62:65], v[140:143], v[172:175], v[62:65]
	v_mfma_f32_16x16x32_bf16 v[58:61], v[148:151], v[172:175], v[58:61]
	v_mfma_f32_16x16x32_bf16 v[54:57], v[140:143], v[180:183], v[54:57]
	v_mfma_f32_16x16x32_bf16 v[50:53], v[148:151], v[180:183], v[50:53]
	v_mfma_f32_16x16x32_bf16 v[42:45], v[140:143], v[188:191], v[42:45]
	v_mfma_f32_16x16x32_bf16 v[34:37], v[148:151], v[188:191], v[34:37]
	v_mfma_f32_16x16x32_bf16 v[26:29], v[140:143], v[216:219], v[26:29]
	v_mfma_f32_16x16x32_bf16 v[18:21], v[148:151], v[216:219], v[18:21]
	v_mfma_f32_16x16x32_bf16 v[62:65], v[144:147], v[176:179], v[62:65]
	v_mfma_f32_16x16x32_bf16 v[58:61], v[152:155], v[176:179], v[58:61]
	v_mfma_f32_16x16x32_bf16 v[54:57], v[144:147], v[184:187], v[54:57]
	v_mfma_f32_16x16x32_bf16 v[50:53], v[152:155], v[184:187], v[50:53]
	v_mfma_f32_16x16x32_bf16 v[42:45], v[144:147], v[212:215], v[42:45]
	v_mfma_f32_16x16x32_bf16 v[34:37], v[152:155], v[212:215], v[34:37]
	v_mfma_f32_16x16x32_bf16 v[26:29], v[144:147], v[220:223], v[26:29]
	v_mfma_f32_16x16x32_bf16 v[18:21], v[152:155], v[220:223], v[18:21]
	v_mfma_f32_16x16x32_bf16 v[46:49], v[156:159], v[172:175], v[46:49]
	v_mfma_f32_16x16x32_bf16 v[38:41], v[164:167], v[172:175], v[38:41]
	v_mfma_f32_16x16x32_bf16 v[30:33], v[156:159], v[180:183], v[30:33]
	v_mfma_f32_16x16x32_bf16 v[22:25], v[164:167], v[180:183], v[22:25]
	v_mfma_f32_16x16x32_bf16 v[14:17], v[156:159], v[188:191], v[14:17]
	v_mfma_f32_16x16x32_bf16 v[10:13], v[164:167], v[188:191], v[10:13]
	v_mfma_f32_16x16x32_bf16 v[6:9], v[156:159], v[216:219], v[6:9]
	v_mfma_f32_16x16x32_bf16 v[2:5], v[164:167], v[216:219], v[2:5]
	v_mfma_f32_16x16x32_bf16 v[46:49], v[160:163], v[176:179], v[46:49]
	v_mfma_f32_16x16x32_bf16 v[38:41], v[168:171], v[176:179], v[38:41]
	v_mfma_f32_16x16x32_bf16 v[30:33], v[160:163], v[184:187], v[30:33]
	v_mfma_f32_16x16x32_bf16 v[22:25], v[168:171], v[184:187], v[22:25]
	v_mfma_f32_16x16x32_bf16 v[14:17], v[160:163], v[212:215], v[14:17]
	v_mfma_f32_16x16x32_bf16 v[10:13], v[168:171], v[212:215], v[10:13]
	v_mfma_f32_16x16x32_bf16 v[6:9], v[160:163], v[220:223], v[6:9]
	v_mfma_f32_16x16x32_bf16 v[2:5], v[168:171], v[220:223], v[2:5]
	s_barrier
	s_add_i32 s74, 0, 0x18000
	s_add_i32 s75, 0, 0x1c000
	v_add_u32_e32 v152, s74, v206
	v_add_u32_e32 v168, s75, v206
	ds_read_b128 v[140:143], v152
	ds_read_b128 v[144:147], v152 offset:1024
	ds_read_b128 v[148:151], v152 offset:2048
	ds_read_b128 v[152:155], v152 offset:3072
	ds_read_b128 v[156:159], v168
	ds_read_b128 v[160:163], v168 offset:1024
	ds_read_b128 v[164:167], v168 offset:2048
	ds_read_b128 v[168:171], v168 offset:3072
	s_add_u32 s8, s40, 0xb0000
	s_addc_u32 s9, s41, 0
	s_mov_b32 m0, s64
	v_lshl_add_u64 v[230:231], s[8:9], 0, v[134:135]
	ds_read_b128 v[172:175], v210 offset:32768
	ds_read_b128 v[176:179], v210 offset:33792
	ds_read_b128 v[180:183], v210 offset:34816
	ds_read_b128 v[184:187], v210 offset:35840
	ds_read_b128 v[188:191], v210 offset:36864
	ds_read_b128 v[212:215], v210 offset:37888
	ds_read_b128 v[216:219], v210 offset:38912
	ds_read_b128 v[220:223], v210 offset:39936
	global_load_lds_dwordx4 v[230:231], off
	v_lshl_add_u64 v[230:231], s[8:9], 0, v[132:133]
	s_mov_b32 m0, s78
	s_nop 0
	global_load_lds_dwordx4 v[230:231], off
	s_waitcnt vmcnt(8)
	s_waitcnt lgkmcnt(0)
	s_barrier
	s_waitcnt lgkmcnt(0)
	v_mfma_f32_16x16x32_bf16 v[126:129], v[140:143], v[172:175], v[126:129]
	v_mfma_f32_16x16x32_bf16 v[122:125], v[148:151], v[172:175], v[122:125]
	v_mfma_f32_16x16x32_bf16 v[118:121], v[140:143], v[180:183], v[118:121]
	v_mfma_f32_16x16x32_bf16 v[114:117], v[148:151], v[180:183], v[114:117]
	v_mfma_f32_16x16x32_bf16 v[106:109], v[140:143], v[188:191], v[106:109]
	v_mfma_f32_16x16x32_bf16 v[98:101], v[148:151], v[188:191], v[98:101]
	v_mfma_f32_16x16x32_bf16 v[90:93], v[140:143], v[216:219], v[90:93]
	v_mfma_f32_16x16x32_bf16 v[82:85], v[148:151], v[216:219], v[82:85]
	v_mfma_f32_16x16x32_bf16 v[126:129], v[144:147], v[176:179], v[126:129]
	v_mfma_f32_16x16x32_bf16 v[122:125], v[152:155], v[176:179], v[122:125]
	v_mfma_f32_16x16x32_bf16 v[118:121], v[144:147], v[184:187], v[118:121]
	v_mfma_f32_16x16x32_bf16 v[114:117], v[152:155], v[184:187], v[114:117]
	v_mfma_f32_16x16x32_bf16 v[106:109], v[144:147], v[212:215], v[106:109]
	v_mfma_f32_16x16x32_bf16 v[98:101], v[152:155], v[212:215], v[98:101]
	v_mfma_f32_16x16x32_bf16 v[90:93], v[144:147], v[220:223], v[90:93]
	v_mfma_f32_16x16x32_bf16 v[82:85], v[152:155], v[220:223], v[82:85]
	v_mfma_f32_16x16x32_bf16 v[110:113], v[156:159], v[172:175], v[110:113]
	v_mfma_f32_16x16x32_bf16 v[102:105], v[164:167], v[172:175], v[102:105]
	v_mfma_f32_16x16x32_bf16 v[94:97], v[156:159], v[180:183], v[94:97]
	v_mfma_f32_16x16x32_bf16 v[86:89], v[164:167], v[180:183], v[86:89]
	v_mfma_f32_16x16x32_bf16 v[78:81], v[156:159], v[188:191], v[78:81]
	v_mfma_f32_16x16x32_bf16 v[74:77], v[164:167], v[188:191], v[74:77]
	v_mfma_f32_16x16x32_bf16 v[70:73], v[156:159], v[216:219], v[70:73]
	v_mfma_f32_16x16x32_bf16 v[66:69], v[164:167], v[216:219], v[66:69]
	v_mfma_f32_16x16x32_bf16 v[110:113], v[160:163], v[176:179], v[110:113]
	v_mfma_f32_16x16x32_bf16 v[102:105], v[168:171], v[176:179], v[102:105]
	v_mfma_f32_16x16x32_bf16 v[94:97], v[160:163], v[184:187], v[94:97]
	v_mfma_f32_16x16x32_bf16 v[86:89], v[168:171], v[184:187], v[86:89]
	v_mfma_f32_16x16x32_bf16 v[78:81], v[160:163], v[212:215], v[78:81]
	v_mfma_f32_16x16x32_bf16 v[74:77], v[168:171], v[212:215], v[74:77]
	v_mfma_f32_16x16x32_bf16 v[70:73], v[160:163], v[220:223], v[70:73]
	v_mfma_f32_16x16x32_bf16 v[66:69], v[168:171], v[220:223], v[66:69]
	s_barrier
; #define PG8_STAGE(bufoff, gbase, voff) do { _Pragma("unroll") for (int _i = 0; _i < 2; ++_i) \
;         __builtin_amdgcn_global_load_lds((const unsigned*)((const char*)(gbase) + (voff)[_i]), (LAS unsigned*)(lds + (bufoff) + ldsw + _i * 8192), 16, 0, 0); } while (0)
; #define PG8_LDA(dst, b, h) do { _Pragma("unroll") for (int m = 0; m < 4; ++m) _Pragma("unroll") for (int k = 0; k < 2; ++k) dst[m][k] = *(const LAS bf16x8*)(lds + PG8_SA(b, h) + aoff + m * 2048 + k * 1024); } while (0)
; #define PG8_WAIT_V(n) asm volatile("s_waitcnt vmcnt(" #n ")" ::: "memory")
; #define PG8_WAIT_L(n) asm volatile("s_waitcnt lgkmcnt(" #n ")" ::: "memory")
; #define PG8_BAR __builtin_amdgcn_s_barrier()
; template <class Epi, class Sched>
; __device__ __forceinline__ void gemm_phase(LAS unsigned char* lds, const Gemm g, const Sched& S, const Epi& E) {
;     ...
;         for (int t = 0; t < nt; t += 2) {
;             const bool last = (t == nt - 2);
;             const char* a1 = cA + (size_t)(t + 1) * kstep;
;             const char* a2 = last ? nA : cA + (size_t)(t + 2) * kstep; const char* b2 = last ? nB : cB + (size_t)(t + 2) * kstep;
;             const char* a3 = a2 + kstep; const char* b3 = b2 + kstep;
;             if constexpr (Epi::MIDK) { if (t == (nt >> 1)) { int fr_ = fr, fq_ = fq; asm volatile("" : "+v"(fr_), "+v"(fq_)); E.mid(acc, cur, wr, wc, fr_, fq_); } }
;             PG8_LDB(B0, 0, 0); PG8_LDB(B1, 0, 1); PG8_SCHED; PG8_LDA(At, 0, 0); PG8_STAGE(PG8_SA(1, 1), a1 + hsA, voffA);
;             PG8_WAIT_V(8); PG8_WAIT_L(0); PG8_BAR; PG8_MMA(0, 0, At, B0); PG8_MMA(0, 1, At, B1); PG8_BAR; PG8_SCHED;
;             PG8_LDA(At, 0, 1); PG8_STAGE(PG8_SB(0, 0), b2, voffB); PG8_STAGE(PG8_SB(0, 1), b2 + hsB, voffB); PG8_STAGE(PG8_SA(0, 0), a2, voffA);
;             PG8_WAIT_V(8); PG8_WAIT_L(0); PG8_BAR; PG8_MMA(1, 0, At, B0); PG8_MMA(1, 1, At, B1); PG8_BAR; PG8_SCHED;
;             PG8_LDB(B0, 1, 0); PG8_LDB(B1, 1, 1); PG8_SCHED; PG8_LDA(At, 1, 0); PG8_STAGE(PG8_SA(0, 1), a2 + hsA, voffA);
;             PG8_WAIT_V(8); PG8_WAIT_L(0); PG8_BAR; PG8_MMA(0, 0, At, B0); PG8_MMA(0, 1, At, B1); PG8_BAR; PG8_SCHED;
;             PG8_LDA(At, 1, 1); PG8_STAGE(PG8_SB(1, 0), b3, voffB); PG8_STAGE(PG8_SB(1, 1), b3 + hsB, voffB); PG8_STAGE(PG8_SA(1, 0), a3, voffA);
;             PG8_WAIT_V(8); PG8_WAIT_L(0); PG8_BAR; PG8_MMA(1, 0, At, B0); PG8_MMA(1, 1, At, B1); PG8_BAR; PG8_SCHED;
;         }
	s_add_i32 s8, s74, s24
	v_lshl_add_u64 v[208:209], v[208:209], 0, s[18:19]
	s_mov_b32 m0, s8
	ds_read_b128 v[172:175], v210 offset:49152
	ds_read_b128 v[176:179], v210 offset:50176
	ds_read_b128 v[180:183], v210 offset:51200
	ds_read_b128 v[184:187], v210 offset:52224
	ds_read_b128 v[188:191], v210 offset:53248
	ds_read_b128 v[212:215], v210 offset:54272
	ds_read_b128 v[216:219], v210 offset:55296
	ds_read_b128 v[220:223], v210 offset:56320
	global_load_lds_dwordx4 v[208:209], off
	s_add_i32 m0, s8, 0x2000
	s_add_u32 s8, s38, 0xb0080
	v_lshl_add_u64 v[208:209], v[224:225], 0, s[18:19]
	s_addc_u32 s9, s39, 0
	s_add_i32 s38, s75, s24
	global_load_lds_dwordx4 v[208:209], off
	v_lshl_add_u64 v[208:209], s[8:9], 0, v[0:1]
	s_mov_b32 m0, s38
	s_nop 0
	global_load_lds_dwordx4 v[208:209], off
	v_lshl_add_u64 v[208:209], s[8:9], 0, v[130:131]
	s_add_i32 m0, s38, 0x2000
	s_nop 0
	global_load_lds_dwordx4 v[208:209], off
	v_lshl_add_u64 v[208:209], v[226:227], 0, s[18:19]
	s_mov_b32 m0, s16
	s_nop 0
	global_load_lds_dwordx4 v[208:209], off
	v_lshl_add_u64 v[208:209], v[228:229], 0, s[18:19]
	s_mov_b32 m0, s7
	s_nop 0
	global_load_lds_dwordx4 v[208:209], off
	s_waitcnt vmcnt(8)
	s_waitcnt lgkmcnt(0)
	s_barrier
	s_waitcnt lgkmcnt(0)
	v_mfma_f32_16x16x32_bf16 v[62:65], v[140:143], v[172:175], v[62:65]
	v_mfma_f32_16x16x32_bf16 v[58:61], v[148:151], v[172:175], v[58:61]
	v_mfma_f32_16x16x32_bf16 v[54:57], v[140:143], v[180:183], v[54:57]
	v_mfma_f32_16x16x32_bf16 v[50:53], v[148:151], v[180:183], v[50:53]
	v_mfma_f32_16x16x32_bf16 v[42:45], v[140:143], v[188:191], v[42:45]
	v_mfma_f32_16x16x32_bf16 v[34:37], v[148:151], v[188:191], v[34:37]
	v_mfma_f32_16x16x32_bf16 v[26:29], v[140:143], v[216:219], v[26:29]
	v_mfma_f32_16x16x32_bf16 v[18:21], v[148:151], v[216:219], v[18:21]
	v_mfma_f32_16x16x32_bf16 v[62:65], v[144:147], v[176:179], v[62:65]
	v_mfma_f32_16x16x32_bf16 v[58:61], v[152:155], v[176:179], v[58:61]
	v_mfma_f32_16x16x32_bf16 v[54:57], v[144:147], v[184:187], v[54:57]
	v_mfma_f32_16x16x32_bf16 v[50:53], v[152:155], v[184:187], v[50:53]
	v_mfma_f32_16x16x32_bf16 v[42:45], v[144:147], v[212:215], v[42:45]
	v_mfma_f32_16x16x32_bf16 v[34:37], v[152:155], v[212:215], v[34:37]
	v_mfma_f32_16x16x32_bf16 v[26:29], v[144:147], v[220:223], v[26:29]
	v_mfma_f32_16x16x32_bf16 v[18:21], v[152:155], v[220:223], v[18:21]
	v_mfma_f32_16x16x32_bf16 v[46:49], v[156:159], v[172:175], v[46:49]
	v_mfma_f32_16x16x32_bf16 v[38:41], v[164:167], v[172:175], v[38:41]
	v_mfma_f32_16x16x32_bf16 v[30:33], v[156:159], v[180:183], v[30:33]
	v_mfma_f32_16x16x32_bf16 v[22:25], v[164:167], v[180:183], v[22:25]
	v_mfma_f32_16x16x32_bf16 v[14:17], v[156:159], v[188:191], v[14:17]
	v_mfma_f32_16x16x32_bf16 v[10:13], v[164:167], v[188:191], v[10:13]
	v_mfma_f32_16x16x32_bf16 v[6:9], v[156:159], v[216:219], v[6:9]
	v_mfma_f32_16x16x32_bf16 v[2:5], v[164:167], v[216:219], v[2:5]
	v_mfma_f32_16x16x32_bf16 v[46:49], v[160:163], v[176:179], v[46:49]
	v_mfma_f32_16x16x32_bf16 v[38:41], v[168:171], v[176:179], v[38:41]
	v_mfma_f32_16x16x32_bf16 v[30:33], v[160:163], v[184:187], v[30:33]
	v_mfma_f32_16x16x32_bf16 v[22:25], v[168:171], v[184:187], v[22:25]
	v_mfma_f32_16x16x32_bf16 v[14:17], v[160:163], v[212:215], v[14:17]
	v_mfma_f32_16x16x32_bf16 v[10:13], v[168:171], v[212:215], v[10:13]
	v_mfma_f32_16x16x32_bf16 v[6:9], v[160:163], v[220:223], v[6:9]
	v_mfma_f32_16x16x32_bf16 v[2:5], v[168:171], v[220:223], v[2:5]
	s_barrier
	s_add_u32 s84, s84, 0x100
	s_addc_u32 s85, s85, 0
	s_cmp_ge_i32 s96, s12
	s_mov_b64 s[8:9], s[20:21]
	s_mov_b32 s38, s96
	s_cbranch_scc0 .LBB0_298
;     __device__ __forceinline__ void operator()(const Acc& acc, const Unit& u, int wr, int wc, int fr, int fq) const {
;     ...
;             for (int m = 0; m < 4; ++m) { const size_t row = (size_t)(row0 + ai * 128 + m * 16); float s = 0.f;
; #pragma unroll
;                 for (int bj = 0; bj < 2; ++bj) { const size_t off = row * DM + c8 + bj * 128; f32x4 b0, b1; unpack8(bv[m][bj], b0, b1);
;                     const f32x4 o0 = b0 + acc[ai][bj][m][0] * scale, o1 = b1 + acc[ai][bj][m][1] * scale;
	v_pk_mul_f32 v[182:183], v[128:129], 0.5 op_sel_hi:[1,0]
	v_pk_mul_f32 v[184:185], v[126:127], 0.5 op_sel_hi:[1,0]
	v_pk_mul_f32 v[186:187], v[124:125], 0.5 op_sel_hi:[1,0]
	v_pk_mul_f32 v[188:189], v[122:123], 0.5 op_sel_hi:[1,0]
	v_pk_mul_f32 v[180:181], v[112:113], 0.5 op_sel_hi:[1,0]
	v_pk_mul_f32 v[178:179], v[110:111], 0.5 op_sel_hi:[1,0]
	v_pk_mul_f32 v[176:177], v[104:105], 0.5 op_sel_hi:[1,0]
	v_pk_mul_f32 v[174:175], v[102:103], 0.5 op_sel_hi:[1,0]
	v_pk_mul_f32 v[170:171], v[120:121], 0.5 op_sel_hi:[1,0]
	v_pk_mul_f32 v[168:169], v[118:119], 0.5 op_sel_hi:[1,0]
	v_pk_mul_f32 v[166:167], v[116:117], 0.5 op_sel_hi:[1,0]
	v_pk_mul_f32 v[164:165], v[114:115], 0.5 op_sel_hi:[1,0]
	v_pk_mul_f32 v[162:163], v[96:97], 0.5 op_sel_hi:[1,0]
	v_pk_mul_f32 v[160:161], v[94:95], 0.5 op_sel_hi:[1,0]
	v_pk_mul_f32 v[158:159], v[88:89], 0.5 op_sel_hi:[1,0]
	v_pk_mul_f32 v[156:157], v[86:87], 0.5 op_sel_hi:[1,0]
	v_pk_mul_f32 v[150:151], v[108:109], 0.5 op_sel_hi:[1,0]
	v_pk_mul_f32 v[148:149], v[106:107], 0.5 op_sel_hi:[1,0]
	v_pk_mul_f32 v[146:147], v[100:101], 0.5 op_sel_hi:[1,0]
	v_pk_mul_f32 v[144:145], v[98:99], 0.5 op_sel_hi:[1,0]
	v_pk_mul_f32 v[142:143], v[80:81], 0.5 op_sel_hi:[1,0]
	v_pk_mul_f32 v[140:141], v[78:79], 0.5 op_sel_hi:[1,0]
	v_pk_mul_f32 v[128:129], v[76:77], 0.5 op_sel_hi:[1,0]
	v_pk_mul_f32 v[126:127], v[74:75], 0.5 op_sel_hi:[1,0]
	v_pk_mul_f32 v[124:125], v[92:93], 0.5 op_sel_hi:[1,0]
	v_pk_mul_f32 v[122:123], v[90:91], 0.5 op_sel_hi:[1,0]
	v_pk_mul_f32 v[120:121], v[84:85], 0.5 op_sel_hi:[1,0]
	v_pk_mul_f32 v[118:119], v[82:83], 0.5 op_sel_hi:[1,0]
	v_pk_mul_f32 v[116:117], v[72:73], 0.5 op_sel_hi:[1,0]
	v_pk_mul_f32 v[114:115], v[70:71], 0.5 op_sel_hi:[1,0]
	v_pk_mul_f32 v[112:113], v[68:69], 0.5 op_sel_hi:[1,0]
	v_pk_mul_f32 v[110:111], v[66:67], 0.5 op_sel_hi:[1,0]
	v_pk_mul_f32 v[102:103], v[64:65], 0.5 op_sel_hi:[1,0]
	v_pk_mul_f32 v[104:105], v[62:63], 0.5 op_sel_hi:[1,0]
	v_pk_mul_f32 v[106:107], v[60:61], 0.5 op_sel_hi:[1,0]
	v_pk_mul_f32 v[108:109], v[58:59], 0.5 op_sel_hi:[1,0]
	v_pk_mul_f32 v[100:101], v[48:49], 0.5 op_sel_hi:[1,0]
	v_pk_mul_f32 v[98:99], v[46:47], 0.5 op_sel_hi:[1,0]
	v_pk_mul_f32 v[96:97], v[40:41], 0.5 op_sel_hi:[1,0]
	v_pk_mul_f32 v[94:95], v[38:39], 0.5 op_sel_hi:[1,0]
	v_pk_mul_f32 v[92:93], v[56:57], 0.5 op_sel_hi:[1,0]
	v_pk_mul_f32 v[90:91], v[54:55], 0.5 op_sel_hi:[1,0]
	v_pk_mul_f32 v[88:89], v[52:53], 0.5 op_sel_hi:[1,0]
	v_pk_mul_f32 v[86:87], v[50:51], 0.5 op_sel_hi:[1,0]
	v_pk_mul_f32 v[82:83], v[32:33], 0.5 op_sel_hi:[1,0]
	v_pk_mul_f32 v[80:81], v[30:31], 0.5 op_sel_hi:[1,0]
	v_pk_mul_f32 v[78:79], v[24:25], 0.5 op_sel_hi:[1,0]
	v_pk_mul_f32 v[76:77], v[22:23], 0.5 op_sel_hi:[1,0]
	v_pk_mul_f32 v[72:73], v[44:45], 0.5 op_sel_hi:[1,0]
	v_pk_mul_f32 v[70:71], v[42:43], 0.5 op_sel_hi:[1,0]
	v_pk_mul_f32 v[68:69], v[36:37], 0.5 op_sel_hi:[1,0]
	v_pk_mul_f32 v[66:67], v[34:35], 0.5 op_sel_hi:[1,0]
	v_pk_mul_f32 v[64:65], v[16:17], 0.5 op_sel_hi:[1,0]
	v_pk_mul_f32 v[62:63], v[14:15], 0.5 op_sel_hi:[1,0]
	v_pk_mul_f32 v[60:61], v[12:13], 0.5 op_sel_hi:[1,0]
	v_pk_mul_f32 v[58:59], v[10:11], 0.5 op_sel_hi:[1,0]
	v_pk_mul_f32 v[56:57], v[28:29], 0.5 op_sel_hi:[1,0]
	v_pk_mul_f32 v[54:55], v[26:27], 0.5 op_sel_hi:[1,0]
	v_pk_mul_f32 v[52:53], v[20:21], 0.5 op_sel_hi:[1,0]
	v_pk_mul_f32 v[50:51], v[18:19], 0.5 op_sel_hi:[1,0]
	v_pk_mul_f32 v[48:49], v[8:9], 0.5 op_sel_hi:[1,0]
	v_pk_mul_f32 v[46:47], v[6:7], 0.5 op_sel_hi:[1,0]
	v_pk_mul_f32 v[44:45], v[4:5], 0.5 op_sel_hi:[1,0]
	v_pk_mul_f32 v[42:43], v[2:3], 0.5 op_sel_hi:[1,0]
	v_readlane_b32 s96, v250, 43
	s_mov_b32 s73, s22
	s_mov_b32 s74, s23
	s_mov_b32 s75, vcc_lo

; #define PG8_STAGE(bufoff, gbase, voff) do { _Pragma("unroll") for (int _i = 0; _i < 2; ++_i) \
;         __builtin_amdgcn_global_load_lds((const unsigned*)((const char*)(gbase) + (voff)[_i]), (LAS unsigned*)(lds + (bufoff) + ldsw + _i * 8192), 16, 0, 0); } while (0)
; #define PG8_LDA(dst, b, h) do { _Pragma("unroll") for (int m = 0; m < 4; ++m) _Pragma("unroll") for (int k = 0; k < 2; ++k) dst[m][k] = *(const LAS bf16x8*)(lds + PG8_SA(b, h) + aoff + m * 2048 + k * 1024); } while (0)
; #define PG8_LDB(dst, b, h) do { _Pragma("unroll") for (int n = 0; n < 2; ++n) _Pragma("unroll") for (int k = 0; k < 2; ++k) dst[n][k] = *(const LAS bf16x8*)(lds + PG8_SB(b, h) + boff + n * 2048 + k * 1024); } while (0)
; #define PG8_MMA(ai, bj, At, Bt) do { __builtin_amdgcn_s_setprio(1); _Pragma("unroll") for (int m = 0; m < 4; ++m) _Pragma("unroll") for (int n = 0; n < 2; ++n) _Pragma("unroll") for (int k = 0; k < 2; ++k) \
;         acc[ai][bj][m][n] = __builtin_amdgcn_mfma_f32_16x16x32_bf16(Bt[n][k], At[m][k], acc[ai][bj][m][n], 0, 0, 0); __builtin_amdgcn_s_setprio(0); } while (0)
; #define PG8_WAIT_V(n) asm volatile("s_waitcnt vmcnt(" #n ")" ::: "memory")
; #define PG8_WAIT_L(n) asm volatile("s_waitcnt lgkmcnt(" #n ")" ::: "memory")
; template <class Epi, class Sched>
; __device__ __forceinline__ void gemm_phase(LAS unsigned char* lds, const Gemm g, const Sched& S, const Epi& E) {
;     ...
;             const bool last = (t == nt - 2);
;             const char* a1 = cA + (size_t)(t + 1) * kstep;
;             const char* a2 = last ? nA : cA + (size_t)(t + 2) * kstep; const char* b2 = last ? nB : cB + (size_t)(t + 2) * kstep;
;             const char* a3 = a2 + kstep; const char* b3 = b2 + kstep;
;             if constexpr (Epi::MIDK) { if (t == (nt >> 1)) { int fr_ = fr, fq_ = fq; asm volatile("" : "+v"(fr_), "+v"(fq_)); E.mid(acc, cur, wr, wc, fr_, fq_); } }
;             PG8_LDB(B0, 0, 0); PG8_LDB(B1, 0, 1); PG8_SCHED; PG8_LDA(At, 0, 0); PG8_STAGE(PG8_SA(1, 1), a1 + hsA, voffA);
;             PG8_WAIT_V(8); PG8_WAIT_L(0); PG8_BAR; PG8_MMA(0, 0, At, B0); PG8_MMA(0, 1, At, B1); PG8_BAR; PG8_SCHED;
;             PG8_LDA(At, 0, 1); PG8_STAGE(PG8_SB(0, 0), b2, voffB); PG8_STAGE(PG8_SB(0, 1), b2 + hsB, voffB); PG8_STAGE(PG8_SA(0, 0), a2, voffA);
;             PG8_WAIT_V(8); PG8_WAIT_L(0); PG8_BAR; PG8_MMA(1, 0, At, B0); PG8_MMA(1, 1, At, B1); PG8_BAR; PG8_SCHED;
.LBB0_485:
	s_add_i32 s85, s40, 2
	s_add_u32 s41, s38, 0xfffc0080
	s_addc_u32 s42, s39, -1
	s_add_i32 s74, 0, 0x10000
	s_cmp_eq_u32 s26, s40
	s_cselect_b32 s43, s47, s42
	s_cselect_b32 s42, s49, s41
	s_cselect_b32 s41, s73, s84
	s_cselect_b32 s40, s82, s83
	s_add_i32 s75, 0, 0x14000
	v_add_u32_e32 v154, s74, v165
	v_add_u32_e32 v162, s75, v165
	ds_read_b128 v[142:145], v154
	ds_read_b128 v[146:149], v154 offset:1024
	ds_read_b128 v[150:153], v154 offset:2048
	ds_read_b128 v[154:157], v154 offset:3072
	ds_read_b128 v[158:161], v162
	ds_read_b128 v[168:171], v162 offset:1024
	ds_read_b128 v[172:175], v162 offset:2048
	ds_read_b128 v[176:179], v162 offset:3072
	v_lshl_add_u64 v[228:229], s[38:39], 0, v[138:139]
	s_add_i32 m0, s16, 0xc000
	ds_read_b128 v[180:183], v166
	ds_read_b128 v[184:187], v166 offset:1024
	ds_read_b128 v[188:191], v166 offset:2048
	ds_read_b128 v[208:211], v166 offset:3072
	ds_read_b128 v[212:215], v166 offset:4096
	ds_read_b128 v[216:219], v166 offset:5120
	ds_read_b128 v[220:223], v166 offset:6144
	ds_read_b128 v[224:227], v166 offset:7168
	global_load_lds_dwordx4 v[228:229], off
	v_lshl_add_u64 v[228:229], s[38:39], 0, v[140:141]
	s_add_i32 m0, s16, 0xe000
	s_nop 0
	global_load_lds_dwordx4 v[228:229], off
	s_waitcnt vmcnt(8)
	s_waitcnt lgkmcnt(0)
	s_barrier
	s_waitcnt lgkmcnt(0)
	v_mfma_f32_16x16x32_bf16 v[122:125], v[142:145], v[180:183], v[122:125]
	v_mfma_f32_16x16x32_bf16 v[114:117], v[150:153], v[180:183], v[114:117]
	v_mfma_f32_16x16x32_bf16 v[110:113], v[142:145], v[188:191], v[110:113]
	v_mfma_f32_16x16x32_bf16 v[98:101], v[150:153], v[188:191], v[98:101]
	v_mfma_f32_16x16x32_bf16 v[94:97], v[142:145], v[212:215], v[94:97]
	v_mfma_f32_16x16x32_bf16 v[82:85], v[150:153], v[212:215], v[82:85]
	v_mfma_f32_16x16x32_bf16 v[78:81], v[142:145], v[220:223], v[78:81]
	v_mfma_f32_16x16x32_bf16 v[66:69], v[150:153], v[220:223], v[66:69]
	v_mfma_f32_16x16x32_bf16 v[122:125], v[146:149], v[184:187], v[122:125]
	v_mfma_f32_16x16x32_bf16 v[114:117], v[154:157], v[184:187], v[114:117]
	v_mfma_f32_16x16x32_bf16 v[110:113], v[146:149], v[208:211], v[110:113]
	v_mfma_f32_16x16x32_bf16 v[98:101], v[154:157], v[208:211], v[98:101]
	v_mfma_f32_16x16x32_bf16 v[94:97], v[146:149], v[216:219], v[94:97]
	v_mfma_f32_16x16x32_bf16 v[82:85], v[154:157], v[216:219], v[82:85]
	v_mfma_f32_16x16x32_bf16 v[78:81], v[146:149], v[224:227], v[78:81]
	v_mfma_f32_16x16x32_bf16 v[66:69], v[154:157], v[224:227], v[66:69]
	v_mfma_f32_16x16x32_bf16 v[126:129], v[158:161], v[180:183], v[126:129]
	v_mfma_f32_16x16x32_bf16 v[118:121], v[172:175], v[180:183], v[118:121]
	v_mfma_f32_16x16x32_bf16 v[106:109], v[158:161], v[188:191], v[106:109]
	v_mfma_f32_16x16x32_bf16 v[102:105], v[172:175], v[188:191], v[102:105]
	v_mfma_f32_16x16x32_bf16 v[90:93], v[158:161], v[212:215], v[90:93]
	v_mfma_f32_16x16x32_bf16 v[86:89], v[172:175], v[212:215], v[86:89]
	v_mfma_f32_16x16x32_bf16 v[74:77], v[158:161], v[220:223], v[74:77]
	v_mfma_f32_16x16x32_bf16 v[70:73], v[172:175], v[220:223], v[70:73]
	v_mfma_f32_16x16x32_bf16 v[126:129], v[168:171], v[184:187], v[126:129]
	v_mfma_f32_16x16x32_bf16 v[118:121], v[176:179], v[184:187], v[118:121]
	v_mfma_f32_16x16x32_bf16 v[106:109], v[168:171], v[208:211], v[106:109]
	v_mfma_f32_16x16x32_bf16 v[102:105], v[176:179], v[208:211], v[102:105]
	v_mfma_f32_16x16x32_bf16 v[90:93], v[168:171], v[216:219], v[90:93]
	v_mfma_f32_16x16x32_bf16 v[86:89], v[176:179], v[216:219], v[86:89]
	v_mfma_f32_16x16x32_bf16 v[74:77], v[168:171], v[224:227], v[74:77]
	v_mfma_f32_16x16x32_bf16 v[70:73], v[176:179], v[224:227], v[70:73]
	s_barrier
	s_add_i32 s74, s74, s12
	v_lshl_add_u64 v[228:229], s[40:41], 0, v[0:1]
	s_mov_b32 m0, s74
	ds_read_b128 v[180:183], v166 offset:16384
	ds_read_b128 v[184:187], v166 offset:17408
	ds_read_b128 v[188:191], v166 offset:18432
	ds_read_b128 v[208:211], v166 offset:19456
	ds_read_b128 v[212:215], v166 offset:20480
	ds_read_b128 v[216:219], v166 offset:21504
	ds_read_b128 v[220:223], v166 offset:22528
	ds_read_b128 v[224:227], v166 offset:23552
	global_load_lds_dwordx4 v[228:229], off
	s_add_i32 m0, s74, 0x2000
	s_add_u32 vcc_lo, s40, 0x40000
	v_lshl_add_u64 v[230:231], s[40:41], 0, v[130:131]
	s_addc_u32 vcc_hi, s41, 0
	s_add_i32 s74, s75, s12
	global_load_lds_dwordx4 v[230:231], off
	v_lshl_add_u64 v[232:233], vcc, 0, v[0:1]
	s_mov_b32 m0, s74
	v_lshl_add_u64 v[238:239], s[42:43], 0, v[132:133]
	global_load_lds_dwordx4 v[232:233], off
	v_lshl_add_u64 v[232:233], vcc, 0, v[130:131]
	s_add_i32 m0, s74, 0x2000
	s_nop 0
	global_load_lds_dwordx4 v[232:233], off
	v_lshl_add_u64 v[232:233], s[42:43], 0, v[134:135]
	s_mov_b32 m0, s16
	s_nop 0
	global_load_lds_dwordx4 v[232:233], off
	s_mov_b32 m0, s52
	s_nop 0
	global_load_lds_dwordx4 v[238:239], off
	s_waitcnt vmcnt(8)
	s_waitcnt lgkmcnt(0)
	s_barrier
; #define PG8_STAGE(bufoff, gbase, voff) do { _Pragma("unroll") for (int _i = 0; _i < 2; ++_i) \
;         __builtin_amdgcn_global_load_lds((const unsigned*)((const char*)(gbase) + (voff)[_i]), (LAS unsigned*)(lds + (bufoff) + ldsw + _i * 8192), 16, 0, 0); } while (0)
; #define PG8_LDA(dst, b, h) do { _Pragma("unroll") for (int m = 0; m < 4; ++m) _Pragma("unroll") for (int k = 0; k < 2; ++k) dst[m][k] = *(const LAS bf16x8*)(lds + PG8_SA(b, h) + aoff + m * 2048 + k * 1024); } while (0)
; #define PG8_LDB(dst, b, h) do { _Pragma("unroll") for (int n = 0; n < 2; ++n) _Pragma("unroll") for (int k = 0; k < 2; ++k) dst[n][k] = *(const LAS bf16x8*)(lds + PG8_SB(b, h) + boff + n * 2048 + k * 1024); } while (0)
; #define PG8_MMA(ai, bj, At, Bt) do { __builtin_amdgcn_s_setprio(1); _Pragma("unroll") for (int m = 0; m < 4; ++m) _Pragma("unroll") for (int n = 0; n < 2; ++n) _Pragma("unroll") for (int k = 0; k < 2; ++k) \
;         acc[ai][bj][m][n] = __builtin_amdgcn_mfma_f32_16x16x32_bf16(Bt[n][k], At[m][k], acc[ai][bj][m][n], 0, 0, 0); __builtin_amdgcn_s_setprio(0); } while (0)
; #define PG8_WAIT_V(n) asm volatile("s_waitcnt vmcnt(" #n ")" ::: "memory")
; #define PG8_WAIT_L(n) asm volatile("s_waitcnt lgkmcnt(" #n ")" ::: "memory")
; #define PG8_BAR __builtin_amdgcn_s_barrier()
; #define PG8_SCHED __builtin_amdgcn_sched_barrier(0)
; template <class Epi, class Sched>
; __device__ __forceinline__ void gemm_phase(LAS unsigned char* lds, const Gemm g, const Sched& S, const Epi& E) {
;     ...
;             PG8_WAIT_V(8); PG8_WAIT_L(0); PG8_BAR; PG8_MMA(1, 0, At, B0); PG8_MMA(1, 1, At, B1); PG8_BAR; PG8_SCHED;
;             PG8_LDB(B0, 1, 0); PG8_LDB(B1, 1, 1); PG8_SCHED; PG8_LDA(At, 1, 0); PG8_STAGE(PG8_SA(0, 1), a2 + hsA, voffA);
;             PG8_WAIT_V(8); PG8_WAIT_L(0); PG8_BAR; PG8_MMA(0, 0, At, B0); PG8_MMA(0, 1, At, B1); PG8_BAR; PG8_SCHED;
	s_waitcnt lgkmcnt(0)
	v_mfma_f32_16x16x32_bf16 v[62:65], v[142:145], v[180:183], v[62:65]
	v_mfma_f32_16x16x32_bf16 v[50:53], v[150:153], v[180:183], v[50:53]
	v_mfma_f32_16x16x32_bf16 v[46:49], v[142:145], v[188:191], v[46:49]
	v_mfma_f32_16x16x32_bf16 v[34:37], v[150:153], v[188:191], v[34:37]
	v_mfma_f32_16x16x32_bf16 v[30:33], v[142:145], v[212:215], v[30:33]
	v_mfma_f32_16x16x32_bf16 v[18:21], v[150:153], v[212:215], v[18:21]
	v_mfma_f32_16x16x32_bf16 v[10:13], v[142:145], v[220:223], v[10:13]
	v_mfma_f32_16x16x32_bf16 v[2:5], v[150:153], v[220:223], v[2:5]
	v_mfma_f32_16x16x32_bf16 v[62:65], v[146:149], v[184:187], v[62:65]
	v_mfma_f32_16x16x32_bf16 v[50:53], v[154:157], v[184:187], v[50:53]
	v_mfma_f32_16x16x32_bf16 v[46:49], v[146:149], v[208:211], v[46:49]
	v_mfma_f32_16x16x32_bf16 v[34:37], v[154:157], v[208:211], v[34:37]
	v_mfma_f32_16x16x32_bf16 v[30:33], v[146:149], v[216:219], v[30:33]
	v_mfma_f32_16x16x32_bf16 v[18:21], v[154:157], v[216:219], v[18:21]
	v_mfma_f32_16x16x32_bf16 v[10:13], v[146:149], v[224:227], v[10:13]
	v_mfma_f32_16x16x32_bf16 v[2:5], v[154:157], v[224:227], v[2:5]
	v_mfma_f32_16x16x32_bf16 v[58:61], v[158:161], v[180:183], v[58:61]
	v_mfma_f32_16x16x32_bf16 v[54:57], v[172:175], v[180:183], v[54:57]
	v_mfma_f32_16x16x32_bf16 v[42:45], v[158:161], v[188:191], v[42:45]
	v_mfma_f32_16x16x32_bf16 v[38:41], v[172:175], v[188:191], v[38:41]
	v_mfma_f32_16x16x32_bf16 v[26:29], v[158:161], v[212:215], v[26:29]
	v_mfma_f32_16x16x32_bf16 v[22:25], v[172:175], v[212:215], v[22:25]
	v_mfma_f32_16x16x32_bf16 v[14:17], v[158:161], v[220:223], v[14:17]
	v_mfma_f32_16x16x32_bf16 v[6:9], v[172:175], v[220:223], v[6:9]
	v_mfma_f32_16x16x32_bf16 v[58:61], v[168:171], v[184:187], v[58:61]
	v_mfma_f32_16x16x32_bf16 v[54:57], v[176:179], v[184:187], v[54:57]
	v_mfma_f32_16x16x32_bf16 v[42:45], v[168:171], v[208:211], v[42:45]
	v_mfma_f32_16x16x32_bf16 v[38:41], v[176:179], v[208:211], v[38:41]
	v_mfma_f32_16x16x32_bf16 v[26:29], v[168:171], v[216:219], v[26:29]
	v_mfma_f32_16x16x32_bf16 v[22:25], v[176:179], v[216:219], v[22:25]
	v_mfma_f32_16x16x32_bf16 v[14:17], v[168:171], v[224:227], v[14:17]
	v_mfma_f32_16x16x32_bf16 v[6:9], v[176:179], v[224:227], v[6:9]
	s_barrier
	s_add_i32 s74, 0, 0x18000
	s_add_i32 s75, 0, 0x1c000
	v_add_u32_e32 v154, s74, v165
	v_add_u32_e32 v162, s75, v165
	ds_read_b128 v[142:145], v154
	ds_read_b128 v[146:149], v154 offset:1024
	ds_read_b128 v[150:153], v154 offset:2048
	ds_read_b128 v[154:157], v154 offset:3072
	ds_read_b128 v[158:161], v162
	ds_read_b128 v[168:171], v162 offset:1024
	ds_read_b128 v[172:175], v162 offset:2048
	ds_read_b128 v[176:179], v162 offset:3072
	s_add_u32 s42, s42, 0x40000
	s_addc_u32 s43, s43, 0
	s_mov_b32 m0, s64
	v_lshl_add_u64 v[240:241], s[42:43], 0, v[134:135]
	ds_read_b128 v[180:183], v166 offset:32768
	ds_read_b128 v[184:187], v166 offset:33792
	ds_read_b128 v[188:191], v166 offset:34816
	ds_read_b128 v[208:211], v166 offset:35840
	ds_read_b128 v[212:215], v166 offset:36864
	ds_read_b128 v[216:219], v166 offset:37888
	ds_read_b128 v[220:223], v166 offset:38912
	ds_read_b128 v[224:227], v166 offset:39936
	global_load_lds_dwordx4 v[240:241], off
	v_lshl_add_u64 v[240:241], s[42:43], 0, v[132:133]
	s_mov_b32 m0, s78
	s_nop 0
	global_load_lds_dwordx4 v[240:241], off
	s_waitcnt vmcnt(8)
	s_waitcnt lgkmcnt(0)
	s_barrier
	s_waitcnt lgkmcnt(0)
	v_mfma_f32_16x16x32_bf16 v[122:125], v[142:145], v[180:183], v[122:125]
	v_mfma_f32_16x16x32_bf16 v[114:117], v[150:153], v[180:183], v[114:117]
	v_mfma_f32_16x16x32_bf16 v[110:113], v[142:145], v[188:191], v[110:113]
	v_mfma_f32_16x16x32_bf16 v[98:101], v[150:153], v[188:191], v[98:101]
	v_mfma_f32_16x16x32_bf16 v[94:97], v[142:145], v[212:215], v[94:97]
	v_mfma_f32_16x16x32_bf16 v[82:85], v[150:153], v[212:215], v[82:85]
	v_mfma_f32_16x16x32_bf16 v[78:81], v[142:145], v[220:223], v[78:81]
	v_mfma_f32_16x16x32_bf16 v[66:69], v[150:153], v[220:223], v[66:69]
	v_mfma_f32_16x16x32_bf16 v[122:125], v[146:149], v[184:187], v[122:125]
	v_mfma_f32_16x16x32_bf16 v[114:117], v[154:157], v[184:187], v[114:117]
	v_mfma_f32_16x16x32_bf16 v[110:113], v[146:149], v[208:211], v[110:113]
	v_mfma_f32_16x16x32_bf16 v[98:101], v[154:157], v[208:211], v[98:101]
	v_mfma_f32_16x16x32_bf16 v[94:97], v[146:149], v[216:219], v[94:97]
	v_mfma_f32_16x16x32_bf16 v[82:85], v[154:157], v[216:219], v[82:85]
	v_mfma_f32_16x16x32_bf16 v[78:81], v[146:149], v[224:227], v[78:81]
	v_mfma_f32_16x16x32_bf16 v[66:69], v[154:157], v[224:227], v[66:69]
	v_mfma_f32_16x16x32_bf16 v[126:129], v[158:161], v[180:183], v[126:129]
	v_mfma_f32_16x16x32_bf16 v[118:121], v[172:175], v[180:183], v[118:121]
	v_mfma_f32_16x16x32_bf16 v[106:109], v[158:161], v[188:191], v[106:109]
	v_mfma_f32_16x16x32_bf16 v[102:105], v[172:175], v[188:191], v[102:105]
	v_mfma_f32_16x16x32_bf16 v[90:93], v[158:161], v[212:215], v[90:93]
	v_mfma_f32_16x16x32_bf16 v[86:89], v[172:175], v[212:215], v[86:89]
	v_mfma_f32_16x16x32_bf16 v[74:77], v[158:161], v[220:223], v[74:77]
	v_mfma_f32_16x16x32_bf16 v[70:73], v[172:175], v[220:223], v[70:73]
	v_mfma_f32_16x16x32_bf16 v[126:129], v[168:171], v[184:187], v[126:129]
	v_mfma_f32_16x16x32_bf16 v[118:121], v[176:179], v[184:187], v[118:121]
	v_mfma_f32_16x16x32_bf16 v[106:109], v[168:171], v[208:211], v[106:109]
	v_mfma_f32_16x16x32_bf16 v[102:105], v[176:179], v[208:211], v[102:105]
	v_mfma_f32_16x16x32_bf16 v[90:93], v[168:171], v[216:219], v[90:93]
	v_mfma_f32_16x16x32_bf16 v[86:89], v[176:179], v[216:219], v[86:89]
	v_mfma_f32_16x16x32_bf16 v[74:77], v[168:171], v[224:227], v[74:77]
	v_mfma_f32_16x16x32_bf16 v[70:73], v[176:179], v[224:227], v[70:73]
	s_barrier
; #define PG8_STAGE(bufoff, gbase, voff) do { _Pragma("unroll") for (int _i = 0; _i < 2; ++_i) \
;         __builtin_amdgcn_global_load_lds((const unsigned*)((const char*)(gbase) + (voff)[_i]), (LAS unsigned*)(lds + (bufoff) + ldsw + _i * 8192), 16, 0, 0); } while (0)
; #define PG8_LDA(dst, b, h) do { _Pragma("unroll") for (int m = 0; m < 4; ++m) _Pragma("unroll") for (int k = 0; k < 2; ++k) dst[m][k] = *(const LAS bf16x8*)(lds + PG8_SA(b, h) + aoff + m * 2048 + k * 1024); } while (0)
; #define PG8_MMA(ai, bj, At, Bt) do { __builtin_amdgcn_s_setprio(1); _Pragma("unroll") for (int m = 0; m < 4; ++m) _Pragma("unroll") for (int n = 0; n < 2; ++n) _Pragma("unroll") for (int k = 0; k < 2; ++k) \
;         acc[ai][bj][m][n] = __builtin_amdgcn_mfma_f32_16x16x32_bf16(Bt[n][k], At[m][k], acc[ai][bj][m][n], 0, 0, 0); __builtin_amdgcn_s_setprio(0); } while (0)
; #define PG8_WAIT_V(n) asm volatile("s_waitcnt vmcnt(" #n ")" ::: "memory")
; #define PG8_WAIT_L(n) asm volatile("s_waitcnt lgkmcnt(" #n ")" ::: "memory")
; #define PG8_BAR __builtin_amdgcn_s_barrier()
; #define PG8_SCHED __builtin_amdgcn_sched_barrier(0)
; template <class Epi, class Sched>
; __device__ __forceinline__ void gemm_phase(LAS unsigned char* lds, const Gemm g, const Sched& S, const Epi& E) {
;     ...
;             PG8_LDA(At, 1, 1); PG8_STAGE(PG8_SB(1, 0), b3, voffB); PG8_STAGE(PG8_SB(1, 1), b3 + hsB, voffB); PG8_STAGE(PG8_SA(1, 0), a3, voffA);
;             PG8_WAIT_V(8); PG8_WAIT_L(0); PG8_BAR; PG8_MMA(1, 0, At, B0); PG8_MMA(1, 1, At, B1); PG8_BAR; PG8_SCHED;
;         }
	s_add_i32 s42, s74, s12
	v_lshl_add_u64 v[228:229], v[228:229], 0, s[18:19]
	s_mov_b32 m0, s42
	ds_read_b128 v[180:183], v166 offset:49152
	ds_read_b128 v[184:187], v166 offset:50176
	ds_read_b128 v[188:191], v166 offset:51200
	ds_read_b128 v[208:211], v166 offset:52224
	ds_read_b128 v[212:215], v166 offset:53248
	ds_read_b128 v[216:219], v166 offset:54272
	ds_read_b128 v[220:223], v166 offset:55296
	ds_read_b128 v[224:227], v166 offset:56320
	global_load_lds_dwordx4 v[228:229], off
	s_add_i32 m0, s42, 0x2000
	s_add_u32 s40, s40, 0x40080
	v_lshl_add_u64 v[228:229], v[230:231], 0, s[18:19]
	s_addc_u32 s41, s41, 0
	s_add_i32 s42, s75, s12
	global_load_lds_dwordx4 v[228:229], off
	v_lshl_add_u64 v[228:229], s[40:41], 0, v[0:1]
	s_mov_b32 m0, s42
	s_nop 0
	global_load_lds_dwordx4 v[228:229], off
	v_lshl_add_u64 v[228:229], s[40:41], 0, v[130:131]
	s_add_i32 m0, s42, 0x2000
	s_nop 0
	global_load_lds_dwordx4 v[228:229], off
	v_lshl_add_u64 v[228:229], v[232:233], 0, s[18:19]
	s_mov_b32 m0, s1
	s_nop 0
	global_load_lds_dwordx4 v[228:229], off
	v_lshl_add_u64 v[228:229], v[238:239], 0, s[18:19]
	s_mov_b32 m0, s7
	s_nop 0
	global_load_lds_dwordx4 v[228:229], off
	s_waitcnt vmcnt(8)
	s_waitcnt lgkmcnt(0)
	s_barrier
	s_waitcnt lgkmcnt(0)
	v_mfma_f32_16x16x32_bf16 v[62:65], v[142:145], v[180:183], v[62:65]
	v_mfma_f32_16x16x32_bf16 v[50:53], v[150:153], v[180:183], v[50:53]
	v_mfma_f32_16x16x32_bf16 v[46:49], v[142:145], v[188:191], v[46:49]
	v_mfma_f32_16x16x32_bf16 v[34:37], v[150:153], v[188:191], v[34:37]
	v_mfma_f32_16x16x32_bf16 v[30:33], v[142:145], v[212:215], v[30:33]
	v_mfma_f32_16x16x32_bf16 v[18:21], v[150:153], v[212:215], v[18:21]
	v_mfma_f32_16x16x32_bf16 v[10:13], v[142:145], v[220:223], v[10:13]
	v_mfma_f32_16x16x32_bf16 v[2:5], v[150:153], v[220:223], v[2:5]
	v_mfma_f32_16x16x32_bf16 v[62:65], v[146:149], v[184:187], v[62:65]
	v_mfma_f32_16x16x32_bf16 v[50:53], v[154:157], v[184:187], v[50:53]
	v_mfma_f32_16x16x32_bf16 v[46:49], v[146:149], v[208:211], v[46:49]
	v_mfma_f32_16x16x32_bf16 v[34:37], v[154:157], v[208:211], v[34:37]
	v_mfma_f32_16x16x32_bf16 v[30:33], v[146:149], v[216:219], v[30:33]
	v_mfma_f32_16x16x32_bf16 v[18:21], v[154:157], v[216:219], v[18:21]
	v_mfma_f32_16x16x32_bf16 v[10:13], v[146:149], v[224:227], v[10:13]
	v_mfma_f32_16x16x32_bf16 v[2:5], v[154:157], v[224:227], v[2:5]
	v_mfma_f32_16x16x32_bf16 v[58:61], v[158:161], v[180:183], v[58:61]
	v_mfma_f32_16x16x32_bf16 v[54:57], v[172:175], v[180:183], v[54:57]
	v_mfma_f32_16x16x32_bf16 v[42:45], v[158:161], v[188:191], v[42:45]
	v_mfma_f32_16x16x32_bf16 v[38:41], v[172:175], v[188:191], v[38:41]
	v_mfma_f32_16x16x32_bf16 v[26:29], v[158:161], v[212:215], v[26:29]
	v_mfma_f32_16x16x32_bf16 v[22:25], v[172:175], v[212:215], v[22:25]
	v_mfma_f32_16x16x32_bf16 v[14:17], v[158:161], v[220:223], v[14:17]
	v_mfma_f32_16x16x32_bf16 v[6:9], v[172:175], v[220:223], v[6:9]
	v_mfma_f32_16x16x32_bf16 v[58:61], v[168:171], v[184:187], v[58:61]
	v_mfma_f32_16x16x32_bf16 v[54:57], v[176:179], v[184:187], v[54:57]
	v_mfma_f32_16x16x32_bf16 v[42:45], v[168:171], v[208:211], v[42:45]
	v_mfma_f32_16x16x32_bf16 v[38:41], v[176:179], v[208:211], v[38:41]
	v_mfma_f32_16x16x32_bf16 v[26:29], v[168:171], v[216:219], v[26:29]
	v_mfma_f32_16x16x32_bf16 v[22:25], v[176:179], v[216:219], v[22:25]
	v_mfma_f32_16x16x32_bf16 v[14:17], v[168:171], v[224:227], v[14:17]
	v_mfma_f32_16x16x32_bf16 v[6:9], v[176:179], v[224:227], v[6:9]
	s_barrier
	s_add_u32 s38, s38, 0x100
	s_addc_u32 s39, s39, 0
	s_add_u32 s83, s83, 0x100
	s_addc_u32 s84, s84, 0
	s_cmp_ge_i32 s85, s11
	s_mov_b32 s40, s85
	s_cbranch_scc0 .LBB0_485

; #define PG8_STAGE(bufoff, gbase, voff) do { _Pragma("unroll") for (int _i = 0; _i < 2; ++_i) \
;         __builtin_amdgcn_global_load_lds((const unsigned*)((const char*)(gbase) + (voff)[_i]), (LAS unsigned*)(lds + (bufoff) + ldsw + _i * 8192), 16, 0, 0); } while (0)
; #define PG8_LDA(dst, b, h) do { _Pragma("unroll") for (int m = 0; m < 4; ++m) _Pragma("unroll") for (int k = 0; k < 2; ++k) dst[m][k] = *(const LAS bf16x8*)(lds + PG8_SA(b, h) + aoff + m * 2048 + k * 1024); } while (0)
; #define PG8_LDB(dst, b, h) do { _Pragma("unroll") for (int n = 0; n < 2; ++n) _Pragma("unroll") for (int k = 0; k < 2; ++k) dst[n][k] = *(const LAS bf16x8*)(lds + PG8_SB(b, h) + boff + n * 2048 + k * 1024); } while (0)
; #define PG8_MMA(ai, bj, At, Bt) do { __builtin_amdgcn_s_setprio(1); _Pragma("unroll") for (int m = 0; m < 4; ++m) _Pragma("unroll") for (int n = 0; n < 2; ++n) _Pragma("unroll") for (int k = 0; k < 2; ++k) \
;         acc[ai][bj][m][n] = __builtin_amdgcn_mfma_f32_16x16x32_bf16(Bt[n][k], At[m][k], acc[ai][bj][m][n], 0, 0, 0); __builtin_amdgcn_s_setprio(0); } while (0)
; #define PG8_WAIT_V(n) asm volatile("s_waitcnt vmcnt(" #n ")" ::: "memory")
; #define PG8_WAIT_L(n) asm volatile("s_waitcnt lgkmcnt(" #n ")" ::: "memory")
; template <class Epi, class Sched>
; __device__ __forceinline__ void gemm_phase(LAS unsigned char* lds, const Gemm g, const Sched& S, const Epi& E) {
;     ...
;             const bool last = (t == nt - 2);
;             const char* a1 = cA + (size_t)(t + 1) * kstep;
;             const char* a2 = last ? nA : cA + (size_t)(t + 2) * kstep; const char* b2 = last ? nB : cB + (size_t)(t + 2) * kstep;
;             const char* a3 = a2 + kstep; const char* b3 = b2 + kstep;
;             if constexpr (Epi::MIDK) { if (t == (nt >> 1)) { int fr_ = fr, fq_ = fq; asm volatile("" : "+v"(fr_), "+v"(fq_)); E.mid(acc, cur, wr, wc, fr_, fq_); } }
;             PG8_LDB(B0, 0, 0); PG8_LDB(B1, 0, 1); PG8_SCHED; PG8_LDA(At, 0, 0); PG8_STAGE(PG8_SA(1, 1), a1 + hsA, voffA);
;             PG8_WAIT_V(8); PG8_WAIT_L(0); PG8_BAR; PG8_MMA(0, 0, At, B0); PG8_MMA(0, 1, At, B1); PG8_BAR; PG8_SCHED;
;             PG8_LDA(At, 0, 1); PG8_STAGE(PG8_SB(0, 0), b2, voffB); PG8_STAGE(PG8_SB(0, 1), b2 + hsB, voffB); PG8_STAGE(PG8_SA(0, 0), a2, voffA);
;             PG8_WAIT_V(8); PG8_WAIT_L(0); PG8_BAR; PG8_MMA(1, 0, At, B0); PG8_MMA(1, 1, At, B1); PG8_BAR; PG8_SCHED;
.LBB0_536:
	s_add_i32 s83, s46, 2
	s_add_u32 s74, s44, 0xfffc0080
	s_addc_u32 s47, s45, -1
	s_add_i32 s75, 0, 0x10000
	s_cmp_eq_u32 s51, s46
	s_cselect_b32 s47, s73, s47
	s_cselect_b32 s46, s76, s74
	v_add_u32_e32 v144, s75, v148
	s_cselect_b32 s85, s77, s82
	s_cselect_b32 s84, s78, s80
	s_add_i32 s74, 0, 0x14000
	ds_read_b128 v[140:143], v144
	ds_read_b128 v[150:153], v144 offset:1024
	ds_read_b128 v[154:157], v144 offset:2048
	ds_read_b128 v[158:161], v144 offset:3072
	v_add_u32_e32 v144, s74, v148
	ds_read_b128 v[162:165], v144
	ds_read_b128 v[166:169], v144 offset:1024
	ds_read_b128 v[170:173], v144 offset:2048
	ds_read_b128 v[174:177], v144 offset:3072
	v_lshl_add_u64 v[144:145], s[44:45], 0, v[136:137]
	s_add_i32 m0, s11, 0xc000
	ds_read_b128 v[178:181], v149
	ds_read_b128 v[182:185], v149 offset:1024
	ds_read_b128 v[186:189], v149 offset:2048
	ds_read_b128 v[208:211], v149 offset:3072
	ds_read_b128 v[212:215], v149 offset:4096
	ds_read_b128 v[216:219], v149 offset:5120
	ds_read_b128 v[220:223], v149 offset:6144
	ds_read_b128 v[224:227], v149 offset:7168
	global_load_lds_dwordx4 v[144:145], off
	v_lshl_add_u64 v[144:145], s[44:45], 0, v[138:139]
	s_add_i32 m0, s11, 0xe000
	s_nop 0
	global_load_lds_dwordx4 v[144:145], off
	s_waitcnt vmcnt(8)
	s_waitcnt lgkmcnt(0)
	s_barrier
	s_waitcnt lgkmcnt(0)
	v_mfma_f32_16x16x32_bf16 v[122:125], v[140:143], v[178:181], v[122:125]
	v_mfma_f32_16x16x32_bf16 v[126:129], v[154:157], v[178:181], v[126:129]
	v_mfma_f32_16x16x32_bf16 v[110:113], v[140:143], v[186:189], v[110:113]
	v_mfma_f32_16x16x32_bf16 v[106:109], v[154:157], v[186:189], v[106:109]
	v_mfma_f32_16x16x32_bf16 v[94:97], v[140:143], v[212:215], v[94:97]
	v_mfma_f32_16x16x32_bf16 v[90:93], v[154:157], v[212:215], v[90:93]
	v_mfma_f32_16x16x32_bf16 v[78:81], v[140:143], v[220:223], v[78:81]
	v_mfma_f32_16x16x32_bf16 v[74:77], v[154:157], v[220:223], v[74:77]
	v_mfma_f32_16x16x32_bf16 v[122:125], v[150:153], v[182:185], v[122:125]
	v_mfma_f32_16x16x32_bf16 v[126:129], v[158:161], v[182:185], v[126:129]
	v_mfma_f32_16x16x32_bf16 v[110:113], v[150:153], v[208:211], v[110:113]
	v_mfma_f32_16x16x32_bf16 v[106:109], v[158:161], v[208:211], v[106:109]
	v_mfma_f32_16x16x32_bf16 v[94:97], v[150:153], v[216:219], v[94:97]
	v_mfma_f32_16x16x32_bf16 v[90:93], v[158:161], v[216:219], v[90:93]
	v_mfma_f32_16x16x32_bf16 v[78:81], v[150:153], v[224:227], v[78:81]
	v_mfma_f32_16x16x32_bf16 v[74:77], v[158:161], v[224:227], v[74:77]
	v_mfma_f32_16x16x32_bf16 v[118:121], v[162:165], v[178:181], v[118:121]
	v_mfma_f32_16x16x32_bf16 v[114:117], v[170:173], v[178:181], v[114:117]
	v_mfma_f32_16x16x32_bf16 v[102:105], v[162:165], v[186:189], v[102:105]
	v_mfma_f32_16x16x32_bf16 v[98:101], v[170:173], v[186:189], v[98:101]
	v_mfma_f32_16x16x32_bf16 v[86:89], v[162:165], v[212:215], v[86:89]
	v_mfma_f32_16x16x32_bf16 v[82:85], v[170:173], v[212:215], v[82:85]
	v_mfma_f32_16x16x32_bf16 v[70:73], v[162:165], v[220:223], v[70:73]
	v_mfma_f32_16x16x32_bf16 v[66:69], v[170:173], v[220:223], v[66:69]
	v_mfma_f32_16x16x32_bf16 v[118:121], v[166:169], v[182:185], v[118:121]
	v_mfma_f32_16x16x32_bf16 v[114:117], v[174:177], v[182:185], v[114:117]
	v_mfma_f32_16x16x32_bf16 v[102:105], v[166:169], v[208:211], v[102:105]
	v_mfma_f32_16x16x32_bf16 v[98:101], v[174:177], v[208:211], v[98:101]
	v_mfma_f32_16x16x32_bf16 v[86:89], v[166:169], v[216:219], v[86:89]
	v_mfma_f32_16x16x32_bf16 v[82:85], v[174:177], v[216:219], v[82:85]
	v_mfma_f32_16x16x32_bf16 v[70:73], v[166:169], v[224:227], v[70:73]
	v_mfma_f32_16x16x32_bf16 v[66:69], v[174:177], v[224:227], v[66:69]
	s_barrier
	s_add_i32 s75, s75, s7
	v_lshl_add_u64 v[144:145], s[84:85], 0, v[0:1]
	s_mov_b32 m0, s75
	ds_read_b128 v[178:181], v149 offset:16384
	ds_read_b128 v[182:185], v149 offset:17408
	ds_read_b128 v[186:189], v149 offset:18432
	ds_read_b128 v[208:211], v149 offset:19456
	ds_read_b128 v[212:215], v149 offset:20480
	ds_read_b128 v[216:219], v149 offset:21504
	ds_read_b128 v[220:223], v149 offset:22528
	ds_read_b128 v[224:227], v149 offset:23552
	global_load_lds_dwordx4 v[144:145], off
	v_lshl_add_u64 v[190:191], s[84:85], 0, v[130:131]
	s_add_i32 m0, s75, 0x2000
	s_add_i32 s74, s74, s7
	global_load_lds_dwordx4 v[190:191], off
	v_lshl_add_u64 v[228:229], v[144:145], 0, s[22:23]
	s_mov_b32 m0, s74
	v_lshl_add_u64 v[230:231], s[46:47], 0, v[132:133]
	global_load_lds_dwordx4 v[228:229], off
	v_lshl_add_u64 v[228:229], v[190:191], 0, s[22:23]
	s_add_i32 m0, s74, 0x2000
	s_nop 0
	global_load_lds_dwordx4 v[228:229], off
	v_lshl_add_u64 v[228:229], s[46:47], 0, v[134:135]
	s_mov_b32 m0, s11
	s_nop 0
	global_load_lds_dwordx4 v[228:229], off
	s_mov_b32 m0, s12
	s_nop 0
	global_load_lds_dwordx4 v[230:231], off
	s_waitcnt vmcnt(8)
	s_waitcnt lgkmcnt(0)
	s_barrier
; #define PG8_STAGE(bufoff, gbase, voff) do { _Pragma("unroll") for (int _i = 0; _i < 2; ++_i) \
;         __builtin_amdgcn_global_load_lds((const unsigned*)((const char*)(gbase) + (voff)[_i]), (LAS unsigned*)(lds + (bufoff) + ldsw + _i * 8192), 16, 0, 0); } while (0)
; #define PG8_LDA(dst, b, h) do { _Pragma("unroll") for (int m = 0; m < 4; ++m) _Pragma("unroll") for (int k = 0; k < 2; ++k) dst[m][k] = *(const LAS bf16x8*)(lds + PG8_SA(b, h) + aoff + m * 2048 + k * 1024); } while (0)
; #define PG8_LDB(dst, b, h) do { _Pragma("unroll") for (int n = 0; n < 2; ++n) _Pragma("unroll") for (int k = 0; k < 2; ++k) dst[n][k] = *(const LAS bf16x8*)(lds + PG8_SB(b, h) + boff + n * 2048 + k * 1024); } while (0)
; #define PG8_MMA(ai, bj, At, Bt) do { __builtin_amdgcn_s_setprio(1); _Pragma("unroll") for (int m = 0; m < 4; ++m) _Pragma("unroll") for (int n = 0; n < 2; ++n) _Pragma("unroll") for (int k = 0; k < 2; ++k) \
;         acc[ai][bj][m][n] = __builtin_amdgcn_mfma_f32_16x16x32_bf16(Bt[n][k], At[m][k], acc[ai][bj][m][n], 0, 0, 0); __builtin_amdgcn_s_setprio(0); } while (0)
; #define PG8_WAIT_V(n) asm volatile("s_waitcnt vmcnt(" #n ")" ::: "memory")
; #define PG8_WAIT_L(n) asm volatile("s_waitcnt lgkmcnt(" #n ")" ::: "memory")
; #define PG8_BAR __builtin_amdgcn_s_barrier()
; #define PG8_SCHED __builtin_amdgcn_sched_barrier(0)
; template <class Epi, class Sched>
; __device__ __forceinline__ void gemm_phase(LAS unsigned char* lds, const Gemm g, const Sched& S, const Epi& E) {
;     ...
;             PG8_WAIT_V(8); PG8_WAIT_L(0); PG8_BAR; PG8_MMA(1, 0, At, B0); PG8_MMA(1, 1, At, B1); PG8_BAR; PG8_SCHED;
;             PG8_LDB(B0, 1, 0); PG8_LDB(B1, 1, 1); PG8_SCHED; PG8_LDA(At, 1, 0); PG8_STAGE(PG8_SA(0, 1), a2 + hsA, voffA);
;             PG8_WAIT_V(8); PG8_WAIT_L(0); PG8_BAR; PG8_MMA(0, 0, At, B0); PG8_MMA(0, 1, At, B1); PG8_BAR; PG8_SCHED;
	s_waitcnt lgkmcnt(0)
	v_mfma_f32_16x16x32_bf16 v[62:65], v[140:143], v[178:181], v[62:65]
	v_mfma_f32_16x16x32_bf16 v[58:61], v[154:157], v[178:181], v[58:61]
	v_mfma_f32_16x16x32_bf16 v[46:49], v[140:143], v[186:189], v[46:49]
	v_mfma_f32_16x16x32_bf16 v[42:45], v[154:157], v[186:189], v[42:45]
	v_mfma_f32_16x16x32_bf16 v[30:33], v[140:143], v[212:215], v[30:33]
	v_mfma_f32_16x16x32_bf16 v[26:29], v[154:157], v[212:215], v[26:29]
	v_mfma_f32_16x16x32_bf16 v[14:17], v[140:143], v[220:223], v[14:17]
	v_mfma_f32_16x16x32_bf16 v[10:13], v[154:157], v[220:223], v[10:13]
	v_mfma_f32_16x16x32_bf16 v[62:65], v[150:153], v[182:185], v[62:65]
	v_mfma_f32_16x16x32_bf16 v[58:61], v[158:161], v[182:185], v[58:61]
	v_mfma_f32_16x16x32_bf16 v[46:49], v[150:153], v[208:211], v[46:49]
	v_mfma_f32_16x16x32_bf16 v[42:45], v[158:161], v[208:211], v[42:45]
	v_mfma_f32_16x16x32_bf16 v[30:33], v[150:153], v[216:219], v[30:33]
	v_mfma_f32_16x16x32_bf16 v[26:29], v[158:161], v[216:219], v[26:29]
	v_mfma_f32_16x16x32_bf16 v[14:17], v[150:153], v[224:227], v[14:17]
	v_mfma_f32_16x16x32_bf16 v[10:13], v[158:161], v[224:227], v[10:13]
	v_mfma_f32_16x16x32_bf16 v[54:57], v[162:165], v[178:181], v[54:57]
	v_mfma_f32_16x16x32_bf16 v[50:53], v[170:173], v[178:181], v[50:53]
	v_mfma_f32_16x16x32_bf16 v[38:41], v[162:165], v[186:189], v[38:41]
	v_mfma_f32_16x16x32_bf16 v[34:37], v[170:173], v[186:189], v[34:37]
	v_mfma_f32_16x16x32_bf16 v[22:25], v[162:165], v[212:215], v[22:25]
	v_mfma_f32_16x16x32_bf16 v[18:21], v[170:173], v[212:215], v[18:21]
	v_mfma_f32_16x16x32_bf16 v[6:9], v[162:165], v[220:223], v[6:9]
	v_mfma_f32_16x16x32_bf16 v[2:5], v[170:173], v[220:223], v[2:5]
	v_mfma_f32_16x16x32_bf16 v[54:57], v[166:169], v[182:185], v[54:57]
	v_mfma_f32_16x16x32_bf16 v[50:53], v[174:177], v[182:185], v[50:53]
	v_mfma_f32_16x16x32_bf16 v[38:41], v[166:169], v[208:211], v[38:41]
	v_mfma_f32_16x16x32_bf16 v[34:37], v[174:177], v[208:211], v[34:37]
	v_mfma_f32_16x16x32_bf16 v[22:25], v[166:169], v[216:219], v[22:25]
	v_mfma_f32_16x16x32_bf16 v[18:21], v[174:177], v[216:219], v[18:21]
	v_mfma_f32_16x16x32_bf16 v[6:9], v[166:169], v[224:227], v[6:9]
	v_mfma_f32_16x16x32_bf16 v[2:5], v[174:177], v[224:227], v[2:5]
	s_barrier
	s_add_i32 s74, 0, 0x18000
	s_add_i32 s75, 0, 0x1c000
	v_add_u32_e32 v158, s74, v148
	v_add_u32_e32 v174, s75, v148
	ds_read_b128 v[140:143], v158
	ds_read_b128 v[150:153], v158 offset:1024
	ds_read_b128 v[154:157], v158 offset:2048
	ds_read_b128 v[158:161], v158 offset:3072
	ds_read_b128 v[162:165], v174
	ds_read_b128 v[166:169], v174 offset:1024
	ds_read_b128 v[170:173], v174 offset:2048
	ds_read_b128 v[174:177], v174 offset:3072
	s_add_u32 s46, s46, 0x40000
	s_addc_u32 s47, s47, 0
	s_mov_b32 m0, s16
	v_lshl_add_u64 v[232:233], s[46:47], 0, v[134:135]
	ds_read_b128 v[178:181], v149 offset:32768
	ds_read_b128 v[182:185], v149 offset:33792
	ds_read_b128 v[186:189], v149 offset:34816
	ds_read_b128 v[208:211], v149 offset:35840
	ds_read_b128 v[212:215], v149 offset:36864
	ds_read_b128 v[216:219], v149 offset:37888
	ds_read_b128 v[220:223], v149 offset:38912
	ds_read_b128 v[224:227], v149 offset:39936
	global_load_lds_dwordx4 v[232:233], off
	v_lshl_add_u64 v[232:233], s[46:47], 0, v[132:133]
	s_mov_b32 m0, s24
	s_nop 0
	global_load_lds_dwordx4 v[232:233], off
	s_waitcnt vmcnt(8)
	s_waitcnt lgkmcnt(0)
	s_barrier
	s_waitcnt lgkmcnt(0)
	v_mfma_f32_16x16x32_bf16 v[122:125], v[140:143], v[178:181], v[122:125]
	v_mfma_f32_16x16x32_bf16 v[126:129], v[154:157], v[178:181], v[126:129]
	v_mfma_f32_16x16x32_bf16 v[110:113], v[140:143], v[186:189], v[110:113]
	v_mfma_f32_16x16x32_bf16 v[106:109], v[154:157], v[186:189], v[106:109]
	v_mfma_f32_16x16x32_bf16 v[94:97], v[140:143], v[212:215], v[94:97]
	v_mfma_f32_16x16x32_bf16 v[90:93], v[154:157], v[212:215], v[90:93]
	v_mfma_f32_16x16x32_bf16 v[78:81], v[140:143], v[220:223], v[78:81]
	v_mfma_f32_16x16x32_bf16 v[74:77], v[154:157], v[220:223], v[74:77]
	v_mfma_f32_16x16x32_bf16 v[122:125], v[150:153], v[182:185], v[122:125]
	v_mfma_f32_16x16x32_bf16 v[126:129], v[158:161], v[182:185], v[126:129]
	v_mfma_f32_16x16x32_bf16 v[110:113], v[150:153], v[208:211], v[110:113]
	v_mfma_f32_16x16x32_bf16 v[106:109], v[158:161], v[208:211], v[106:109]
	v_mfma_f32_16x16x32_bf16 v[94:97], v[150:153], v[216:219], v[94:97]
	v_mfma_f32_16x16x32_bf16 v[90:93], v[158:161], v[216:219], v[90:93]
	v_mfma_f32_16x16x32_bf16 v[78:81], v[150:153], v[224:227], v[78:81]
	v_mfma_f32_16x16x32_bf16 v[74:77], v[158:161], v[224:227], v[74:77]
	v_mfma_f32_16x16x32_bf16 v[118:121], v[162:165], v[178:181], v[118:121]
	v_mfma_f32_16x16x32_bf16 v[114:117], v[170:173], v[178:181], v[114:117]
	v_mfma_f32_16x16x32_bf16 v[102:105], v[162:165], v[186:189], v[102:105]
	v_mfma_f32_16x16x32_bf16 v[98:101], v[170:173], v[186:189], v[98:101]
	v_mfma_f32_16x16x32_bf16 v[86:89], v[162:165], v[212:215], v[86:89]
	v_mfma_f32_16x16x32_bf16 v[82:85], v[170:173], v[212:215], v[82:85]
	v_mfma_f32_16x16x32_bf16 v[70:73], v[162:165], v[220:223], v[70:73]
	v_mfma_f32_16x16x32_bf16 v[66:69], v[170:173], v[220:223], v[66:69]
	v_mfma_f32_16x16x32_bf16 v[118:121], v[166:169], v[182:185], v[118:121]
	v_mfma_f32_16x16x32_bf16 v[114:117], v[174:177], v[182:185], v[114:117]
	v_mfma_f32_16x16x32_bf16 v[102:105], v[166:169], v[208:211], v[102:105]
	v_mfma_f32_16x16x32_bf16 v[98:101], v[174:177], v[208:211], v[98:101]
	v_mfma_f32_16x16x32_bf16 v[86:89], v[166:169], v[216:219], v[86:89]
	v_mfma_f32_16x16x32_bf16 v[82:85], v[174:177], v[216:219], v[82:85]
	v_mfma_f32_16x16x32_bf16 v[70:73], v[166:169], v[224:227], v[70:73]
	v_mfma_f32_16x16x32_bf16 v[66:69], v[174:177], v[224:227], v[66:69]
	s_barrier
; #define PG8_STAGE(bufoff, gbase, voff) do { _Pragma("unroll") for (int _i = 0; _i < 2; ++_i) \
;         __builtin_amdgcn_global_load_lds((const unsigned*)((const char*)(gbase) + (voff)[_i]), (LAS unsigned*)(lds + (bufoff) + ldsw + _i * 8192), 16, 0, 0); } while (0)
; #define PG8_LDA(dst, b, h) do { _Pragma("unroll") for (int m = 0; m < 4; ++m) _Pragma("unroll") for (int k = 0; k < 2; ++k) dst[m][k] = *(const LAS bf16x8*)(lds + PG8_SA(b, h) + aoff + m * 2048 + k * 1024); } while (0)
; #define PG8_MMA(ai, bj, At, Bt) do { __builtin_amdgcn_s_setprio(1); _Pragma("unroll") for (int m = 0; m < 4; ++m) _Pragma("unroll") for (int n = 0; n < 2; ++n) _Pragma("unroll") for (int k = 0; k < 2; ++k) \
;         acc[ai][bj][m][n] = __builtin_amdgcn_mfma_f32_16x16x32_bf16(Bt[n][k], At[m][k], acc[ai][bj][m][n], 0, 0, 0); __builtin_amdgcn_s_setprio(0); } while (0)
; #define PG8_WAIT_V(n) asm volatile("s_waitcnt vmcnt(" #n ")" ::: "memory")
; #define PG8_WAIT_L(n) asm volatile("s_waitcnt lgkmcnt(" #n ")" ::: "memory")
; #define PG8_BAR __builtin_amdgcn_s_barrier()
; #define PG8_SCHED __builtin_amdgcn_sched_barrier(0)
; template <class Epi, class Sched>
; __device__ __forceinline__ void gemm_phase(LAS unsigned char* lds, const Gemm g, const Sched& S, const Epi& E) {
;     ...
;             PG8_LDA(At, 1, 1); PG8_STAGE(PG8_SB(1, 0), b3, voffB); PG8_STAGE(PG8_SB(1, 1), b3 + hsB, voffB); PG8_STAGE(PG8_SA(1, 0), a3, voffA);
;             PG8_WAIT_V(8); PG8_WAIT_L(0); PG8_BAR; PG8_MMA(1, 0, At, B0); PG8_MMA(1, 1, At, B1); PG8_BAR; PG8_SCHED;
;         }
	s_add_i32 s46, s74, s7
	v_lshl_add_u64 v[232:233], v[144:145], 0, s[18:19]
	s_mov_b32 m0, s46
	ds_read_b128 v[178:181], v149 offset:49152
	ds_read_b128 v[182:185], v149 offset:50176
	ds_read_b128 v[186:189], v149 offset:51200
	ds_read_b128 v[208:211], v149 offset:52224
	ds_read_b128 v[212:215], v149 offset:53248
	ds_read_b128 v[216:219], v149 offset:54272
	ds_read_b128 v[220:223], v149 offset:55296
	ds_read_b128 v[224:227], v149 offset:56320
	global_load_lds_dwordx4 v[232:233], off
	v_lshl_add_u64 v[232:233], v[190:191], 0, s[18:19]
	s_add_i32 m0, s46, 0x2000
	s_add_i32 s46, s75, s7
	global_load_lds_dwordx4 v[232:233], off
	v_lshl_add_u64 v[144:145], v[144:145], 0, vcc
	s_mov_b32 m0, s46
	s_nop 0
	global_load_lds_dwordx4 v[144:145], off
	v_lshl_add_u64 v[144:145], v[190:191], 0, vcc
	s_add_i32 m0, s46, 0x2000
	s_nop 0
	global_load_lds_dwordx4 v[144:145], off
	v_lshl_add_u64 v[144:145], v[228:229], 0, s[18:19]
	s_mov_b32 m0, s49
	s_nop 0
	global_load_lds_dwordx4 v[144:145], off
	v_lshl_add_u64 v[144:145], v[230:231], 0, s[18:19]
	s_mov_b32 m0, s50
	s_nop 0
	global_load_lds_dwordx4 v[144:145], off
	s_waitcnt vmcnt(8)
	s_waitcnt lgkmcnt(0)
	s_barrier
	s_waitcnt lgkmcnt(0)
	v_mfma_f32_16x16x32_bf16 v[62:65], v[140:143], v[178:181], v[62:65]
	v_mfma_f32_16x16x32_bf16 v[58:61], v[154:157], v[178:181], v[58:61]
	v_mfma_f32_16x16x32_bf16 v[46:49], v[140:143], v[186:189], v[46:49]
	v_mfma_f32_16x16x32_bf16 v[42:45], v[154:157], v[186:189], v[42:45]
	v_mfma_f32_16x16x32_bf16 v[30:33], v[140:143], v[212:215], v[30:33]
	v_mfma_f32_16x16x32_bf16 v[26:29], v[154:157], v[212:215], v[26:29]
	v_mfma_f32_16x16x32_bf16 v[14:17], v[140:143], v[220:223], v[14:17]
	v_mfma_f32_16x16x32_bf16 v[10:13], v[154:157], v[220:223], v[10:13]
	v_mfma_f32_16x16x32_bf16 v[62:65], v[150:153], v[182:185], v[62:65]
	v_mfma_f32_16x16x32_bf16 v[58:61], v[158:161], v[182:185], v[58:61]
	v_mfma_f32_16x16x32_bf16 v[46:49], v[150:153], v[208:211], v[46:49]
	v_mfma_f32_16x16x32_bf16 v[42:45], v[158:161], v[208:211], v[42:45]
	v_mfma_f32_16x16x32_bf16 v[30:33], v[150:153], v[216:219], v[30:33]
	v_mfma_f32_16x16x32_bf16 v[26:29], v[158:161], v[216:219], v[26:29]
	v_mfma_f32_16x16x32_bf16 v[14:17], v[150:153], v[224:227], v[14:17]
	v_mfma_f32_16x16x32_bf16 v[10:13], v[158:161], v[224:227], v[10:13]
	v_mfma_f32_16x16x32_bf16 v[54:57], v[162:165], v[178:181], v[54:57]
	v_mfma_f32_16x16x32_bf16 v[50:53], v[170:173], v[178:181], v[50:53]
	v_mfma_f32_16x16x32_bf16 v[38:41], v[162:165], v[186:189], v[38:41]
	v_mfma_f32_16x16x32_bf16 v[34:37], v[170:173], v[186:189], v[34:37]
	v_mfma_f32_16x16x32_bf16 v[22:25], v[162:165], v[212:215], v[22:25]
	v_mfma_f32_16x16x32_bf16 v[18:21], v[170:173], v[212:215], v[18:21]
	v_mfma_f32_16x16x32_bf16 v[6:9], v[162:165], v[220:223], v[6:9]
	v_mfma_f32_16x16x32_bf16 v[2:5], v[170:173], v[220:223], v[2:5]
	v_mfma_f32_16x16x32_bf16 v[54:57], v[166:169], v[182:185], v[54:57]
	v_mfma_f32_16x16x32_bf16 v[50:53], v[174:177], v[182:185], v[50:53]
	v_mfma_f32_16x16x32_bf16 v[38:41], v[166:169], v[208:211], v[38:41]
	v_mfma_f32_16x16x32_bf16 v[34:37], v[174:177], v[208:211], v[34:37]
	v_mfma_f32_16x16x32_bf16 v[22:25], v[166:169], v[216:219], v[22:25]
	v_mfma_f32_16x16x32_bf16 v[18:21], v[174:177], v[216:219], v[18:21]
	v_mfma_f32_16x16x32_bf16 v[6:9], v[166:169], v[224:227], v[6:9]
	v_mfma_f32_16x16x32_bf16 v[2:5], v[174:177], v[224:227], v[2:5]
	s_barrier
	s_add_u32 s44, s44, 0x100
	s_addc_u32 s45, s45, 0
	s_add_u32 s80, s80, 0x100
	s_addc_u32 s82, s82, 0
	s_cmp_ge_i32 s83, s26
	s_mov_b32 s46, s83
	s_cbranch_scc0 .LBB0_536
	v_readlane_b32 s82, v254, 45
	v_readlane_b32 s83, v254, 46

; #define PG8_STAGE(bufoff, gbase, voff) do { _Pragma("unroll") for (int _i = 0; _i < 2; ++_i) \
;         __builtin_amdgcn_global_load_lds((const unsigned*)((const char*)(gbase) + (voff)[_i]), (LAS unsigned*)(lds + (bufoff) + ldsw + _i * 8192), 16, 0, 0); } while (0)
; #define PG8_LDA(dst, b, h) do { _Pragma("unroll") for (int m = 0; m < 4; ++m) _Pragma("unroll") for (int k = 0; k < 2; ++k) dst[m][k] = *(const LAS bf16x8*)(lds + PG8_SA(b, h) + aoff + m * 2048 + k * 1024); } while (0)
; #define PG8_LDB(dst, b, h) do { _Pragma("unroll") for (int n = 0; n < 2; ++n) _Pragma("unroll") for (int k = 0; k < 2; ++k) dst[n][k] = *(const LAS bf16x8*)(lds + PG8_SB(b, h) + boff + n * 2048 + k * 1024); } while (0)
; #define PG8_WAIT_V(n) asm volatile("s_waitcnt vmcnt(" #n ")" ::: "memory")
; #define PG8_WAIT_L(n) asm volatile("s_waitcnt lgkmcnt(" #n ")" ::: "memory")
; #define PG8_BAR __builtin_amdgcn_s_barrier()
; #define PG8_SCHED __builtin_amdgcn_sched_barrier(0)
; template <class Epi, class Sched>
; __device__ __forceinline__ void gemm_phase(LAS unsigned char* lds, const Gemm g, const Sched& S, const Epi& E) {
;     ...
;             const bool last = (t == nt - 2);
;             const char* a1 = cA + (size_t)(t + 1) * kstep;
;             const char* a2 = last ? nA : cA + (size_t)(t + 2) * kstep; const char* b2 = last ? nB : cB + (size_t)(t + 2) * kstep;
;             const char* a3 = a2 + kstep; const char* b3 = b2 + kstep;
;             if constexpr (Epi::MIDK) { if (t == (nt >> 1)) { int fr_ = fr, fq_ = fq; asm volatile("" : "+v"(fr_), "+v"(fq_)); E.mid(acc, cur, wr, wc, fr_, fq_); } }
;             PG8_LDB(B0, 0, 0); PG8_LDB(B1, 0, 1); PG8_SCHED; PG8_LDA(At, 0, 0); PG8_STAGE(PG8_SA(1, 1), a1 + hsA, voffA);
;             PG8_WAIT_V(8); PG8_WAIT_L(0); PG8_BAR; PG8_MMA(0, 0, At, B0); PG8_MMA(0, 1, At, B1); PG8_BAR; PG8_SCHED;
;             PG8_LDA(At, 0, 1); PG8_STAGE(PG8_SB(0, 0), b2, voffB); PG8_STAGE(PG8_SB(0, 1), b2 + hsB, voffB); PG8_STAGE(PG8_SA(0, 0), a2, voffA);
;             PG8_WAIT_V(8); PG8_WAIT_L(0); PG8_BAR; PG8_MMA(1, 0, At, B0); PG8_MMA(1, 1, At, B1); PG8_BAR; PG8_SCHED;
;         const int chalf = L & 1, k2g = (L >> 1) % ng, b = (L >> 1) / ng; u.offA = 0; u.offB = (((size_t)b * 512 + chalf * 256) * (256 * (size_t)N1) + (size_t)k2g * 512) * 2; return true; }
.LBB0_637:
	s_add_i32 s0, s46, 2
	s_add_u32 s44, s42, 0x100
	s_addc_u32 s45, s43, 0
	s_add_u32 s1, s77, s42
	s_addc_u32 s22, s78, s43
	s_cmp_eq_u32 s56, s46
	s_cselect_b32 s48, 0, s44
	s_cselect_b32 s23, 0, s45
	s_cselect_b32 s46, s76, s1
	s_cselect_b32 s47, s73, s22
	s_add_u32 s48, s58, s48
	s_addc_u32 s49, s59, s23
	s_add_i32 s1, 0, 0x10000
	v_add_u32_e32 v0, s1, v152
	s_add_i32 s22, 0, 0x14000
	ds_read_b128 v[142:145], v0
	ds_read_b128 v[146:149], v0 offset:1024
	ds_read_b128 v[154:157], v0 offset:2048
	ds_read_b128 v[158:161], v0 offset:3072
	v_add_u32_e32 v0, s22, v152
	ds_read_b128 v[162:165], v0
	ds_read_b128 v[166:169], v0 offset:1024
	ds_read_b128 v[170:173], v0 offset:2048
	ds_read_b128 v[174:177], v0 offset:3072
	v_lshl_add_u64 v[190:191], v[138:139], 0, s[42:43]
	s_add_i32 m0, s11, 0xc000
	ds_read_b128 v[178:181], v153
	ds_read_b128 v[182:185], v153 offset:1024
	ds_read_b128 v[186:189], v153 offset:2048
	ds_read_b128 v[208:211], v153 offset:3072
	ds_read_b128 v[212:215], v153 offset:4096
	ds_read_b128 v[216:219], v153 offset:5120
	ds_read_b128 v[220:223], v153 offset:6144
	ds_read_b128 v[224:227], v153 offset:7168
	global_load_lds_dwordx4 v[190:191], off
	v_lshl_add_u64 v[190:191], v[140:141], 0, s[42:43]
	s_add_i32 m0, s11, 0xe000
	s_nop 0
	global_load_lds_dwordx4 v[190:191], off
	s_waitcnt vmcnt(8)
	s_waitcnt lgkmcnt(0)
	s_barrier
	s_waitcnt lgkmcnt(0)
	v_mfma_f32_16x16x32_bf16 v[126:129], v[142:145], v[178:181], v[126:129]
	v_mfma_f32_16x16x32_bf16 v[118:121], v[154:157], v[178:181], v[118:121]
	v_mfma_f32_16x16x32_bf16 v[94:97], v[142:145], v[186:189], v[94:97]
	v_mfma_f32_16x16x32_bf16 v[86:89], v[154:157], v[186:189], v[86:89]
	v_mfma_f32_16x16x32_bf16 v[62:65], v[142:145], v[212:215], v[62:65]
	v_mfma_f32_16x16x32_bf16 v[54:57], v[154:157], v[212:215], v[54:57]
	v_mfma_f32_16x16x32_bf16 v[30:33], v[142:145], v[220:223], v[30:33]
	v_mfma_f32_16x16x32_bf16 v[22:25], v[154:157], v[220:223], v[22:25]
	v_mfma_f32_16x16x32_bf16 v[126:129], v[146:149], v[182:185], v[126:129]
	v_mfma_f32_16x16x32_bf16 v[118:121], v[158:161], v[182:185], v[118:121]
	v_mfma_f32_16x16x32_bf16 v[94:97], v[146:149], v[208:211], v[94:97]
	v_mfma_f32_16x16x32_bf16 v[86:89], v[158:161], v[208:211], v[86:89]
	v_mfma_f32_16x16x32_bf16 v[62:65], v[146:149], v[216:219], v[62:65]
	v_mfma_f32_16x16x32_bf16 v[54:57], v[158:161], v[216:219], v[54:57]
	v_mfma_f32_16x16x32_bf16 v[30:33], v[146:149], v[224:227], v[30:33]
	v_mfma_f32_16x16x32_bf16 v[22:25], v[158:161], v[224:227], v[22:25]
	v_mfma_f32_16x16x32_bf16 v[110:113], v[162:165], v[178:181], v[110:113]
	v_mfma_f32_16x16x32_bf16 v[102:105], v[170:173], v[178:181], v[102:105]
	v_mfma_f32_16x16x32_bf16 v[78:81], v[162:165], v[186:189], v[78:81]
	v_mfma_f32_16x16x32_bf16 v[70:73], v[170:173], v[186:189], v[70:73]
	v_mfma_f32_16x16x32_bf16 v[46:49], v[162:165], v[212:215], v[46:49]
	v_mfma_f32_16x16x32_bf16 v[38:41], v[170:173], v[212:215], v[38:41]
	v_mfma_f32_16x16x32_bf16 v[14:17], v[162:165], v[220:223], v[14:17]
	v_mfma_f32_16x16x32_bf16 v[6:9], v[170:173], v[220:223], v[6:9]
	v_mfma_f32_16x16x32_bf16 v[110:113], v[166:169], v[182:185], v[110:113]
	v_mfma_f32_16x16x32_bf16 v[102:105], v[174:177], v[182:185], v[102:105]
	v_mfma_f32_16x16x32_bf16 v[78:81], v[166:169], v[208:211], v[78:81]
	v_mfma_f32_16x16x32_bf16 v[70:73], v[174:177], v[208:211], v[70:73]
	v_mfma_f32_16x16x32_bf16 v[46:49], v[166:169], v[216:219], v[46:49]
	v_mfma_f32_16x16x32_bf16 v[38:41], v[174:177], v[216:219], v[38:41]
	v_mfma_f32_16x16x32_bf16 v[14:17], v[166:169], v[224:227], v[14:17]
	v_mfma_f32_16x16x32_bf16 v[6:9], v[174:177], v[224:227], v[6:9]
	s_barrier
	s_add_i32 s1, s1, s7
	v_lshl_add_u64 v[190:191], s[46:47], 0, v[134:135]
	s_mov_b32 m0, s1
	ds_read_b128 v[178:181], v153 offset:16384
	ds_read_b128 v[182:185], v153 offset:17408
	ds_read_b128 v[186:189], v153 offset:18432
	ds_read_b128 v[208:211], v153 offset:19456
	ds_read_b128 v[212:215], v153 offset:20480
	ds_read_b128 v[216:219], v153 offset:21504
	ds_read_b128 v[220:223], v153 offset:22528
	ds_read_b128 v[224:227], v153 offset:23552
	global_load_lds_dwordx4 v[190:191], off
	s_add_i32 m0, s1, 0x2000
	s_add_u32 s42, s46, 0x10000
	v_lshl_add_u64 v[228:229], s[46:47], 0, v[130:131]
	s_addc_u32 s43, s47, 0
	s_add_i32 s1, s22, s7
	global_load_lds_dwordx4 v[228:229], off
	v_lshl_add_u64 v[230:231], s[42:43], 0, v[134:135]
	s_mov_b32 m0, s1
	v_lshl_add_u64 v[232:233], s[48:49], 0, v[132:133]
	global_load_lds_dwordx4 v[230:231], off
	v_lshl_add_u64 v[230:231], s[42:43], 0, v[130:131]
	s_add_i32 m0, s1, 0x2000
	s_nop 0
	global_load_lds_dwordx4 v[230:231], off
	v_lshl_add_u64 v[230:231], s[48:49], 0, v[136:137]
	s_mov_b32 m0, s11
	s_nop 0
	global_load_lds_dwordx4 v[230:231], off
	s_mov_b32 m0, s12
	s_nop 0
	global_load_lds_dwordx4 v[232:233], off
	s_waitcnt vmcnt(8)
	s_waitcnt lgkmcnt(0)
	s_barrier
; #define PG8_STAGE(bufoff, gbase, voff) do { _Pragma("unroll") for (int _i = 0; _i < 2; ++_i) \
;         __builtin_amdgcn_global_load_lds((const unsigned*)((const char*)(gbase) + (voff)[_i]), (LAS unsigned*)(lds + (bufoff) + ldsw + _i * 8192), 16, 0, 0); } while (0)
; #define PG8_LDA(dst, b, h) do { _Pragma("unroll") for (int m = 0; m < 4; ++m) _Pragma("unroll") for (int k = 0; k < 2; ++k) dst[m][k] = *(const LAS bf16x8*)(lds + PG8_SA(b, h) + aoff + m * 2048 + k * 1024); } while (0)
; #define PG8_LDB(dst, b, h) do { _Pragma("unroll") for (int n = 0; n < 2; ++n) _Pragma("unroll") for (int k = 0; k < 2; ++k) dst[n][k] = *(const LAS bf16x8*)(lds + PG8_SB(b, h) + boff + n * 2048 + k * 1024); } while (0)
; #define PG8_MMA(ai, bj, At, Bt) do { __builtin_amdgcn_s_setprio(1); _Pragma("unroll") for (int m = 0; m < 4; ++m) _Pragma("unroll") for (int n = 0; n < 2; ++n) _Pragma("unroll") for (int k = 0; k < 2; ++k) \
;         acc[ai][bj][m][n] = __builtin_amdgcn_mfma_f32_16x16x32_bf16(Bt[n][k], At[m][k], acc[ai][bj][m][n], 0, 0, 0); __builtin_amdgcn_s_setprio(0); } while (0)
; #define PG8_WAIT_V(n) asm volatile("s_waitcnt vmcnt(" #n ")" ::: "memory")
; #define PG8_WAIT_L(n) asm volatile("s_waitcnt lgkmcnt(" #n ")" ::: "memory")
; #define PG8_BAR __builtin_amdgcn_s_barrier()
; #define PG8_SCHED __builtin_amdgcn_sched_barrier(0)
; template <class Epi, class Sched>
; __device__ __forceinline__ void gemm_phase(LAS unsigned char* lds, const Gemm g, const Sched& S, const Epi& E) {
;     ...
;             PG8_WAIT_V(8); PG8_WAIT_L(0); PG8_BAR; PG8_MMA(1, 0, At, B0); PG8_MMA(1, 1, At, B1); PG8_BAR; PG8_SCHED;
;             PG8_LDB(B0, 1, 0); PG8_LDB(B1, 1, 1); PG8_SCHED; PG8_LDA(At, 1, 0); PG8_STAGE(PG8_SA(0, 1), a2 + hsA, voffA);
;             PG8_WAIT_V(8); PG8_WAIT_L(0); PG8_BAR; PG8_MMA(0, 0, At, B0); PG8_MMA(0, 1, At, B1); PG8_BAR; PG8_SCHED;
	s_waitcnt lgkmcnt(0)
	v_mfma_f32_16x16x32_bf16 v[122:125], v[142:145], v[178:181], v[122:125]
	v_mfma_f32_16x16x32_bf16 v[114:117], v[154:157], v[178:181], v[114:117]
	v_mfma_f32_16x16x32_bf16 v[90:93], v[142:145], v[186:189], v[90:93]
	v_mfma_f32_16x16x32_bf16 v[82:85], v[154:157], v[186:189], v[82:85]
	v_mfma_f32_16x16x32_bf16 v[58:61], v[142:145], v[212:215], v[58:61]
	v_mfma_f32_16x16x32_bf16 v[50:53], v[154:157], v[212:215], v[50:53]
	v_mfma_f32_16x16x32_bf16 v[26:29], v[142:145], v[220:223], v[26:29]
	v_mfma_f32_16x16x32_bf16 v[18:21], v[154:157], v[220:223], v[18:21]
	v_mfma_f32_16x16x32_bf16 v[122:125], v[146:149], v[182:185], v[122:125]
	v_mfma_f32_16x16x32_bf16 v[114:117], v[158:161], v[182:185], v[114:117]
	v_mfma_f32_16x16x32_bf16 v[90:93], v[146:149], v[208:211], v[90:93]
	v_mfma_f32_16x16x32_bf16 v[82:85], v[158:161], v[208:211], v[82:85]
	v_mfma_f32_16x16x32_bf16 v[58:61], v[146:149], v[216:219], v[58:61]
	v_mfma_f32_16x16x32_bf16 v[50:53], v[158:161], v[216:219], v[50:53]
	v_mfma_f32_16x16x32_bf16 v[26:29], v[146:149], v[224:227], v[26:29]
	v_mfma_f32_16x16x32_bf16 v[18:21], v[158:161], v[224:227], v[18:21]
	v_mfma_f32_16x16x32_bf16 v[106:109], v[162:165], v[178:181], v[106:109]
	v_mfma_f32_16x16x32_bf16 v[98:101], v[170:173], v[178:181], v[98:101]
	v_mfma_f32_16x16x32_bf16 v[74:77], v[162:165], v[186:189], v[74:77]
	v_mfma_f32_16x16x32_bf16 v[66:69], v[170:173], v[186:189], v[66:69]
	v_mfma_f32_16x16x32_bf16 v[42:45], v[162:165], v[212:215], v[42:45]
	v_mfma_f32_16x16x32_bf16 v[34:37], v[170:173], v[212:215], v[34:37]
	v_mfma_f32_16x16x32_bf16 v[10:13], v[162:165], v[220:223], v[10:13]
	v_mfma_f32_16x16x32_bf16 v[2:5], v[170:173], v[220:223], v[2:5]
	v_mfma_f32_16x16x32_bf16 v[106:109], v[166:169], v[182:185], v[106:109]
	v_mfma_f32_16x16x32_bf16 v[98:101], v[174:177], v[182:185], v[98:101]
	v_mfma_f32_16x16x32_bf16 v[74:77], v[166:169], v[208:211], v[74:77]
	v_mfma_f32_16x16x32_bf16 v[66:69], v[174:177], v[208:211], v[66:69]
	v_mfma_f32_16x16x32_bf16 v[42:45], v[166:169], v[216:219], v[42:45]
	v_mfma_f32_16x16x32_bf16 v[34:37], v[174:177], v[216:219], v[34:37]
	v_mfma_f32_16x16x32_bf16 v[10:13], v[166:169], v[224:227], v[10:13]
	v_mfma_f32_16x16x32_bf16 v[2:5], v[174:177], v[224:227], v[2:5]
	s_barrier
	s_add_i32 s1, 0, 0x18000
	v_add_u32_e32 v0, s1, v152
	s_add_i32 s22, 0, 0x1c000
	ds_read_b128 v[142:145], v0
	ds_read_b128 v[146:149], v0 offset:1024
	ds_read_b128 v[154:157], v0 offset:2048
	ds_read_b128 v[158:161], v0 offset:3072
	v_add_u32_e32 v0, s22, v152
	ds_read_b128 v[162:165], v0
	ds_read_b128 v[166:169], v0 offset:1024
	ds_read_b128 v[170:173], v0 offset:2048
	ds_read_b128 v[174:177], v0 offset:3072
	s_add_u32 s42, s48, 0x10000
	s_addc_u32 s43, s49, 0
	s_mov_b32 m0, s16
	v_lshl_add_u64 v[238:239], s[42:43], 0, v[136:137]
	ds_read_b128 v[178:181], v153 offset:32768
	ds_read_b128 v[182:185], v153 offset:33792
	ds_read_b128 v[186:189], v153 offset:34816
	ds_read_b128 v[208:211], v153 offset:35840
	ds_read_b128 v[212:215], v153 offset:36864
	ds_read_b128 v[216:219], v153 offset:37888
	ds_read_b128 v[220:223], v153 offset:38912
	ds_read_b128 v[224:227], v153 offset:39936
	global_load_lds_dwordx4 v[238:239], off
	v_lshl_add_u64 v[238:239], s[42:43], 0, v[132:133]
	s_mov_b32 m0, s24
	s_nop 0
	global_load_lds_dwordx4 v[238:239], off
	s_waitcnt vmcnt(8)
	s_waitcnt lgkmcnt(0)
	s_barrier
	s_waitcnt lgkmcnt(0)
	v_mfma_f32_16x16x32_bf16 v[126:129], v[142:145], v[178:181], v[126:129]
	v_mfma_f32_16x16x32_bf16 v[118:121], v[154:157], v[178:181], v[118:121]
	v_mfma_f32_16x16x32_bf16 v[94:97], v[142:145], v[186:189], v[94:97]
	v_mfma_f32_16x16x32_bf16 v[86:89], v[154:157], v[186:189], v[86:89]
	v_mfma_f32_16x16x32_bf16 v[62:65], v[142:145], v[212:215], v[62:65]
	v_mfma_f32_16x16x32_bf16 v[54:57], v[154:157], v[212:215], v[54:57]
	v_mfma_f32_16x16x32_bf16 v[30:33], v[142:145], v[220:223], v[30:33]
	v_mfma_f32_16x16x32_bf16 v[22:25], v[154:157], v[220:223], v[22:25]
	v_mfma_f32_16x16x32_bf16 v[126:129], v[146:149], v[182:185], v[126:129]
	v_mfma_f32_16x16x32_bf16 v[118:121], v[158:161], v[182:185], v[118:121]
	v_mfma_f32_16x16x32_bf16 v[94:97], v[146:149], v[208:211], v[94:97]
	v_mfma_f32_16x16x32_bf16 v[86:89], v[158:161], v[208:211], v[86:89]
	v_mfma_f32_16x16x32_bf16 v[62:65], v[146:149], v[216:219], v[62:65]
	v_mfma_f32_16x16x32_bf16 v[54:57], v[158:161], v[216:219], v[54:57]
	v_mfma_f32_16x16x32_bf16 v[30:33], v[146:149], v[224:227], v[30:33]
	v_mfma_f32_16x16x32_bf16 v[22:25], v[158:161], v[224:227], v[22:25]
	v_mfma_f32_16x16x32_bf16 v[110:113], v[162:165], v[178:181], v[110:113]
	v_mfma_f32_16x16x32_bf16 v[102:105], v[170:173], v[178:181], v[102:105]
	v_mfma_f32_16x16x32_bf16 v[78:81], v[162:165], v[186:189], v[78:81]
	v_mfma_f32_16x16x32_bf16 v[70:73], v[170:173], v[186:189], v[70:73]
	v_mfma_f32_16x16x32_bf16 v[46:49], v[162:165], v[212:215], v[46:49]
	v_mfma_f32_16x16x32_bf16 v[38:41], v[170:173], v[212:215], v[38:41]
	v_mfma_f32_16x16x32_bf16 v[14:17], v[162:165], v[220:223], v[14:17]
	v_mfma_f32_16x16x32_bf16 v[6:9], v[170:173], v[220:223], v[6:9]
	v_mfma_f32_16x16x32_bf16 v[110:113], v[166:169], v[182:185], v[110:113]
	v_mfma_f32_16x16x32_bf16 v[102:105], v[174:177], v[182:185], v[102:105]
	v_mfma_f32_16x16x32_bf16 v[78:81], v[166:169], v[208:211], v[78:81]
	v_mfma_f32_16x16x32_bf16 v[70:73], v[174:177], v[208:211], v[70:73]
	v_mfma_f32_16x16x32_bf16 v[46:49], v[166:169], v[216:219], v[46:49]
	v_mfma_f32_16x16x32_bf16 v[38:41], v[174:177], v[216:219], v[38:41]
	v_mfma_f32_16x16x32_bf16 v[14:17], v[166:169], v[224:227], v[14:17]
	v_mfma_f32_16x16x32_bf16 v[6:9], v[174:177], v[224:227], v[6:9]
	s_barrier
; #define PG8_STAGE(bufoff, gbase, voff) do { _Pragma("unroll") for (int _i = 0; _i < 2; ++_i) \
;         __builtin_amdgcn_global_load_lds((const unsigned*)((const char*)(gbase) + (voff)[_i]), (LAS unsigned*)(lds + (bufoff) + ldsw + _i * 8192), 16, 0, 0); } while (0)
; #define PG8_LDA(dst, b, h) do { _Pragma("unroll") for (int m = 0; m < 4; ++m) _Pragma("unroll") for (int k = 0; k < 2; ++k) dst[m][k] = *(const LAS bf16x8*)(lds + PG8_SA(b, h) + aoff + m * 2048 + k * 1024); } while (0)
; #define PG8_MMA(ai, bj, At, Bt) do { __builtin_amdgcn_s_setprio(1); _Pragma("unroll") for (int m = 0; m < 4; ++m) _Pragma("unroll") for (int n = 0; n < 2; ++n) _Pragma("unroll") for (int k = 0; k < 2; ++k) \
;         acc[ai][bj][m][n] = __builtin_amdgcn_mfma_f32_16x16x32_bf16(Bt[n][k], At[m][k], acc[ai][bj][m][n], 0, 0, 0); __builtin_amdgcn_s_setprio(0); } while (0)
; #define PG8_WAIT_V(n) asm volatile("s_waitcnt vmcnt(" #n ")" ::: "memory")
; #define PG8_WAIT_L(n) asm volatile("s_waitcnt lgkmcnt(" #n ")" ::: "memory")
; #define PG8_BAR __builtin_amdgcn_s_barrier()
; #define PG8_SCHED __builtin_amdgcn_sched_barrier(0)
; template <class Epi, class Sched>
; __device__ __forceinline__ void gemm_phase(LAS unsigned char* lds, const Gemm g, const Sched& S, const Epi& E) {
;     ...
;             PG8_LDA(At, 1, 1); PG8_STAGE(PG8_SB(1, 0), b3, voffB); PG8_STAGE(PG8_SB(1, 1), b3 + hsB, voffB); PG8_STAGE(PG8_SA(1, 0), a3, voffA);
;             PG8_WAIT_V(8); PG8_WAIT_L(0); PG8_BAR; PG8_MMA(1, 0, At, B0); PG8_MMA(1, 1, At, B1); PG8_BAR; PG8_SCHED;
;         }
	s_add_i32 s1, s1, s7
	v_lshl_add_u64 v[190:191], v[190:191], 0, s[18:19]
	s_mov_b32 m0, s1
	ds_read_b128 v[178:181], v153 offset:49152
	ds_read_b128 v[182:185], v153 offset:50176
	ds_read_b128 v[186:189], v153 offset:51200
	ds_read_b128 v[208:211], v153 offset:52224
	ds_read_b128 v[212:215], v153 offset:53248
	ds_read_b128 v[216:219], v153 offset:54272
	ds_read_b128 v[220:223], v153 offset:55296
	ds_read_b128 v[224:227], v153 offset:56320
	global_load_lds_dwordx4 v[190:191], off
	s_add_i32 m0, s1, 0x2000
	s_add_u32 s42, s46, 0x10080
	v_lshl_add_u64 v[190:191], v[228:229], 0, s[18:19]
	s_addc_u32 s43, s47, 0
	s_add_i32 s1, s22, s7
	global_load_lds_dwordx4 v[190:191], off
	v_lshl_add_u64 v[190:191], s[42:43], 0, v[134:135]
	s_mov_b32 m0, s1
	s_nop 0
	global_load_lds_dwordx4 v[190:191], off
	v_lshl_add_u64 v[190:191], s[42:43], 0, v[130:131]
	s_add_i32 m0, s1, 0x2000
	s_nop 0
	global_load_lds_dwordx4 v[190:191], off
	v_lshl_add_u64 v[190:191], v[230:231], 0, s[18:19]
	s_mov_b32 m0, s51
	s_nop 0
	global_load_lds_dwordx4 v[190:191], off
	v_lshl_add_u64 v[190:191], v[232:233], 0, s[18:19]
	s_mov_b32 m0, s52
	s_nop 0
	global_load_lds_dwordx4 v[190:191], off
	s_waitcnt vmcnt(8)
	s_waitcnt lgkmcnt(0)
	s_barrier
	s_waitcnt lgkmcnt(0)
	v_mfma_f32_16x16x32_bf16 v[122:125], v[142:145], v[178:181], v[122:125]
	v_mfma_f32_16x16x32_bf16 v[114:117], v[154:157], v[178:181], v[114:117]
	v_mfma_f32_16x16x32_bf16 v[90:93], v[142:145], v[186:189], v[90:93]
	v_mfma_f32_16x16x32_bf16 v[82:85], v[154:157], v[186:189], v[82:85]
	v_mfma_f32_16x16x32_bf16 v[58:61], v[142:145], v[212:215], v[58:61]
	v_mfma_f32_16x16x32_bf16 v[50:53], v[154:157], v[212:215], v[50:53]
	v_mfma_f32_16x16x32_bf16 v[26:29], v[142:145], v[220:223], v[26:29]
	v_mfma_f32_16x16x32_bf16 v[18:21], v[154:157], v[220:223], v[18:21]
	v_mfma_f32_16x16x32_bf16 v[122:125], v[146:149], v[182:185], v[122:125]
	v_mfma_f32_16x16x32_bf16 v[114:117], v[158:161], v[182:185], v[114:117]
	v_mfma_f32_16x16x32_bf16 v[90:93], v[146:149], v[208:211], v[90:93]
	v_mfma_f32_16x16x32_bf16 v[82:85], v[158:161], v[208:211], v[82:85]
	v_mfma_f32_16x16x32_bf16 v[58:61], v[146:149], v[216:219], v[58:61]
	v_mfma_f32_16x16x32_bf16 v[50:53], v[158:161], v[216:219], v[50:53]
	v_mfma_f32_16x16x32_bf16 v[26:29], v[146:149], v[224:227], v[26:29]
	v_mfma_f32_16x16x32_bf16 v[18:21], v[158:161], v[224:227], v[18:21]
	v_mfma_f32_16x16x32_bf16 v[106:109], v[162:165], v[178:181], v[106:109]
	v_mfma_f32_16x16x32_bf16 v[98:101], v[170:173], v[178:181], v[98:101]
	v_mfma_f32_16x16x32_bf16 v[74:77], v[162:165], v[186:189], v[74:77]
	v_mfma_f32_16x16x32_bf16 v[66:69], v[170:173], v[186:189], v[66:69]
	v_mfma_f32_16x16x32_bf16 v[42:45], v[162:165], v[212:215], v[42:45]
	v_mfma_f32_16x16x32_bf16 v[34:37], v[170:173], v[212:215], v[34:37]
	v_mfma_f32_16x16x32_bf16 v[10:13], v[162:165], v[220:223], v[10:13]
	v_mfma_f32_16x16x32_bf16 v[2:5], v[170:173], v[220:223], v[2:5]
	v_mfma_f32_16x16x32_bf16 v[106:109], v[166:169], v[182:185], v[106:109]
	v_mfma_f32_16x16x32_bf16 v[98:101], v[174:177], v[182:185], v[98:101]
	v_mfma_f32_16x16x32_bf16 v[74:77], v[166:169], v[208:211], v[74:77]
	v_mfma_f32_16x16x32_bf16 v[66:69], v[174:177], v[208:211], v[66:69]
	v_mfma_f32_16x16x32_bf16 v[42:45], v[166:169], v[216:219], v[42:45]
	v_mfma_f32_16x16x32_bf16 v[34:37], v[174:177], v[216:219], v[34:37]
	v_mfma_f32_16x16x32_bf16 v[10:13], v[166:169], v[224:227], v[10:13]
	v_mfma_f32_16x16x32_bf16 v[2:5], v[174:177], v[224:227], v[2:5]
	s_barrier
	s_cmp_ge_i32 s0, s26
	s_mov_b64 s[42:43], s[44:45]
	s_mov_b32 s46, s0
	s_cbranch_scc0 .LBB0_637

; #define PG8_STAGE(bufoff, gbase, voff) do { _Pragma("unroll") for (int _i = 0; _i < 2; ++_i) \
;         __builtin_amdgcn_global_load_lds((const unsigned*)((const char*)(gbase) + (voff)[_i]), (LAS unsigned*)(lds + (bufoff) + ldsw + _i * 8192), 16, 0, 0); } while (0)
; #define PG8_LDA(dst, b, h) do { _Pragma("unroll") for (int m = 0; m < 4; ++m) _Pragma("unroll") for (int k = 0; k < 2; ++k) dst[m][k] = *(const LAS bf16x8*)(lds + PG8_SA(b, h) + aoff + m * 2048 + k * 1024); } while (0)
; #define PG8_LDB(dst, b, h) do { _Pragma("unroll") for (int n = 0; n < 2; ++n) _Pragma("unroll") for (int k = 0; k < 2; ++k) dst[n][k] = *(const LAS bf16x8*)(lds + PG8_SB(b, h) + boff + n * 2048 + k * 1024); } while (0)
; #define PG8_MMA(ai, bj, At, Bt) do { __builtin_amdgcn_s_setprio(1); _Pragma("unroll") for (int m = 0; m < 4; ++m) _Pragma("unroll") for (int n = 0; n < 2; ++n) _Pragma("unroll") for (int k = 0; k < 2; ++k) \
;         acc[ai][bj][m][n] = __builtin_amdgcn_mfma_f32_16x16x32_bf16(Bt[n][k], At[m][k], acc[ai][bj][m][n], 0, 0, 0); __builtin_amdgcn_s_setprio(0); } while (0)
; #define PG8_WAIT_V(n) asm volatile("s_waitcnt vmcnt(" #n ")" ::: "memory")
; #define PG8_WAIT_L(n) asm volatile("s_waitcnt lgkmcnt(" #n ")" ::: "memory")
; template <class Epi, class Sched>
; __device__ __forceinline__ void gemm_phase(LAS unsigned char* lds, const Gemm g, const Sched& S, const Epi& E) {
;     ...
;             const bool last = (t == nt - 2);
;             const char* a1 = cA + (size_t)(t + 1) * kstep;
;             const char* a2 = last ? nA : cA + (size_t)(t + 2) * kstep; const char* b2 = last ? nB : cB + (size_t)(t + 2) * kstep;
;             const char* a3 = a2 + kstep; const char* b3 = b2 + kstep;
;             if constexpr (Epi::MIDK) { if (t == (nt >> 1)) { int fr_ = fr, fq_ = fq; asm volatile("" : "+v"(fr_), "+v"(fq_)); E.mid(acc, cur, wr, wc, fr_, fq_); } }
;             PG8_LDB(B0, 0, 0); PG8_LDB(B1, 0, 1); PG8_SCHED; PG8_LDA(At, 0, 0); PG8_STAGE(PG8_SA(1, 1), a1 + hsA, voffA);
;             PG8_WAIT_V(8); PG8_WAIT_L(0); PG8_BAR; PG8_MMA(0, 0, At, B0); PG8_MMA(0, 1, At, B1); PG8_BAR; PG8_SCHED;
;             PG8_LDA(At, 0, 1); PG8_STAGE(PG8_SB(0, 0), b2, voffB); PG8_STAGE(PG8_SB(0, 1), b2 + hsB, voffB); PG8_STAGE(PG8_SA(0, 0), a2, voffA);
;             PG8_WAIT_V(8); PG8_WAIT_L(0); PG8_BAR; PG8_MMA(1, 0, At, B0); PG8_MMA(1, 1, At, B1); PG8_BAR; PG8_SCHED;
.LBB0_660:
	s_add_i32 s0, s40, 2
	s_add_u32 s1, s36, 0xfffc0080
	s_addc_u32 s41, s37, -1
	s_add_i32 s74, 0, 0x10000
	s_cmp_eq_u32 s11, s40
	s_cselect_b32 s85, s47, s41
	s_cselect_b32 s84, s49, s1
	s_cselect_b32 s41, s83, s96
	s_cselect_b32 s40, vcc_lo, vcc_hi
	s_add_i32 s1, 0, 0x14000
	v_add_u32_e32 v154, s74, v165
	v_add_u32_e32 v162, s1, v165
	ds_read_b128 v[142:145], v154
	ds_read_b128 v[146:149], v154 offset:1024
	ds_read_b128 v[150:153], v154 offset:2048
	ds_read_b128 v[154:157], v154 offset:3072
	ds_read_b128 v[158:161], v162
	ds_read_b128 v[168:171], v162 offset:1024
	ds_read_b128 v[172:175], v162 offset:2048
	ds_read_b128 v[176:179], v162 offset:3072
	v_lshl_add_u64 v[228:229], s[36:37], 0, v[138:139]
	s_add_i32 m0, s16, 0xc000
	ds_read_b128 v[180:183], v166
	ds_read_b128 v[184:187], v166 offset:1024
	ds_read_b128 v[188:191], v166 offset:2048
	ds_read_b128 v[208:211], v166 offset:3072
	ds_read_b128 v[212:215], v166 offset:4096
	ds_read_b128 v[216:219], v166 offset:5120
	ds_read_b128 v[220:223], v166 offset:6144
	ds_read_b128 v[224:227], v166 offset:7168
	global_load_lds_dwordx4 v[228:229], off
	v_lshl_add_u64 v[228:229], s[36:37], 0, v[140:141]
	s_add_i32 m0, s16, 0xe000
	s_nop 0
	global_load_lds_dwordx4 v[228:229], off
	s_waitcnt vmcnt(8)
	s_waitcnt lgkmcnt(0)
	s_barrier
	s_waitcnt lgkmcnt(0)
	v_mfma_f32_16x16x32_bf16 v[122:125], v[142:145], v[180:183], v[122:125]
	v_mfma_f32_16x16x32_bf16 v[114:117], v[150:153], v[180:183], v[114:117]
	v_mfma_f32_16x16x32_bf16 v[110:113], v[142:145], v[188:191], v[110:113]
	v_mfma_f32_16x16x32_bf16 v[98:101], v[150:153], v[188:191], v[98:101]
	v_mfma_f32_16x16x32_bf16 v[94:97], v[142:145], v[212:215], v[94:97]
	v_mfma_f32_16x16x32_bf16 v[82:85], v[150:153], v[212:215], v[82:85]
	v_mfma_f32_16x16x32_bf16 v[78:81], v[142:145], v[220:223], v[78:81]
	v_mfma_f32_16x16x32_bf16 v[66:69], v[150:153], v[220:223], v[66:69]
	v_mfma_f32_16x16x32_bf16 v[122:125], v[146:149], v[184:187], v[122:125]
	v_mfma_f32_16x16x32_bf16 v[114:117], v[154:157], v[184:187], v[114:117]
	v_mfma_f32_16x16x32_bf16 v[110:113], v[146:149], v[208:211], v[110:113]
	v_mfma_f32_16x16x32_bf16 v[98:101], v[154:157], v[208:211], v[98:101]
	v_mfma_f32_16x16x32_bf16 v[94:97], v[146:149], v[216:219], v[94:97]
	v_mfma_f32_16x16x32_bf16 v[82:85], v[154:157], v[216:219], v[82:85]
	v_mfma_f32_16x16x32_bf16 v[78:81], v[146:149], v[224:227], v[78:81]
	v_mfma_f32_16x16x32_bf16 v[66:69], v[154:157], v[224:227], v[66:69]
	v_mfma_f32_16x16x32_bf16 v[126:129], v[158:161], v[180:183], v[126:129]
	v_mfma_f32_16x16x32_bf16 v[118:121], v[172:175], v[180:183], v[118:121]
	v_mfma_f32_16x16x32_bf16 v[106:109], v[158:161], v[188:191], v[106:109]
	v_mfma_f32_16x16x32_bf16 v[102:105], v[172:175], v[188:191], v[102:105]
	v_mfma_f32_16x16x32_bf16 v[90:93], v[158:161], v[212:215], v[90:93]
	v_mfma_f32_16x16x32_bf16 v[86:89], v[172:175], v[212:215], v[86:89]
	v_mfma_f32_16x16x32_bf16 v[74:77], v[158:161], v[220:223], v[74:77]
	v_mfma_f32_16x16x32_bf16 v[70:73], v[172:175], v[220:223], v[70:73]
	v_mfma_f32_16x16x32_bf16 v[126:129], v[168:171], v[184:187], v[126:129]
	v_mfma_f32_16x16x32_bf16 v[118:121], v[176:179], v[184:187], v[118:121]
	v_mfma_f32_16x16x32_bf16 v[106:109], v[168:171], v[208:211], v[106:109]
	v_mfma_f32_16x16x32_bf16 v[102:105], v[176:179], v[208:211], v[102:105]
	v_mfma_f32_16x16x32_bf16 v[90:93], v[168:171], v[216:219], v[90:93]
	v_mfma_f32_16x16x32_bf16 v[86:89], v[176:179], v[216:219], v[86:89]
	v_mfma_f32_16x16x32_bf16 v[74:77], v[168:171], v[224:227], v[74:77]
	v_mfma_f32_16x16x32_bf16 v[70:73], v[176:179], v[224:227], v[70:73]
	s_barrier
	s_add_i32 s74, s74, s12
	v_lshl_add_u64 v[228:229], s[40:41], 0, v[0:1]
	s_mov_b32 m0, s74
	ds_read_b128 v[180:183], v166 offset:16384
	ds_read_b128 v[184:187], v166 offset:17408
	ds_read_b128 v[188:191], v166 offset:18432
	ds_read_b128 v[208:211], v166 offset:19456
	ds_read_b128 v[212:215], v166 offset:20480
	ds_read_b128 v[216:219], v166 offset:21504
	ds_read_b128 v[220:223], v166 offset:22528
	ds_read_b128 v[224:227], v166 offset:23552
	global_load_lds_dwordx4 v[228:229], off
	s_add_i32 m0, s74, 0x2000
	s_add_u32 s74, s40, 0x40000
	v_lshl_add_u64 v[230:231], s[40:41], 0, v[130:131]
	s_addc_u32 s75, s41, 0
	s_add_i32 s1, s1, s12
	global_load_lds_dwordx4 v[230:231], off
	v_lshl_add_u64 v[232:233], s[74:75], 0, v[0:1]
	s_mov_b32 m0, s1
	v_lshl_add_u64 v[238:239], s[84:85], 0, v[132:133]
	global_load_lds_dwordx4 v[232:233], off
	v_lshl_add_u64 v[232:233], s[74:75], 0, v[130:131]
	s_add_i32 m0, s1, 0x2000
	s_nop 0
	global_load_lds_dwordx4 v[232:233], off
	v_lshl_add_u64 v[232:233], s[84:85], 0, v[134:135]
	s_mov_b32 m0, s16
	s_nop 0
	global_load_lds_dwordx4 v[232:233], off
	s_mov_b32 m0, s52
	s_nop 0
	global_load_lds_dwordx4 v[238:239], off
	s_waitcnt vmcnt(8)
	s_waitcnt lgkmcnt(0)
	s_barrier
; #define PG8_STAGE(bufoff, gbase, voff) do { _Pragma("unroll") for (int _i = 0; _i < 2; ++_i) \
;         __builtin_amdgcn_global_load_lds((const unsigned*)((const char*)(gbase) + (voff)[_i]), (LAS unsigned*)(lds + (bufoff) + ldsw + _i * 8192), 16, 0, 0); } while (0)
; #define PG8_LDA(dst, b, h) do { _Pragma("unroll") for (int m = 0; m < 4; ++m) _Pragma("unroll") for (int k = 0; k < 2; ++k) dst[m][k] = *(const LAS bf16x8*)(lds + PG8_SA(b, h) + aoff + m * 2048 + k * 1024); } while (0)
; #define PG8_LDB(dst, b, h) do { _Pragma("unroll") for (int n = 0; n < 2; ++n) _Pragma("unroll") for (int k = 0; k < 2; ++k) dst[n][k] = *(const LAS bf16x8*)(lds + PG8_SB(b, h) + boff + n * 2048 + k * 1024); } while (0)
; #define PG8_MMA(ai, bj, At, Bt) do { __builtin_amdgcn_s_setprio(1); _Pragma("unroll") for (int m = 0; m < 4; ++m) _Pragma("unroll") for (int n = 0; n < 2; ++n) _Pragma("unroll") for (int k = 0; k < 2; ++k) \
;         acc[ai][bj][m][n] = __builtin_amdgcn_mfma_f32_16x16x32_bf16(Bt[n][k], At[m][k], acc[ai][bj][m][n], 0, 0, 0); __builtin_amdgcn_s_setprio(0); } while (0)
; #define PG8_WAIT_V(n) asm volatile("s_waitcnt vmcnt(" #n ")" ::: "memory")
; #define PG8_WAIT_L(n) asm volatile("s_waitcnt lgkmcnt(" #n ")" ::: "memory")
; #define PG8_BAR __builtin_amdgcn_s_barrier()
; #define PG8_SCHED __builtin_amdgcn_sched_barrier(0)
; template <class Epi, class Sched>
; __device__ __forceinline__ void gemm_phase(LAS unsigned char* lds, const Gemm g, const Sched& S, const Epi& E) {
;     ...
;             PG8_WAIT_V(8); PG8_WAIT_L(0); PG8_BAR; PG8_MMA(1, 0, At, B0); PG8_MMA(1, 1, At, B1); PG8_BAR; PG8_SCHED;
;             PG8_LDB(B0, 1, 0); PG8_LDB(B1, 1, 1); PG8_SCHED; PG8_LDA(At, 1, 0); PG8_STAGE(PG8_SA(0, 1), a2 + hsA, voffA);
;             PG8_WAIT_V(8); PG8_WAIT_L(0); PG8_BAR; PG8_MMA(0, 0, At, B0); PG8_MMA(0, 1, At, B1); PG8_BAR; PG8_SCHED;
	s_waitcnt lgkmcnt(0)
	v_mfma_f32_16x16x32_bf16 v[62:65], v[142:145], v[180:183], v[62:65]
	v_mfma_f32_16x16x32_bf16 v[50:53], v[150:153], v[180:183], v[50:53]
	v_mfma_f32_16x16x32_bf16 v[46:49], v[142:145], v[188:191], v[46:49]
	v_mfma_f32_16x16x32_bf16 v[34:37], v[150:153], v[188:191], v[34:37]
	v_mfma_f32_16x16x32_bf16 v[30:33], v[142:145], v[212:215], v[30:33]
	v_mfma_f32_16x16x32_bf16 v[18:21], v[150:153], v[212:215], v[18:21]
	v_mfma_f32_16x16x32_bf16 v[10:13], v[142:145], v[220:223], v[10:13]
	v_mfma_f32_16x16x32_bf16 v[2:5], v[150:153], v[220:223], v[2:5]
	v_mfma_f32_16x16x32_bf16 v[62:65], v[146:149], v[184:187], v[62:65]
	v_mfma_f32_16x16x32_bf16 v[50:53], v[154:157], v[184:187], v[50:53]
	v_mfma_f32_16x16x32_bf16 v[46:49], v[146:149], v[208:211], v[46:49]
	v_mfma_f32_16x16x32_bf16 v[34:37], v[154:157], v[208:211], v[34:37]
	v_mfma_f32_16x16x32_bf16 v[30:33], v[146:149], v[216:219], v[30:33]
	v_mfma_f32_16x16x32_bf16 v[18:21], v[154:157], v[216:219], v[18:21]
	v_mfma_f32_16x16x32_bf16 v[10:13], v[146:149], v[224:227], v[10:13]
	v_mfma_f32_16x16x32_bf16 v[2:5], v[154:157], v[224:227], v[2:5]
	v_mfma_f32_16x16x32_bf16 v[58:61], v[158:161], v[180:183], v[58:61]
	v_mfma_f32_16x16x32_bf16 v[54:57], v[172:175], v[180:183], v[54:57]
	v_mfma_f32_16x16x32_bf16 v[42:45], v[158:161], v[188:191], v[42:45]
	v_mfma_f32_16x16x32_bf16 v[38:41], v[172:175], v[188:191], v[38:41]
	v_mfma_f32_16x16x32_bf16 v[26:29], v[158:161], v[212:215], v[26:29]
	v_mfma_f32_16x16x32_bf16 v[22:25], v[172:175], v[212:215], v[22:25]
	v_mfma_f32_16x16x32_bf16 v[14:17], v[158:161], v[220:223], v[14:17]
	v_mfma_f32_16x16x32_bf16 v[6:9], v[172:175], v[220:223], v[6:9]
	v_mfma_f32_16x16x32_bf16 v[58:61], v[168:171], v[184:187], v[58:61]
	v_mfma_f32_16x16x32_bf16 v[54:57], v[176:179], v[184:187], v[54:57]
	v_mfma_f32_16x16x32_bf16 v[42:45], v[168:171], v[208:211], v[42:45]
	v_mfma_f32_16x16x32_bf16 v[38:41], v[176:179], v[208:211], v[38:41]
	v_mfma_f32_16x16x32_bf16 v[26:29], v[168:171], v[216:219], v[26:29]
	v_mfma_f32_16x16x32_bf16 v[22:25], v[176:179], v[216:219], v[22:25]
	v_mfma_f32_16x16x32_bf16 v[14:17], v[168:171], v[224:227], v[14:17]
	v_mfma_f32_16x16x32_bf16 v[6:9], v[176:179], v[224:227], v[6:9]
	s_barrier
	s_add_i32 s1, 0, 0x18000
	s_add_i32 s22, 0, 0x1c000
	v_add_u32_e32 v154, s1, v165
	v_add_u32_e32 v162, s22, v165
	ds_read_b128 v[142:145], v154
	ds_read_b128 v[146:149], v154 offset:1024
	ds_read_b128 v[150:153], v154 offset:2048
	ds_read_b128 v[154:157], v154 offset:3072
	ds_read_b128 v[158:161], v162
	ds_read_b128 v[168:171], v162 offset:1024
	ds_read_b128 v[172:175], v162 offset:2048
	ds_read_b128 v[176:179], v162 offset:3072
	s_add_u32 s74, s84, 0x40000
	s_addc_u32 s75, s85, 0
	s_mov_b32 m0, s64
	v_lshl_add_u64 v[240:241], s[74:75], 0, v[134:135]
	ds_read_b128 v[180:183], v166 offset:32768
	ds_read_b128 v[184:187], v166 offset:33792
	ds_read_b128 v[188:191], v166 offset:34816
	ds_read_b128 v[208:211], v166 offset:35840
	ds_read_b128 v[212:215], v166 offset:36864
	ds_read_b128 v[216:219], v166 offset:37888
	ds_read_b128 v[220:223], v166 offset:38912
	ds_read_b128 v[224:227], v166 offset:39936
	global_load_lds_dwordx4 v[240:241], off
	v_lshl_add_u64 v[240:241], s[74:75], 0, v[132:133]
	s_mov_b32 m0, s78
	s_nop 0
	global_load_lds_dwordx4 v[240:241], off
	s_waitcnt vmcnt(8)
	s_waitcnt lgkmcnt(0)
	s_barrier
	s_waitcnt lgkmcnt(0)
	v_mfma_f32_16x16x32_bf16 v[122:125], v[142:145], v[180:183], v[122:125]
	v_mfma_f32_16x16x32_bf16 v[114:117], v[150:153], v[180:183], v[114:117]
	v_mfma_f32_16x16x32_bf16 v[110:113], v[142:145], v[188:191], v[110:113]
	v_mfma_f32_16x16x32_bf16 v[98:101], v[150:153], v[188:191], v[98:101]
	v_mfma_f32_16x16x32_bf16 v[94:97], v[142:145], v[212:215], v[94:97]
	v_mfma_f32_16x16x32_bf16 v[82:85], v[150:153], v[212:215], v[82:85]
	v_mfma_f32_16x16x32_bf16 v[78:81], v[142:145], v[220:223], v[78:81]
	v_mfma_f32_16x16x32_bf16 v[66:69], v[150:153], v[220:223], v[66:69]
	v_mfma_f32_16x16x32_bf16 v[122:125], v[146:149], v[184:187], v[122:125]
	v_mfma_f32_16x16x32_bf16 v[114:117], v[154:157], v[184:187], v[114:117]
	v_mfma_f32_16x16x32_bf16 v[110:113], v[146:149], v[208:211], v[110:113]
	v_mfma_f32_16x16x32_bf16 v[98:101], v[154:157], v[208:211], v[98:101]
	v_mfma_f32_16x16x32_bf16 v[94:97], v[146:149], v[216:219], v[94:97]
	v_mfma_f32_16x16x32_bf16 v[82:85], v[154:157], v[216:219], v[82:85]
	v_mfma_f32_16x16x32_bf16 v[78:81], v[146:149], v[224:227], v[78:81]
	v_mfma_f32_16x16x32_bf16 v[66:69], v[154:157], v[224:227], v[66:69]
	v_mfma_f32_16x16x32_bf16 v[126:129], v[158:161], v[180:183], v[126:129]
	v_mfma_f32_16x16x32_bf16 v[118:121], v[172:175], v[180:183], v[118:121]
	v_mfma_f32_16x16x32_bf16 v[106:109], v[158:161], v[188:191], v[106:109]
	v_mfma_f32_16x16x32_bf16 v[102:105], v[172:175], v[188:191], v[102:105]
	v_mfma_f32_16x16x32_bf16 v[90:93], v[158:161], v[212:215], v[90:93]
	v_mfma_f32_16x16x32_bf16 v[86:89], v[172:175], v[212:215], v[86:89]
	v_mfma_f32_16x16x32_bf16 v[74:77], v[158:161], v[220:223], v[74:77]
	v_mfma_f32_16x16x32_bf16 v[70:73], v[172:175], v[220:223], v[70:73]
	v_mfma_f32_16x16x32_bf16 v[126:129], v[168:171], v[184:187], v[126:129]
	v_mfma_f32_16x16x32_bf16 v[118:121], v[176:179], v[184:187], v[118:121]
	v_mfma_f32_16x16x32_bf16 v[106:109], v[168:171], v[208:211], v[106:109]
	v_mfma_f32_16x16x32_bf16 v[102:105], v[176:179], v[208:211], v[102:105]
	v_mfma_f32_16x16x32_bf16 v[90:93], v[168:171], v[216:219], v[90:93]
	v_mfma_f32_16x16x32_bf16 v[86:89], v[176:179], v[216:219], v[86:89]
	v_mfma_f32_16x16x32_bf16 v[74:77], v[168:171], v[224:227], v[74:77]
	v_mfma_f32_16x16x32_bf16 v[70:73], v[176:179], v[224:227], v[70:73]
	s_barrier
; #define PG8_STAGE(bufoff, gbase, voff) do { _Pragma("unroll") for (int _i = 0; _i < 2; ++_i) \
;         __builtin_amdgcn_global_load_lds((const unsigned*)((const char*)(gbase) + (voff)[_i]), (LAS unsigned*)(lds + (bufoff) + ldsw + _i * 8192), 16, 0, 0); } while (0)
; #define PG8_LDA(dst, b, h) do { _Pragma("unroll") for (int m = 0; m < 4; ++m) _Pragma("unroll") for (int k = 0; k < 2; ++k) dst[m][k] = *(const LAS bf16x8*)(lds + PG8_SA(b, h) + aoff + m * 2048 + k * 1024); } while (0)
; #define PG8_MMA(ai, bj, At, Bt) do { __builtin_amdgcn_s_setprio(1); _Pragma("unroll") for (int m = 0; m < 4; ++m) _Pragma("unroll") for (int n = 0; n < 2; ++n) _Pragma("unroll") for (int k = 0; k < 2; ++k) \
;         acc[ai][bj][m][n] = __builtin_amdgcn_mfma_f32_16x16x32_bf16(Bt[n][k], At[m][k], acc[ai][bj][m][n], 0, 0, 0); __builtin_amdgcn_s_setprio(0); } while (0)
; #define PG8_WAIT_V(n) asm volatile("s_waitcnt vmcnt(" #n ")" ::: "memory")
; #define PG8_WAIT_L(n) asm volatile("s_waitcnt lgkmcnt(" #n ")" ::: "memory")
; #define PG8_BAR __builtin_amdgcn_s_barrier()
; #define PG8_SCHED __builtin_amdgcn_sched_barrier(0)
; template <class Epi, class Sched>
; __device__ __forceinline__ void gemm_phase(LAS unsigned char* lds, const Gemm g, const Sched& S, const Epi& E) {
;     ...
;             PG8_LDA(At, 1, 1); PG8_STAGE(PG8_SB(1, 0), b3, voffB); PG8_STAGE(PG8_SB(1, 1), b3 + hsB, voffB); PG8_STAGE(PG8_SA(1, 0), a3, voffA);
;             PG8_WAIT_V(8); PG8_WAIT_L(0); PG8_BAR; PG8_MMA(1, 0, At, B0); PG8_MMA(1, 1, At, B1); PG8_BAR; PG8_SCHED;
;         }
	s_add_i32 s1, s1, s12
	v_lshl_add_u64 v[228:229], v[228:229], 0, s[18:19]
	s_mov_b32 m0, s1
	ds_read_b128 v[180:183], v166 offset:49152
	ds_read_b128 v[184:187], v166 offset:50176
	ds_read_b128 v[188:191], v166 offset:51200
	ds_read_b128 v[208:211], v166 offset:52224
	ds_read_b128 v[212:215], v166 offset:53248
	ds_read_b128 v[216:219], v166 offset:54272
	ds_read_b128 v[220:223], v166 offset:55296
	ds_read_b128 v[224:227], v166 offset:56320
	global_load_lds_dwordx4 v[228:229], off
	s_add_i32 m0, s1, 0x2000
	s_add_u32 s40, s40, 0x40080
	v_lshl_add_u64 v[228:229], v[230:231], 0, s[18:19]
	s_addc_u32 s41, s41, 0
	s_add_i32 s1, s22, s12
	global_load_lds_dwordx4 v[228:229], off
	v_lshl_add_u64 v[228:229], s[40:41], 0, v[0:1]
	s_mov_b32 m0, s1
	s_nop 0
	global_load_lds_dwordx4 v[228:229], off
	v_lshl_add_u64 v[228:229], s[40:41], 0, v[130:131]
	s_add_i32 m0, s1, 0x2000
	s_nop 0
	global_load_lds_dwordx4 v[228:229], off
	v_lshl_add_u64 v[228:229], v[232:233], 0, s[18:19]
	s_mov_b32 m0, s26
	s_nop 0
	global_load_lds_dwordx4 v[228:229], off
	v_lshl_add_u64 v[228:229], v[238:239], 0, s[18:19]
	s_mov_b32 m0, s57
	s_nop 0
	global_load_lds_dwordx4 v[228:229], off
	s_waitcnt vmcnt(8)
	s_waitcnt lgkmcnt(0)
	s_barrier
	s_waitcnt lgkmcnt(0)
	v_mfma_f32_16x16x32_bf16 v[62:65], v[142:145], v[180:183], v[62:65]
	v_mfma_f32_16x16x32_bf16 v[50:53], v[150:153], v[180:183], v[50:53]
	v_mfma_f32_16x16x32_bf16 v[46:49], v[142:145], v[188:191], v[46:49]
	v_mfma_f32_16x16x32_bf16 v[34:37], v[150:153], v[188:191], v[34:37]
	v_mfma_f32_16x16x32_bf16 v[30:33], v[142:145], v[212:215], v[30:33]
	v_mfma_f32_16x16x32_bf16 v[18:21], v[150:153], v[212:215], v[18:21]
	v_mfma_f32_16x16x32_bf16 v[10:13], v[142:145], v[220:223], v[10:13]
	v_mfma_f32_16x16x32_bf16 v[2:5], v[150:153], v[220:223], v[2:5]
	v_mfma_f32_16x16x32_bf16 v[62:65], v[146:149], v[184:187], v[62:65]
	v_mfma_f32_16x16x32_bf16 v[50:53], v[154:157], v[184:187], v[50:53]
	v_mfma_f32_16x16x32_bf16 v[46:49], v[146:149], v[208:211], v[46:49]
	v_mfma_f32_16x16x32_bf16 v[34:37], v[154:157], v[208:211], v[34:37]
	v_mfma_f32_16x16x32_bf16 v[30:33], v[146:149], v[216:219], v[30:33]
	v_mfma_f32_16x16x32_bf16 v[18:21], v[154:157], v[216:219], v[18:21]
	v_mfma_f32_16x16x32_bf16 v[10:13], v[146:149], v[224:227], v[10:13]
	v_mfma_f32_16x16x32_bf16 v[2:5], v[154:157], v[224:227], v[2:5]
	v_mfma_f32_16x16x32_bf16 v[58:61], v[158:161], v[180:183], v[58:61]
	v_mfma_f32_16x16x32_bf16 v[54:57], v[172:175], v[180:183], v[54:57]
	v_mfma_f32_16x16x32_bf16 v[42:45], v[158:161], v[188:191], v[42:45]
	v_mfma_f32_16x16x32_bf16 v[38:41], v[172:175], v[188:191], v[38:41]
	v_mfma_f32_16x16x32_bf16 v[26:29], v[158:161], v[212:215], v[26:29]
	v_mfma_f32_16x16x32_bf16 v[22:25], v[172:175], v[212:215], v[22:25]
	v_mfma_f32_16x16x32_bf16 v[14:17], v[158:161], v[220:223], v[14:17]
	v_mfma_f32_16x16x32_bf16 v[6:9], v[172:175], v[220:223], v[6:9]
	v_mfma_f32_16x16x32_bf16 v[58:61], v[168:171], v[184:187], v[58:61]
	v_mfma_f32_16x16x32_bf16 v[54:57], v[176:179], v[184:187], v[54:57]
	v_mfma_f32_16x16x32_bf16 v[42:45], v[168:171], v[208:211], v[42:45]
	v_mfma_f32_16x16x32_bf16 v[38:41], v[176:179], v[208:211], v[38:41]
	v_mfma_f32_16x16x32_bf16 v[26:29], v[168:171], v[216:219], v[26:29]
	v_mfma_f32_16x16x32_bf16 v[22:25], v[176:179], v[216:219], v[22:25]
	v_mfma_f32_16x16x32_bf16 v[14:17], v[168:171], v[224:227], v[14:17]
	v_mfma_f32_16x16x32_bf16 v[6:9], v[176:179], v[224:227], v[6:9]
	s_barrier
	s_add_u32 s36, s36, 0x100
	s_addc_u32 s37, s37, 0
	s_add_u32 vcc_hi, vcc_hi, 0x100
	s_addc_u32 s96, s96, 0
	s_cmp_ge_i32 s0, s56
	s_mov_b32 s40, s0
	s_cbranch_scc0 .LBB0_660
	v_readlane_b32 s96, v250, 43

; #define PG8_STAGE(bufoff, gbase, voff) do { _Pragma("unroll") for (int _i = 0; _i < 2; ++_i) \
;         __builtin_amdgcn_global_load_lds((const unsigned*)((const char*)(gbase) + (voff)[_i]), (LAS unsigned*)(lds + (bufoff) + ldsw + _i * 8192), 16, 0, 0); } while (0)
; #define PG8_LDA(dst, b, h) do { _Pragma("unroll") for (int m = 0; m < 4; ++m) _Pragma("unroll") for (int k = 0; k < 2; ++k) dst[m][k] = *(const LAS bf16x8*)(lds + PG8_SA(b, h) + aoff + m * 2048 + k * 1024); } while (0)
; #define PG8_LDB(dst, b, h) do { _Pragma("unroll") for (int n = 0; n < 2; ++n) _Pragma("unroll") for (int k = 0; k < 2; ++k) dst[n][k] = *(const LAS bf16x8*)(lds + PG8_SB(b, h) + boff + n * 2048 + k * 1024); } while (0)
; #define PG8_WAIT_V(n) asm volatile("s_waitcnt vmcnt(" #n ")" ::: "memory")
; #define PG8_WAIT_L(n) asm volatile("s_waitcnt lgkmcnt(" #n ")" ::: "memory")
; #define PG8_BAR __builtin_amdgcn_s_barrier()
; #define PG8_SCHED __builtin_amdgcn_sched_barrier(0)
; template <class Epi, class Sched>
; __device__ __forceinline__ void gemm_phase(LAS unsigned char* lds, const Gemm g, const Sched& S, const Epi& E) {
;     ...
;             const bool last = (t == nt - 2);
;             const char* a1 = cA + (size_t)(t + 1) * kstep;
;             const char* a2 = last ? nA : cA + (size_t)(t + 2) * kstep; const char* b2 = last ? nB : cB + (size_t)(t + 2) * kstep;
;             const char* a3 = a2 + kstep; const char* b3 = b2 + kstep;
;             if constexpr (Epi::MIDK) { if (t == (nt >> 1)) { int fr_ = fr, fq_ = fq; asm volatile("" : "+v"(fr_), "+v"(fq_)); E.mid(acc, cur, wr, wc, fr_, fq_); } }
;             PG8_LDB(B0, 0, 0); PG8_LDB(B1, 0, 1); PG8_SCHED; PG8_LDA(At, 0, 0); PG8_STAGE(PG8_SA(1, 1), a1 + hsA, voffA);
;             PG8_WAIT_V(8); PG8_WAIT_L(0); PG8_BAR; PG8_MMA(0, 0, At, B0); PG8_MMA(0, 1, At, B1); PG8_BAR; PG8_SCHED;
;             PG8_LDA(At, 0, 1); PG8_STAGE(PG8_SB(0, 0), b2, voffB); PG8_STAGE(PG8_SB(0, 1), b2 + hsB, voffB); PG8_STAGE(PG8_SA(0, 0), a2, voffA);
;             PG8_WAIT_V(8); PG8_WAIT_L(0); PG8_BAR; PG8_MMA(1, 0, At, B0); PG8_MMA(1, 1, At, B1); PG8_BAR; PG8_SCHED;
;         const int chalf = L & 1, k2g = (L >> 1) % ng, b = (L >> 1) / ng; u.offA = 0; u.offB = (((size_t)b * 512 + chalf * 256) * (256 * (size_t)N1) + (size_t)k2g * 512) * 2; return true; }
.LBB0_763:
	s_add_i32 s73, s46, 2
	s_add_u32 s44, s42, 0x100
	s_addc_u32 s45, s43, 0
	s_add_u32 s47, s57, s42
	s_addc_u32 s74, s64, s43
	s_cmp_eq_u32 s49, s46
	s_cselect_b32 s46, 0, s44
	s_cselect_b32 s75, 0, s45
	s_cselect_b32 s76, s56, s47
	s_cselect_b32 s77, s52, s74
	s_add_u32 s46, s22, s46
	s_addc_u32 s47, s23, s75
	s_add_i32 s74, 0, 0x10000
	v_add_u32_e32 v0, s74, v144
	s_add_i32 s75, 0, 0x14000
	ds_read_b128 v[146:149], v0
	ds_read_b128 v[150:153], v0 offset:1024
	ds_read_b128 v[154:157], v0 offset:2048
	ds_read_b128 v[158:161], v0 offset:3072
	v_add_u32_e32 v0, s75, v144
	ds_read_b128 v[162:165], v0
	ds_read_b128 v[166:169], v0 offset:1024
	ds_read_b128 v[170:173], v0 offset:2048
	ds_read_b128 v[174:177], v0 offset:3072
	v_lshl_add_u64 v[190:191], v[138:139], 0, s[42:43]
	s_add_i32 m0, s11, 0xc000
	ds_read_b128 v[178:181], v145
	ds_read_b128 v[182:185], v145 offset:1024
	ds_read_b128 v[186:189], v145 offset:2048
	ds_read_b128 v[208:211], v145 offset:3072
	ds_read_b128 v[212:215], v145 offset:4096
	ds_read_b128 v[216:219], v145 offset:5120
	ds_read_b128 v[220:223], v145 offset:6144
	ds_read_b128 v[224:227], v145 offset:7168
	global_load_lds_dwordx4 v[190:191], off
	v_lshl_add_u64 v[190:191], v[140:141], 0, s[42:43]
	s_add_i32 m0, s11, 0xe000
	s_nop 0
	global_load_lds_dwordx4 v[190:191], off
	s_waitcnt vmcnt(8)
	s_waitcnt lgkmcnt(0)
	s_barrier
	s_waitcnt lgkmcnt(0)
	v_mfma_f32_16x16x32_bf16 v[122:125], v[146:149], v[178:181], v[122:125]
	v_mfma_f32_16x16x32_bf16 v[126:129], v[154:157], v[178:181], v[126:129]
	v_mfma_f32_16x16x32_bf16 v[110:113], v[146:149], v[186:189], v[110:113]
	v_mfma_f32_16x16x32_bf16 v[106:109], v[154:157], v[186:189], v[106:109]
	v_mfma_f32_16x16x32_bf16 v[94:97], v[146:149], v[212:215], v[94:97]
	v_mfma_f32_16x16x32_bf16 v[90:93], v[154:157], v[212:215], v[90:93]
	v_mfma_f32_16x16x32_bf16 v[78:81], v[146:149], v[220:223], v[78:81]
	v_mfma_f32_16x16x32_bf16 v[74:77], v[154:157], v[220:223], v[74:77]
	v_mfma_f32_16x16x32_bf16 v[122:125], v[150:153], v[182:185], v[122:125]
	v_mfma_f32_16x16x32_bf16 v[126:129], v[158:161], v[182:185], v[126:129]
	v_mfma_f32_16x16x32_bf16 v[110:113], v[150:153], v[208:211], v[110:113]
	v_mfma_f32_16x16x32_bf16 v[106:109], v[158:161], v[208:211], v[106:109]
	v_mfma_f32_16x16x32_bf16 v[94:97], v[150:153], v[216:219], v[94:97]
	v_mfma_f32_16x16x32_bf16 v[90:93], v[158:161], v[216:219], v[90:93]
	v_mfma_f32_16x16x32_bf16 v[78:81], v[150:153], v[224:227], v[78:81]
	v_mfma_f32_16x16x32_bf16 v[74:77], v[158:161], v[224:227], v[74:77]
	v_mfma_f32_16x16x32_bf16 v[118:121], v[162:165], v[178:181], v[118:121]
	v_mfma_f32_16x16x32_bf16 v[114:117], v[170:173], v[178:181], v[114:117]
	v_mfma_f32_16x16x32_bf16 v[102:105], v[162:165], v[186:189], v[102:105]
	v_mfma_f32_16x16x32_bf16 v[98:101], v[170:173], v[186:189], v[98:101]
	v_mfma_f32_16x16x32_bf16 v[86:89], v[162:165], v[212:215], v[86:89]
	v_mfma_f32_16x16x32_bf16 v[82:85], v[170:173], v[212:215], v[82:85]
	v_mfma_f32_16x16x32_bf16 v[70:73], v[162:165], v[220:223], v[70:73]
	v_mfma_f32_16x16x32_bf16 v[66:69], v[170:173], v[220:223], v[66:69]
	v_mfma_f32_16x16x32_bf16 v[118:121], v[166:169], v[182:185], v[118:121]
	v_mfma_f32_16x16x32_bf16 v[114:117], v[174:177], v[182:185], v[114:117]
	v_mfma_f32_16x16x32_bf16 v[102:105], v[166:169], v[208:211], v[102:105]
	v_mfma_f32_16x16x32_bf16 v[98:101], v[174:177], v[208:211], v[98:101]
	v_mfma_f32_16x16x32_bf16 v[86:89], v[166:169], v[216:219], v[86:89]
	v_mfma_f32_16x16x32_bf16 v[82:85], v[174:177], v[216:219], v[82:85]
	v_mfma_f32_16x16x32_bf16 v[70:73], v[166:169], v[224:227], v[70:73]
	v_mfma_f32_16x16x32_bf16 v[66:69], v[174:177], v[224:227], v[66:69]
	s_barrier
	s_add_i32 s42, s74, s7
	v_lshl_add_u64 v[190:191], s[76:77], 0, v[134:135]
	s_mov_b32 m0, s42
	ds_read_b128 v[178:181], v145 offset:16384
	ds_read_b128 v[182:185], v145 offset:17408
	ds_read_b128 v[186:189], v145 offset:18432
	ds_read_b128 v[208:211], v145 offset:19456
	ds_read_b128 v[212:215], v145 offset:20480
	ds_read_b128 v[216:219], v145 offset:21504
	ds_read_b128 v[220:223], v145 offset:22528
	ds_read_b128 v[224:227], v145 offset:23552
	global_load_lds_dwordx4 v[190:191], off
	s_add_i32 m0, s42, 0x2000
	s_add_u32 s42, s76, s78
	v_lshl_add_u64 v[228:229], s[76:77], 0, v[130:131]
	s_addc_u32 s43, s77, 0
	s_add_i32 s74, s75, s7
	global_load_lds_dwordx4 v[228:229], off
	v_lshl_add_u64 v[230:231], s[42:43], 0, v[134:135]
	s_mov_b32 m0, s74
	v_lshl_add_u64 v[232:233], s[42:43], 0, v[130:131]
	global_load_lds_dwordx4 v[230:231], off
	s_add_i32 m0, s74, 0x2000
	v_lshl_add_u64 v[238:239], s[46:47], 0, v[136:137]
	global_load_lds_dwordx4 v[232:233], off
	s_mov_b32 m0, s11
	v_lshl_add_u64 v[240:241], s[46:47], 0, v[132:133]
	global_load_lds_dwordx4 v[238:239], off
	s_mov_b32 m0, s10
	s_nop 0
	global_load_lds_dwordx4 v[240:241], off
	s_waitcnt vmcnt(8)
	s_waitcnt lgkmcnt(0)
	s_barrier
; #define PG8_STAGE(bufoff, gbase, voff) do { _Pragma("unroll") for (int _i = 0; _i < 2; ++_i) \
;         __builtin_amdgcn_global_load_lds((const unsigned*)((const char*)(gbase) + (voff)[_i]), (LAS unsigned*)(lds + (bufoff) + ldsw + _i * 8192), 16, 0, 0); } while (0)
; #define PG8_LDA(dst, b, h) do { _Pragma("unroll") for (int m = 0; m < 4; ++m) _Pragma("unroll") for (int k = 0; k < 2; ++k) dst[m][k] = *(const LAS bf16x8*)(lds + PG8_SA(b, h) + aoff + m * 2048 + k * 1024); } while (0)
; #define PG8_LDB(dst, b, h) do { _Pragma("unroll") for (int n = 0; n < 2; ++n) _Pragma("unroll") for (int k = 0; k < 2; ++k) dst[n][k] = *(const LAS bf16x8*)(lds + PG8_SB(b, h) + boff + n * 2048 + k * 1024); } while (0)
; #define PG8_MMA(ai, bj, At, Bt) do { __builtin_amdgcn_s_setprio(1); _Pragma("unroll") for (int m = 0; m < 4; ++m) _Pragma("unroll") for (int n = 0; n < 2; ++n) _Pragma("unroll") for (int k = 0; k < 2; ++k) \
;         acc[ai][bj][m][n] = __builtin_amdgcn_mfma_f32_16x16x32_bf16(Bt[n][k], At[m][k], acc[ai][bj][m][n], 0, 0, 0); __builtin_amdgcn_s_setprio(0); } while (0)
; #define PG8_WAIT_V(n) asm volatile("s_waitcnt vmcnt(" #n ")" ::: "memory")
; #define PG8_WAIT_L(n) asm volatile("s_waitcnt lgkmcnt(" #n ")" ::: "memory")
; #define PG8_BAR __builtin_amdgcn_s_barrier()
; #define PG8_SCHED __builtin_amdgcn_sched_barrier(0)
; template <class Epi, class Sched>
; __device__ __forceinline__ void gemm_phase(LAS unsigned char* lds, const Gemm g, const Sched& S, const Epi& E) {
;     ...
;             PG8_WAIT_V(8); PG8_WAIT_L(0); PG8_BAR; PG8_MMA(1, 0, At, B0); PG8_MMA(1, 1, At, B1); PG8_BAR; PG8_SCHED;
;             PG8_LDB(B0, 1, 0); PG8_LDB(B1, 1, 1); PG8_SCHED; PG8_LDA(At, 1, 0); PG8_STAGE(PG8_SA(0, 1), a2 + hsA, voffA);
;             PG8_WAIT_V(8); PG8_WAIT_L(0); PG8_BAR; PG8_MMA(0, 0, At, B0); PG8_MMA(0, 1, At, B1); PG8_BAR; PG8_SCHED;
	s_waitcnt lgkmcnt(0)
	v_mfma_f32_16x16x32_bf16 v[62:65], v[146:149], v[178:181], v[62:65]
	v_mfma_f32_16x16x32_bf16 v[58:61], v[154:157], v[178:181], v[58:61]
	v_mfma_f32_16x16x32_bf16 v[46:49], v[146:149], v[186:189], v[46:49]
	v_mfma_f32_16x16x32_bf16 v[42:45], v[154:157], v[186:189], v[42:45]
	v_mfma_f32_16x16x32_bf16 v[30:33], v[146:149], v[212:215], v[30:33]
	v_mfma_f32_16x16x32_bf16 v[26:29], v[154:157], v[212:215], v[26:29]
	v_mfma_f32_16x16x32_bf16 v[14:17], v[146:149], v[220:223], v[14:17]
	v_mfma_f32_16x16x32_bf16 v[10:13], v[154:157], v[220:223], v[10:13]
	v_mfma_f32_16x16x32_bf16 v[62:65], v[150:153], v[182:185], v[62:65]
	v_mfma_f32_16x16x32_bf16 v[58:61], v[158:161], v[182:185], v[58:61]
	v_mfma_f32_16x16x32_bf16 v[46:49], v[150:153], v[208:211], v[46:49]
	v_mfma_f32_16x16x32_bf16 v[42:45], v[158:161], v[208:211], v[42:45]
	v_mfma_f32_16x16x32_bf16 v[30:33], v[150:153], v[216:219], v[30:33]
	v_mfma_f32_16x16x32_bf16 v[26:29], v[158:161], v[216:219], v[26:29]
	v_mfma_f32_16x16x32_bf16 v[14:17], v[150:153], v[224:227], v[14:17]
	v_mfma_f32_16x16x32_bf16 v[10:13], v[158:161], v[224:227], v[10:13]
	v_mfma_f32_16x16x32_bf16 v[54:57], v[162:165], v[178:181], v[54:57]
	v_mfma_f32_16x16x32_bf16 v[50:53], v[170:173], v[178:181], v[50:53]
	v_mfma_f32_16x16x32_bf16 v[38:41], v[162:165], v[186:189], v[38:41]
	v_mfma_f32_16x16x32_bf16 v[34:37], v[170:173], v[186:189], v[34:37]
	v_mfma_f32_16x16x32_bf16 v[22:25], v[162:165], v[212:215], v[22:25]
	v_mfma_f32_16x16x32_bf16 v[18:21], v[170:173], v[212:215], v[18:21]
	v_mfma_f32_16x16x32_bf16 v[6:9], v[162:165], v[220:223], v[6:9]
	v_mfma_f32_16x16x32_bf16 v[2:5], v[170:173], v[220:223], v[2:5]
	v_mfma_f32_16x16x32_bf16 v[54:57], v[166:169], v[182:185], v[54:57]
	v_mfma_f32_16x16x32_bf16 v[50:53], v[174:177], v[182:185], v[50:53]
	v_mfma_f32_16x16x32_bf16 v[38:41], v[166:169], v[208:211], v[38:41]
	v_mfma_f32_16x16x32_bf16 v[34:37], v[174:177], v[208:211], v[34:37]
	v_mfma_f32_16x16x32_bf16 v[22:25], v[166:169], v[216:219], v[22:25]
	v_mfma_f32_16x16x32_bf16 v[18:21], v[174:177], v[216:219], v[18:21]
	v_mfma_f32_16x16x32_bf16 v[6:9], v[166:169], v[224:227], v[6:9]
	v_mfma_f32_16x16x32_bf16 v[2:5], v[174:177], v[224:227], v[2:5]
	s_barrier
	s_add_i32 s74, 0, 0x18000
	v_add_u32_e32 v0, s74, v144
	s_add_i32 s75, 0, 0x1c000
	ds_read_b128 v[146:149], v0
	ds_read_b128 v[150:153], v0 offset:1024
	ds_read_b128 v[154:157], v0 offset:2048
	ds_read_b128 v[158:161], v0 offset:3072
	v_add_u32_e32 v0, s75, v144
	ds_read_b128 v[162:165], v0
	ds_read_b128 v[166:169], v0 offset:1024
	ds_read_b128 v[170:173], v0 offset:2048
	ds_read_b128 v[174:177], v0 offset:3072
	s_add_u32 s42, s46, 0x20000
	s_addc_u32 s43, s47, 0
	s_mov_b32 m0, s12
	v_lshl_add_u64 v[242:243], s[42:43], 0, v[136:137]
	ds_read_b128 v[178:181], v145 offset:32768
	ds_read_b128 v[182:185], v145 offset:33792
	ds_read_b128 v[186:189], v145 offset:34816
	ds_read_b128 v[208:211], v145 offset:35840
	ds_read_b128 v[212:215], v145 offset:36864
	ds_read_b128 v[216:219], v145 offset:37888
	ds_read_b128 v[220:223], v145 offset:38912
	ds_read_b128 v[224:227], v145 offset:39936
	global_load_lds_dwordx4 v[242:243], off
	v_lshl_add_u64 v[242:243], s[42:43], 0, v[132:133]
	s_mov_b32 m0, s16
	s_nop 0
	global_load_lds_dwordx4 v[242:243], off
	s_waitcnt vmcnt(8)
	s_waitcnt lgkmcnt(0)
	s_barrier
	s_waitcnt lgkmcnt(0)
	v_mfma_f32_16x16x32_bf16 v[122:125], v[146:149], v[178:181], v[122:125]
	v_mfma_f32_16x16x32_bf16 v[126:129], v[154:157], v[178:181], v[126:129]
	v_mfma_f32_16x16x32_bf16 v[110:113], v[146:149], v[186:189], v[110:113]
	v_mfma_f32_16x16x32_bf16 v[106:109], v[154:157], v[186:189], v[106:109]
	v_mfma_f32_16x16x32_bf16 v[94:97], v[146:149], v[212:215], v[94:97]
	v_mfma_f32_16x16x32_bf16 v[90:93], v[154:157], v[212:215], v[90:93]
	v_mfma_f32_16x16x32_bf16 v[78:81], v[146:149], v[220:223], v[78:81]
	v_mfma_f32_16x16x32_bf16 v[74:77], v[154:157], v[220:223], v[74:77]
	v_mfma_f32_16x16x32_bf16 v[122:125], v[150:153], v[182:185], v[122:125]
	v_mfma_f32_16x16x32_bf16 v[126:129], v[158:161], v[182:185], v[126:129]
	v_mfma_f32_16x16x32_bf16 v[110:113], v[150:153], v[208:211], v[110:113]
	v_mfma_f32_16x16x32_bf16 v[106:109], v[158:161], v[208:211], v[106:109]
	v_mfma_f32_16x16x32_bf16 v[94:97], v[150:153], v[216:219], v[94:97]
	v_mfma_f32_16x16x32_bf16 v[90:93], v[158:161], v[216:219], v[90:93]
	v_mfma_f32_16x16x32_bf16 v[78:81], v[150:153], v[224:227], v[78:81]
	v_mfma_f32_16x16x32_bf16 v[74:77], v[158:161], v[224:227], v[74:77]
	v_mfma_f32_16x16x32_bf16 v[118:121], v[162:165], v[178:181], v[118:121]
	v_mfma_f32_16x16x32_bf16 v[114:117], v[170:173], v[178:181], v[114:117]
	v_mfma_f32_16x16x32_bf16 v[102:105], v[162:165], v[186:189], v[102:105]
	v_mfma_f32_16x16x32_bf16 v[98:101], v[170:173], v[186:189], v[98:101]
	v_mfma_f32_16x16x32_bf16 v[86:89], v[162:165], v[212:215], v[86:89]
	v_mfma_f32_16x16x32_bf16 v[82:85], v[170:173], v[212:215], v[82:85]
	v_mfma_f32_16x16x32_bf16 v[70:73], v[162:165], v[220:223], v[70:73]
	v_mfma_f32_16x16x32_bf16 v[66:69], v[170:173], v[220:223], v[66:69]
	v_mfma_f32_16x16x32_bf16 v[118:121], v[166:169], v[182:185], v[118:121]
	v_mfma_f32_16x16x32_bf16 v[114:117], v[174:177], v[182:185], v[114:117]
	v_mfma_f32_16x16x32_bf16 v[102:105], v[166:169], v[208:211], v[102:105]
	v_mfma_f32_16x16x32_bf16 v[98:101], v[174:177], v[208:211], v[98:101]
	v_mfma_f32_16x16x32_bf16 v[86:89], v[166:169], v[216:219], v[86:89]
	v_mfma_f32_16x16x32_bf16 v[82:85], v[174:177], v[216:219], v[82:85]
	v_mfma_f32_16x16x32_bf16 v[70:73], v[166:169], v[224:227], v[70:73]
	v_mfma_f32_16x16x32_bf16 v[66:69], v[174:177], v[224:227], v[66:69]
	s_barrier
; #define PG8_STAGE(bufoff, gbase, voff) do { _Pragma("unroll") for (int _i = 0; _i < 2; ++_i) \
;         __builtin_amdgcn_global_load_lds((const unsigned*)((const char*)(gbase) + (voff)[_i]), (LAS unsigned*)(lds + (bufoff) + ldsw + _i * 8192), 16, 0, 0); } while (0)
; #define PG8_LDA(dst, b, h) do { _Pragma("unroll") for (int m = 0; m < 4; ++m) _Pragma("unroll") for (int k = 0; k < 2; ++k) dst[m][k] = *(const LAS bf16x8*)(lds + PG8_SA(b, h) + aoff + m * 2048 + k * 1024); } while (0)
; #define PG8_MMA(ai, bj, At, Bt) do { __builtin_amdgcn_s_setprio(1); _Pragma("unroll") for (int m = 0; m < 4; ++m) _Pragma("unroll") for (int n = 0; n < 2; ++n) _Pragma("unroll") for (int k = 0; k < 2; ++k) \
;         acc[ai][bj][m][n] = __builtin_amdgcn_mfma_f32_16x16x32_bf16(Bt[n][k], At[m][k], acc[ai][bj][m][n], 0, 0, 0); __builtin_amdgcn_s_setprio(0); } while (0)
; #define PG8_WAIT_V(n) asm volatile("s_waitcnt vmcnt(" #n ")" ::: "memory")
; #define PG8_WAIT_L(n) asm volatile("s_waitcnt lgkmcnt(" #n ")" ::: "memory")
; #define PG8_BAR __builtin_amdgcn_s_barrier()
; #define PG8_SCHED __builtin_amdgcn_sched_barrier(0)
; template <class Epi, class Sched>
; __device__ __forceinline__ void gemm_phase(LAS unsigned char* lds, const Gemm g, const Sched& S, const Epi& E) {
;     ...
;             PG8_LDA(At, 1, 1); PG8_STAGE(PG8_SB(1, 0), b3, voffB); PG8_STAGE(PG8_SB(1, 1), b3 + hsB, voffB); PG8_STAGE(PG8_SA(1, 0), a3, voffA);
;             PG8_WAIT_V(8); PG8_WAIT_L(0); PG8_BAR; PG8_MMA(1, 0, At, B0); PG8_MMA(1, 1, At, B1); PG8_BAR; PG8_SCHED;
;         }
	s_add_i32 s42, s74, s7
	v_lshl_add_u64 v[190:191], v[190:191], 0, s[18:19]
	s_mov_b32 m0, s42
	ds_read_b128 v[178:181], v145 offset:49152
	ds_read_b128 v[182:185], v145 offset:50176
	ds_read_b128 v[186:189], v145 offset:51200
	ds_read_b128 v[208:211], v145 offset:52224
	ds_read_b128 v[212:215], v145 offset:53248
	ds_read_b128 v[216:219], v145 offset:54272
	ds_read_b128 v[220:223], v145 offset:55296
	ds_read_b128 v[224:227], v145 offset:56320
	global_load_lds_dwordx4 v[190:191], off
	v_lshl_add_u64 v[190:191], v[228:229], 0, s[18:19]
	s_add_i32 m0, s42, 0x2000
	s_add_i32 s42, s75, s7
	global_load_lds_dwordx4 v[190:191], off
	v_lshl_add_u64 v[190:191], v[230:231], 0, s[18:19]
	s_mov_b32 m0, s42
	s_nop 0
	global_load_lds_dwordx4 v[190:191], off
	v_lshl_add_u64 v[190:191], v[232:233], 0, s[18:19]
	s_add_i32 m0, s42, 0x2000
	s_nop 0
	global_load_lds_dwordx4 v[190:191], off
	v_lshl_add_u64 v[190:191], v[238:239], 0, s[18:19]
	s_mov_b32 m0, s30
	s_nop 0
	global_load_lds_dwordx4 v[190:191], off
	v_lshl_add_u64 v[190:191], v[240:241], 0, s[18:19]
	s_mov_b32 m0, s48
	s_nop 0
	global_load_lds_dwordx4 v[190:191], off
	s_waitcnt vmcnt(8)
	s_waitcnt lgkmcnt(0)
	s_barrier
	s_waitcnt lgkmcnt(0)
	v_mfma_f32_16x16x32_bf16 v[62:65], v[146:149], v[178:181], v[62:65]
	v_mfma_f32_16x16x32_bf16 v[58:61], v[154:157], v[178:181], v[58:61]
	v_mfma_f32_16x16x32_bf16 v[46:49], v[146:149], v[186:189], v[46:49]
	v_mfma_f32_16x16x32_bf16 v[42:45], v[154:157], v[186:189], v[42:45]
	v_mfma_f32_16x16x32_bf16 v[30:33], v[146:149], v[212:215], v[30:33]
	v_mfma_f32_16x16x32_bf16 v[26:29], v[154:157], v[212:215], v[26:29]
	v_mfma_f32_16x16x32_bf16 v[14:17], v[146:149], v[220:223], v[14:17]
	v_mfma_f32_16x16x32_bf16 v[10:13], v[154:157], v[220:223], v[10:13]
	v_mfma_f32_16x16x32_bf16 v[62:65], v[150:153], v[182:185], v[62:65]
	v_mfma_f32_16x16x32_bf16 v[58:61], v[158:161], v[182:185], v[58:61]
	v_mfma_f32_16x16x32_bf16 v[46:49], v[150:153], v[208:211], v[46:49]
	v_mfma_f32_16x16x32_bf16 v[42:45], v[158:161], v[208:211], v[42:45]
	v_mfma_f32_16x16x32_bf16 v[30:33], v[150:153], v[216:219], v[30:33]
	v_mfma_f32_16x16x32_bf16 v[26:29], v[158:161], v[216:219], v[26:29]
	v_mfma_f32_16x16x32_bf16 v[14:17], v[150:153], v[224:227], v[14:17]
	v_mfma_f32_16x16x32_bf16 v[10:13], v[158:161], v[224:227], v[10:13]
	v_mfma_f32_16x16x32_bf16 v[54:57], v[162:165], v[178:181], v[54:57]
	v_mfma_f32_16x16x32_bf16 v[50:53], v[170:173], v[178:181], v[50:53]
	v_mfma_f32_16x16x32_bf16 v[38:41], v[162:165], v[186:189], v[38:41]
	v_mfma_f32_16x16x32_bf16 v[34:37], v[170:173], v[186:189], v[34:37]
	v_mfma_f32_16x16x32_bf16 v[22:25], v[162:165], v[212:215], v[22:25]
	v_mfma_f32_16x16x32_bf16 v[18:21], v[170:173], v[212:215], v[18:21]
	v_mfma_f32_16x16x32_bf16 v[6:9], v[162:165], v[220:223], v[6:9]
	v_mfma_f32_16x16x32_bf16 v[2:5], v[170:173], v[220:223], v[2:5]
	v_mfma_f32_16x16x32_bf16 v[54:57], v[166:169], v[182:185], v[54:57]
	v_mfma_f32_16x16x32_bf16 v[50:53], v[174:177], v[182:185], v[50:53]
	v_mfma_f32_16x16x32_bf16 v[38:41], v[166:169], v[208:211], v[38:41]
	v_mfma_f32_16x16x32_bf16 v[34:37], v[174:177], v[208:211], v[34:37]
	v_mfma_f32_16x16x32_bf16 v[22:25], v[166:169], v[216:219], v[22:25]
	v_mfma_f32_16x16x32_bf16 v[18:21], v[174:177], v[216:219], v[18:21]
	v_mfma_f32_16x16x32_bf16 v[6:9], v[166:169], v[224:227], v[6:9]
	v_mfma_f32_16x16x32_bf16 v[2:5], v[174:177], v[224:227], v[2:5]
	s_barrier
	s_cmp_ge_i32 s73, s24
	s_mov_b64 s[42:43], s[44:45]
	s_mov_b32 s46, s73
	s_cbranch_scc0 .LBB0_763

; #define PG8_STAGE(bufoff, gbase, voff) do { _Pragma("unroll") for (int _i = 0; _i < 2; ++_i) \
;         __builtin_amdgcn_global_load_lds((const unsigned*)((const char*)(gbase) + (voff)[_i]), (LAS unsigned*)(lds + (bufoff) + ldsw + _i * 8192), 16, 0, 0); } while (0)
; #define PG8_LDA(dst, b, h) do { _Pragma("unroll") for (int m = 0; m < 4; ++m) _Pragma("unroll") for (int k = 0; k < 2; ++k) dst[m][k] = *(const LAS bf16x8*)(lds + PG8_SA(b, h) + aoff + m * 2048 + k * 1024); } while (0)
; #define PG8_LDB(dst, b, h) do { _Pragma("unroll") for (int n = 0; n < 2; ++n) _Pragma("unroll") for (int k = 0; k < 2; ++k) dst[n][k] = *(const LAS bf16x8*)(lds + PG8_SB(b, h) + boff + n * 2048 + k * 1024); } while (0)
; #define PG8_MMA(ai, bj, At, Bt) do { __builtin_amdgcn_s_setprio(1); _Pragma("unroll") for (int m = 0; m < 4; ++m) _Pragma("unroll") for (int n = 0; n < 2; ++n) _Pragma("unroll") for (int k = 0; k < 2; ++k) \
;         acc[ai][bj][m][n] = __builtin_amdgcn_mfma_f32_16x16x32_bf16(Bt[n][k], At[m][k], acc[ai][bj][m][n], 0, 0, 0); __builtin_amdgcn_s_setprio(0); } while (0)
; #define PG8_WAIT_V(n) asm volatile("s_waitcnt vmcnt(" #n ")" ::: "memory")
; #define PG8_WAIT_L(n) asm volatile("s_waitcnt lgkmcnt(" #n ")" ::: "memory")
; template <class Epi, class Sched>
; __device__ __forceinline__ void gemm_phase(LAS unsigned char* lds, const Gemm g, const Sched& S, const Epi& E) {
;     ...
;             const bool last = (t == nt - 2);
;             const char* a1 = cA + (size_t)(t + 1) * kstep;
;             const char* a2 = last ? nA : cA + (size_t)(t + 2) * kstep; const char* b2 = last ? nB : cB + (size_t)(t + 2) * kstep;
;             const char* a3 = a2 + kstep; const char* b3 = b2 + kstep;
;             if constexpr (Epi::MIDK) { if (t == (nt >> 1)) { int fr_ = fr, fq_ = fq; asm volatile("" : "+v"(fr_), "+v"(fq_)); E.mid(acc, cur, wr, wc, fr_, fq_); } }
;             PG8_LDB(B0, 0, 0); PG8_LDB(B1, 0, 1); PG8_SCHED; PG8_LDA(At, 0, 0); PG8_STAGE(PG8_SA(1, 1), a1 + hsA, voffA);
;             PG8_WAIT_V(8); PG8_WAIT_L(0); PG8_BAR; PG8_MMA(0, 0, At, B0); PG8_MMA(0, 1, At, B1); PG8_BAR; PG8_SCHED;
;             PG8_LDA(At, 0, 1); PG8_STAGE(PG8_SB(0, 0), b2, voffB); PG8_STAGE(PG8_SB(0, 1), b2 + hsB, voffB); PG8_STAGE(PG8_SA(0, 0), a2, voffA);
;             PG8_WAIT_V(8); PG8_WAIT_L(0); PG8_BAR; PG8_MMA(1, 0, At, B0); PG8_MMA(1, 1, At, B1); PG8_BAR; PG8_SCHED;
.LBB0_837:
	s_add_i32 s96, s76, 2
	s_add_u32 s74, s50, 0xfffc0080
	s_addc_u32 s75, s51, -1
	s_cmp_eq_u32 s64, s76
	s_cselect_b32 s85, s10, s75
	s_cselect_b32 s84, s35, s74
	s_cselect_b32 s77, s41, s1
	s_cselect_b32 s76, s83, s0
	s_add_i32 s74, 0, 0x10000
	v_add_u32_e32 v0, s74, v206
	s_add_i32 s75, 0, 0x14000
	ds_read_b128 v[132:135], v0
	ds_read_b128 v[136:139], v0 offset:1024
	ds_read_b128 v[140:143], v0 offset:2048
	ds_read_b128 v[144:147], v0 offset:3072
	v_add_u32_e32 v0, s75, v206
	ds_read_b128 v[148:151], v0
	ds_read_b128 v[152:155], v0 offset:1024
	ds_read_b128 v[156:159], v0 offset:2048
	ds_read_b128 v[160:163], v0 offset:3072
	v_lshl_add_u64 v[2:3], s[50:51], 0, v[216:217]
	s_add_i32 m0, s11, 0xc000
	ds_read_b128 v[164:167], v238
	ds_read_b128 v[168:171], v238 offset:1024
	ds_read_b128 v[172:175], v238 offset:2048
	ds_read_b128 v[176:179], v238 offset:3072
	ds_read_b128 v[180:183], v238 offset:4096
	ds_read_b128 v[184:187], v238 offset:5120
	ds_read_b128 v[188:191], v238 offset:6144
	ds_read_b128 v[220:223], v238 offset:7168
	global_load_lds_dwordx4 v[2:3], off
	v_lshl_add_u64 v[2:3], s[50:51], 0, v[218:219]
	s_add_i32 m0, s11, 0xe000
	s_nop 0
	global_load_lds_dwordx4 v[2:3], off
	s_waitcnt vmcnt(8)
	s_waitcnt lgkmcnt(0)
	s_barrier
	s_waitcnt lgkmcnt(0)
	v_mfma_f32_16x16x32_bf16 v[124:127], v[132:135], v[164:167], v[124:127]
	v_mfma_f32_16x16x32_bf16 v[128:131], v[140:143], v[164:167], v[128:131]
	v_mfma_f32_16x16x32_bf16 v[112:115], v[132:135], v[172:175], v[112:115]
	v_mfma_f32_16x16x32_bf16 v[108:111], v[140:143], v[172:175], v[108:111]
	v_mfma_f32_16x16x32_bf16 v[96:99], v[132:135], v[180:183], v[96:99]
	v_mfma_f32_16x16x32_bf16 v[92:95], v[140:143], v[180:183], v[92:95]
	v_mfma_f32_16x16x32_bf16 v[80:83], v[132:135], v[188:191], v[80:83]
	v_mfma_f32_16x16x32_bf16 v[76:79], v[140:143], v[188:191], v[76:79]
	v_mfma_f32_16x16x32_bf16 v[124:127], v[136:139], v[168:171], v[124:127]
	v_mfma_f32_16x16x32_bf16 v[128:131], v[144:147], v[168:171], v[128:131]
	v_mfma_f32_16x16x32_bf16 v[112:115], v[136:139], v[176:179], v[112:115]
	v_mfma_f32_16x16x32_bf16 v[108:111], v[144:147], v[176:179], v[108:111]
	v_mfma_f32_16x16x32_bf16 v[96:99], v[136:139], v[184:187], v[96:99]
	v_mfma_f32_16x16x32_bf16 v[92:95], v[144:147], v[184:187], v[92:95]
	v_mfma_f32_16x16x32_bf16 v[80:83], v[136:139], v[220:223], v[80:83]
	v_mfma_f32_16x16x32_bf16 v[76:79], v[144:147], v[220:223], v[76:79]
	v_mfma_f32_16x16x32_bf16 v[116:119], v[148:151], v[164:167], v[116:119]
	v_mfma_f32_16x16x32_bf16 v[120:123], v[156:159], v[164:167], v[120:123]
	v_mfma_f32_16x16x32_bf16 v[104:107], v[148:151], v[172:175], v[104:107]
	v_mfma_f32_16x16x32_bf16 v[100:103], v[156:159], v[172:175], v[100:103]
	v_mfma_f32_16x16x32_bf16 v[88:91], v[148:151], v[180:183], v[88:91]
	v_mfma_f32_16x16x32_bf16 v[84:87], v[156:159], v[180:183], v[84:87]
	v_mfma_f32_16x16x32_bf16 v[72:75], v[148:151], v[188:191], v[72:75]
	v_mfma_f32_16x16x32_bf16 v[68:71], v[156:159], v[188:191], v[68:71]
	v_mfma_f32_16x16x32_bf16 v[116:119], v[152:155], v[168:171], v[116:119]
	v_mfma_f32_16x16x32_bf16 v[120:123], v[160:163], v[168:171], v[120:123]
	v_mfma_f32_16x16x32_bf16 v[104:107], v[152:155], v[176:179], v[104:107]
	v_mfma_f32_16x16x32_bf16 v[100:103], v[160:163], v[176:179], v[100:103]
	v_mfma_f32_16x16x32_bf16 v[88:91], v[152:155], v[184:187], v[88:91]
	v_mfma_f32_16x16x32_bf16 v[84:87], v[160:163], v[184:187], v[84:87]
	v_mfma_f32_16x16x32_bf16 v[72:75], v[152:155], v[220:223], v[72:75]
	v_mfma_f32_16x16x32_bf16 v[68:71], v[160:163], v[220:223], v[68:71]
	s_barrier
	s_add_i32 s74, s74, s7
	v_lshl_add_u64 v[224:225], s[76:77], 0, v[212:213]
	s_mov_b32 m0, s74
	ds_read_b128 v[164:167], v238 offset:16384
	ds_read_b128 v[168:171], v238 offset:17408
	ds_read_b128 v[172:175], v238 offset:18432
	ds_read_b128 v[176:179], v238 offset:19456
	ds_read_b128 v[180:183], v238 offset:20480
	ds_read_b128 v[184:187], v238 offset:21504
	ds_read_b128 v[188:191], v238 offset:22528
	ds_read_b128 v[220:223], v238 offset:23552
	global_load_lds_dwordx4 v[224:225], off
	s_add_i32 m0, s74, 0x2000
	s_add_u32 vcc_lo, s76, 0x40000
	v_lshl_add_u64 v[226:227], s[76:77], 0, v[208:209]
	s_addc_u32 vcc_hi, s77, 0
	s_add_i32 s74, s75, s7
	global_load_lds_dwordx4 v[226:227], off
	v_lshl_add_u64 v[2:3], vcc, 0, v[212:213]
	s_mov_b32 m0, s74
	v_lshl_add_u64 v[228:229], s[84:85], 0, v[214:215]
	global_load_lds_dwordx4 v[2:3], off
	v_lshl_add_u64 v[2:3], vcc, 0, v[208:209]
	s_add_i32 m0, s74, 0x2000
	v_lshl_add_u64 v[230:231], s[84:85], 0, v[210:211]
	global_load_lds_dwordx4 v[2:3], off
	s_mov_b32 m0, s11
	s_nop 0
	global_load_lds_dwordx4 v[228:229], off
	s_mov_b32 m0, s12
	s_nop 0
	global_load_lds_dwordx4 v[230:231], off
	s_waitcnt vmcnt(8)
	s_waitcnt lgkmcnt(0)
	s_barrier
; #define PG8_STAGE(bufoff, gbase, voff) do { _Pragma("unroll") for (int _i = 0; _i < 2; ++_i) \
;         __builtin_amdgcn_global_load_lds((const unsigned*)((const char*)(gbase) + (voff)[_i]), (LAS unsigned*)(lds + (bufoff) + ldsw + _i * 8192), 16, 0, 0); } while (0)
; #define PG8_LDA(dst, b, h) do { _Pragma("unroll") for (int m = 0; m < 4; ++m) _Pragma("unroll") for (int k = 0; k < 2; ++k) dst[m][k] = *(const LAS bf16x8*)(lds + PG8_SA(b, h) + aoff + m * 2048 + k * 1024); } while (0)
; #define PG8_LDB(dst, b, h) do { _Pragma("unroll") for (int n = 0; n < 2; ++n) _Pragma("unroll") for (int k = 0; k < 2; ++k) dst[n][k] = *(const LAS bf16x8*)(lds + PG8_SB(b, h) + boff + n * 2048 + k * 1024); } while (0)
; #define PG8_MMA(ai, bj, At, Bt) do { __builtin_amdgcn_s_setprio(1); _Pragma("unroll") for (int m = 0; m < 4; ++m) _Pragma("unroll") for (int n = 0; n < 2; ++n) _Pragma("unroll") for (int k = 0; k < 2; ++k) \
;         acc[ai][bj][m][n] = __builtin_amdgcn_mfma_f32_16x16x32_bf16(Bt[n][k], At[m][k], acc[ai][bj][m][n], 0, 0, 0); __builtin_amdgcn_s_setprio(0); } while (0)
; #define PG8_WAIT_V(n) asm volatile("s_waitcnt vmcnt(" #n ")" ::: "memory")
; #define PG8_WAIT_L(n) asm volatile("s_waitcnt lgkmcnt(" #n ")" ::: "memory")
; #define PG8_BAR __builtin_amdgcn_s_barrier()
; #define PG8_SCHED __builtin_amdgcn_sched_barrier(0)
; template <class Epi, class Sched>
; __device__ __forceinline__ void gemm_phase(LAS unsigned char* lds, const Gemm g, const Sched& S, const Epi& E) {
;     ...
;             PG8_WAIT_V(8); PG8_WAIT_L(0); PG8_BAR; PG8_MMA(1, 0, At, B0); PG8_MMA(1, 1, At, B1); PG8_BAR; PG8_SCHED;
;             PG8_LDB(B0, 1, 0); PG8_LDB(B1, 1, 1); PG8_SCHED; PG8_LDA(At, 1, 0); PG8_STAGE(PG8_SA(0, 1), a2 + hsA, voffA);
;             PG8_WAIT_V(8); PG8_WAIT_L(0); PG8_BAR; PG8_MMA(0, 0, At, B0); PG8_MMA(0, 1, At, B1); PG8_BAR; PG8_SCHED;
	s_waitcnt lgkmcnt(0)
	v_mfma_f32_16x16x32_bf16 v[64:67], v[132:135], v[164:167], v[64:67]
	v_mfma_f32_16x16x32_bf16 v[60:63], v[140:143], v[164:167], v[60:63]
	v_mfma_f32_16x16x32_bf16 v[48:51], v[132:135], v[172:175], v[48:51]
	v_mfma_f32_16x16x32_bf16 v[44:47], v[140:143], v[172:175], v[44:47]
	v_mfma_f32_16x16x32_bf16 v[32:35], v[132:135], v[180:183], v[32:35]
	v_mfma_f32_16x16x32_bf16 v[28:31], v[140:143], v[180:183], v[28:31]
	v_mfma_f32_16x16x32_bf16 v[16:19], v[132:135], v[188:191], v[16:19]
	v_mfma_f32_16x16x32_bf16 v[12:15], v[140:143], v[188:191], v[12:15]
	v_mfma_f32_16x16x32_bf16 v[64:67], v[136:139], v[168:171], v[64:67]
	v_mfma_f32_16x16x32_bf16 v[60:63], v[144:147], v[168:171], v[60:63]
	v_mfma_f32_16x16x32_bf16 v[48:51], v[136:139], v[176:179], v[48:51]
	v_mfma_f32_16x16x32_bf16 v[44:47], v[144:147], v[176:179], v[44:47]
	v_mfma_f32_16x16x32_bf16 v[32:35], v[136:139], v[184:187], v[32:35]
	v_mfma_f32_16x16x32_bf16 v[28:31], v[144:147], v[184:187], v[28:31]
	v_mfma_f32_16x16x32_bf16 v[16:19], v[136:139], v[220:223], v[16:19]
	v_mfma_f32_16x16x32_bf16 v[12:15], v[144:147], v[220:223], v[12:15]
	v_mfma_f32_16x16x32_bf16 v[56:59], v[148:151], v[164:167], v[56:59]
	v_mfma_f32_16x16x32_bf16 v[52:55], v[156:159], v[164:167], v[52:55]
	v_mfma_f32_16x16x32_bf16 v[40:43], v[148:151], v[172:175], v[40:43]
	v_mfma_f32_16x16x32_bf16 v[36:39], v[156:159], v[172:175], v[36:39]
	v_mfma_f32_16x16x32_bf16 v[24:27], v[148:151], v[180:183], v[24:27]
	v_mfma_f32_16x16x32_bf16 v[20:23], v[156:159], v[180:183], v[20:23]
	v_mfma_f32_16x16x32_bf16 v[8:11], v[148:151], v[188:191], v[8:11]
	v_mfma_f32_16x16x32_bf16 v[2:5], v[156:159], v[188:191], v[4:7]
	v_mfma_f32_16x16x32_bf16 v[56:59], v[152:155], v[168:171], v[56:59]
	v_mfma_f32_16x16x32_bf16 v[52:55], v[160:163], v[168:171], v[52:55]
	v_mfma_f32_16x16x32_bf16 v[40:43], v[152:155], v[176:179], v[40:43]
	v_mfma_f32_16x16x32_bf16 v[36:39], v[160:163], v[176:179], v[36:39]
	v_mfma_f32_16x16x32_bf16 v[24:27], v[152:155], v[184:187], v[24:27]
	v_mfma_f32_16x16x32_bf16 v[20:23], v[160:163], v[184:187], v[20:23]
	v_mfma_f32_16x16x32_bf16 v[8:11], v[152:155], v[220:223], v[8:11]
	v_mfma_f32_16x16x32_bf16 v[2:5], v[160:163], v[220:223], v[2:5]
	s_barrier
	s_add_i32 s74, 0, 0x18000
	v_add_u32_e32 v0, s74, v206
	s_add_i32 s75, 0, 0x1c000
	ds_read_b128 v[132:135], v0
	ds_read_b128 v[136:139], v0 offset:1024
	ds_read_b128 v[140:143], v0 offset:2048
	ds_read_b128 v[144:147], v0 offset:3072
	v_add_u32_e32 v0, s75, v206
	ds_read_b128 v[148:151], v0
	ds_read_b128 v[152:155], v0 offset:1024
	ds_read_b128 v[156:159], v0 offset:2048
	ds_read_b128 v[160:163], v0 offset:3072
	s_add_u32 s84, s84, 0x40000
	s_addc_u32 s85, s85, 0
	s_mov_b32 m0, s16
	v_lshl_add_u64 v[6:7], s[84:85], 0, v[214:215]
	ds_read_b128 v[164:167], v238 offset:32768
	ds_read_b128 v[168:171], v238 offset:33792
	ds_read_b128 v[172:175], v238 offset:34816
	ds_read_b128 v[176:179], v238 offset:35840
	ds_read_b128 v[180:183], v238 offset:36864
	ds_read_b128 v[184:187], v238 offset:37888
	ds_read_b128 v[188:191], v238 offset:38912
	ds_read_b128 v[220:223], v238 offset:39936
	global_load_lds_dwordx4 v[6:7], off
	v_lshl_add_u64 v[6:7], s[84:85], 0, v[210:211]
	s_mov_b32 m0, s24
	s_nop 0
	global_load_lds_dwordx4 v[6:7], off
	s_waitcnt vmcnt(8)
	s_waitcnt lgkmcnt(0)
	s_barrier
	s_waitcnt lgkmcnt(0)
	v_mfma_f32_16x16x32_bf16 v[124:127], v[132:135], v[164:167], v[124:127]
	v_mfma_f32_16x16x32_bf16 v[128:131], v[140:143], v[164:167], v[128:131]
	v_mfma_f32_16x16x32_bf16 v[112:115], v[132:135], v[172:175], v[112:115]
	v_mfma_f32_16x16x32_bf16 v[108:111], v[140:143], v[172:175], v[108:111]
	v_mfma_f32_16x16x32_bf16 v[96:99], v[132:135], v[180:183], v[96:99]
	v_mfma_f32_16x16x32_bf16 v[92:95], v[140:143], v[180:183], v[92:95]
	v_mfma_f32_16x16x32_bf16 v[80:83], v[132:135], v[188:191], v[80:83]
	v_mfma_f32_16x16x32_bf16 v[76:79], v[140:143], v[188:191], v[76:79]
	v_mfma_f32_16x16x32_bf16 v[124:127], v[136:139], v[168:171], v[124:127]
	v_mfma_f32_16x16x32_bf16 v[128:131], v[144:147], v[168:171], v[128:131]
	v_mfma_f32_16x16x32_bf16 v[112:115], v[136:139], v[176:179], v[112:115]
	v_mfma_f32_16x16x32_bf16 v[108:111], v[144:147], v[176:179], v[108:111]
	v_mfma_f32_16x16x32_bf16 v[96:99], v[136:139], v[184:187], v[96:99]
	v_mfma_f32_16x16x32_bf16 v[92:95], v[144:147], v[184:187], v[92:95]
	v_mfma_f32_16x16x32_bf16 v[80:83], v[136:139], v[220:223], v[80:83]
	v_mfma_f32_16x16x32_bf16 v[76:79], v[144:147], v[220:223], v[76:79]
	v_mfma_f32_16x16x32_bf16 v[116:119], v[148:151], v[164:167], v[116:119]
	v_mfma_f32_16x16x32_bf16 v[120:123], v[156:159], v[164:167], v[120:123]
	v_mfma_f32_16x16x32_bf16 v[104:107], v[148:151], v[172:175], v[104:107]
	v_mfma_f32_16x16x32_bf16 v[100:103], v[156:159], v[172:175], v[100:103]
	v_mfma_f32_16x16x32_bf16 v[88:91], v[148:151], v[180:183], v[88:91]
	v_mfma_f32_16x16x32_bf16 v[84:87], v[156:159], v[180:183], v[84:87]
	v_mfma_f32_16x16x32_bf16 v[72:75], v[148:151], v[188:191], v[72:75]
	v_mfma_f32_16x16x32_bf16 v[68:71], v[156:159], v[188:191], v[68:71]
	v_mfma_f32_16x16x32_bf16 v[116:119], v[152:155], v[168:171], v[116:119]
	v_mfma_f32_16x16x32_bf16 v[120:123], v[160:163], v[168:171], v[120:123]
	v_mfma_f32_16x16x32_bf16 v[104:107], v[152:155], v[176:179], v[104:107]
	v_mfma_f32_16x16x32_bf16 v[100:103], v[160:163], v[176:179], v[100:103]
	v_mfma_f32_16x16x32_bf16 v[88:91], v[152:155], v[184:187], v[88:91]
	v_mfma_f32_16x16x32_bf16 v[84:87], v[160:163], v[184:187], v[84:87]
	v_mfma_f32_16x16x32_bf16 v[72:75], v[152:155], v[220:223], v[72:75]
	v_mfma_f32_16x16x32_bf16 v[68:71], v[160:163], v[220:223], v[68:71]
	s_barrier
; #define PG8_STAGE(bufoff, gbase, voff) do { _Pragma("unroll") for (int _i = 0; _i < 2; ++_i) \
;         __builtin_amdgcn_global_load_lds((const unsigned*)((const char*)(gbase) + (voff)[_i]), (LAS unsigned*)(lds + (bufoff) + ldsw + _i * 8192), 16, 0, 0); } while (0)
; #define PG8_LDA(dst, b, h) do { _Pragma("unroll") for (int m = 0; m < 4; ++m) _Pragma("unroll") for (int k = 0; k < 2; ++k) dst[m][k] = *(const LAS bf16x8*)(lds + PG8_SA(b, h) + aoff + m * 2048 + k * 1024); } while (0)
; #define PG8_MMA(ai, bj, At, Bt) do { __builtin_amdgcn_s_setprio(1); _Pragma("unroll") for (int m = 0; m < 4; ++m) _Pragma("unroll") for (int n = 0; n < 2; ++n) _Pragma("unroll") for (int k = 0; k < 2; ++k) \
;         acc[ai][bj][m][n] = __builtin_amdgcn_mfma_f32_16x16x32_bf16(Bt[n][k], At[m][k], acc[ai][bj][m][n], 0, 0, 0); __builtin_amdgcn_s_setprio(0); } while (0)
; #define PG8_WAIT_V(n) asm volatile("s_waitcnt vmcnt(" #n ")" ::: "memory")
; #define PG8_WAIT_L(n) asm volatile("s_waitcnt lgkmcnt(" #n ")" ::: "memory")
; #define PG8_BAR __builtin_amdgcn_s_barrier()
; #define PG8_SCHED __builtin_amdgcn_sched_barrier(0)
; template <class Epi, class Sched>
; __device__ __forceinline__ void gemm_phase(LAS unsigned char* lds, const Gemm g, const Sched& S, const Epi& E) {
;     ...
;             if constexpr (Epi::MIDK) { if (t == (nt >> 1)) { int fr_ = fr, fq_ = fq; asm volatile("" : "+v"(fr_), "+v"(fq_)); E.mid(acc, cur, wr, wc, fr_, fq_); } }
;     ...
;             PG8_LDA(At, 1, 1); PG8_STAGE(PG8_SB(1, 0), b3, voffB); PG8_STAGE(PG8_SB(1, 1), b3 + hsB, voffB); PG8_STAGE(PG8_SA(1, 0), a3, voffA);
;             PG8_WAIT_V(8); PG8_WAIT_L(0); PG8_BAR; PG8_MMA(1, 0, At, B0); PG8_MMA(1, 1, At, B1); PG8_BAR; PG8_SCHED;
;         }
	s_add_i32 s74, s74, s7
	v_lshl_add_u64 v[6:7], v[224:225], 0, s[18:19]
	s_mov_b32 m0, s74
	ds_read_b128 v[164:167], v238 offset:49152
	ds_read_b128 v[168:171], v238 offset:50176
	ds_read_b128 v[172:175], v238 offset:51200
	ds_read_b128 v[176:179], v238 offset:52224
	ds_read_b128 v[180:183], v238 offset:53248
	ds_read_b128 v[184:187], v238 offset:54272
	ds_read_b128 v[188:191], v238 offset:55296
	ds_read_b128 v[220:223], v238 offset:56320
	global_load_lds_dwordx4 v[6:7], off
	s_add_i32 m0, s74, 0x2000
	s_add_u32 s76, s76, 0x40080
	v_lshl_add_u64 v[6:7], v[226:227], 0, s[18:19]
	s_addc_u32 s77, s77, 0
	s_add_i32 s74, s75, s7
	global_load_lds_dwordx4 v[6:7], off
	v_lshl_add_u64 v[6:7], s[76:77], 0, v[212:213]
	s_mov_b32 m0, s74
	s_nop 0
	global_load_lds_dwordx4 v[6:7], off
	v_lshl_add_u64 v[6:7], s[76:77], 0, v[208:209]
	s_add_i32 m0, s74, 0x2000
	s_nop 0
	global_load_lds_dwordx4 v[6:7], off
	v_lshl_add_u64 v[6:7], v[228:229], 0, s[18:19]
	s_mov_b32 m0, s56
	s_nop 0
	global_load_lds_dwordx4 v[6:7], off
	v_lshl_add_u64 v[6:7], v[230:231], 0, s[18:19]
	s_mov_b32 m0, s57
	s_nop 0
	global_load_lds_dwordx4 v[6:7], off
	s_waitcnt vmcnt(8)
	s_waitcnt lgkmcnt(0)
	s_barrier
	s_waitcnt lgkmcnt(0)
	v_mfma_f32_16x16x32_bf16 v[64:67], v[132:135], v[164:167], v[64:67]
	v_mfma_f32_16x16x32_bf16 v[60:63], v[140:143], v[164:167], v[60:63]
	v_mfma_f32_16x16x32_bf16 v[48:51], v[132:135], v[172:175], v[48:51]
	v_mfma_f32_16x16x32_bf16 v[44:47], v[140:143], v[172:175], v[44:47]
	v_mfma_f32_16x16x32_bf16 v[32:35], v[132:135], v[180:183], v[32:35]
	v_mfma_f32_16x16x32_bf16 v[28:31], v[140:143], v[180:183], v[28:31]
	v_mfma_f32_16x16x32_bf16 v[16:19], v[132:135], v[188:191], v[16:19]
	v_mfma_f32_16x16x32_bf16 v[12:15], v[140:143], v[188:191], v[12:15]
	v_mfma_f32_16x16x32_bf16 v[64:67], v[136:139], v[168:171], v[64:67]
	v_mfma_f32_16x16x32_bf16 v[60:63], v[144:147], v[168:171], v[60:63]
	v_mfma_f32_16x16x32_bf16 v[48:51], v[136:139], v[176:179], v[48:51]
	v_mfma_f32_16x16x32_bf16 v[44:47], v[144:147], v[176:179], v[44:47]
	v_mfma_f32_16x16x32_bf16 v[32:35], v[136:139], v[184:187], v[32:35]
	v_mfma_f32_16x16x32_bf16 v[28:31], v[144:147], v[184:187], v[28:31]
	v_mfma_f32_16x16x32_bf16 v[16:19], v[136:139], v[220:223], v[16:19]
	v_mfma_f32_16x16x32_bf16 v[12:15], v[144:147], v[220:223], v[12:15]
	v_mfma_f32_16x16x32_bf16 v[56:59], v[148:151], v[164:167], v[56:59]
	v_mfma_f32_16x16x32_bf16 v[52:55], v[156:159], v[164:167], v[52:55]
	v_mfma_f32_16x16x32_bf16 v[40:43], v[148:151], v[172:175], v[40:43]
	v_mfma_f32_16x16x32_bf16 v[36:39], v[156:159], v[172:175], v[36:39]
	v_mfma_f32_16x16x32_bf16 v[24:27], v[148:151], v[180:183], v[24:27]
	v_mfma_f32_16x16x32_bf16 v[20:23], v[156:159], v[180:183], v[20:23]
	v_mfma_f32_16x16x32_bf16 v[6:9], v[148:151], v[188:191], v[8:11]
	v_mfma_f32_16x16x32_bf16 v[2:5], v[156:159], v[188:191], v[2:5]
	v_mfma_f32_16x16x32_bf16 v[56:59], v[152:155], v[168:171], v[56:59]
	v_mfma_f32_16x16x32_bf16 v[52:55], v[160:163], v[168:171], v[52:55]
	v_mfma_f32_16x16x32_bf16 v[40:43], v[152:155], v[176:179], v[40:43]
	v_mfma_f32_16x16x32_bf16 v[36:39], v[160:163], v[176:179], v[36:39]
	v_mfma_f32_16x16x32_bf16 v[24:27], v[152:155], v[184:187], v[24:27]
	v_mfma_f32_16x16x32_bf16 v[20:23], v[160:163], v[184:187], v[20:23]
	v_mfma_f32_16x16x32_bf16 v[8:11], v[152:155], v[220:223], v[6:9]
	v_mfma_f32_16x16x32_bf16 v[4:7], v[160:163], v[220:223], v[2:5]
	s_barrier
	s_add_u32 s50, s50, 0x100
	s_addc_u32 s51, s51, 0
	s_add_u32 s0, s0, 0x100
	s_addc_u32 s1, s1, 0
	s_cmp_ge_i32 s96, s26
	s_cbranch_scc1 .LBB0_839
	s_mov_b32 s76, s96
	s_cmp_lg_u32 s73, s76
	s_cbranch_scc0 .LBB0_836
	s_branch .LBB0_837

; #define PG8_STAGE(bufoff, gbase, voff) do { _Pragma("unroll") for (int _i = 0; _i < 2; ++_i) \
;         __builtin_amdgcn_global_load_lds((const unsigned*)((const char*)(gbase) + (voff)[_i]), (LAS unsigned*)(lds + (bufoff) + ldsw + _i * 8192), 16, 0, 0); } while (0)
; #define PG8_LDA(dst, b, h) do { _Pragma("unroll") for (int m = 0; m < 4; ++m) _Pragma("unroll") for (int k = 0; k < 2; ++k) dst[m][k] = *(const LAS bf16x8*)(lds + PG8_SA(b, h) + aoff + m * 2048 + k * 1024); } while (0)
; #define PG8_LDB(dst, b, h) do { _Pragma("unroll") for (int n = 0; n < 2; ++n) _Pragma("unroll") for (int k = 0; k < 2; ++k) dst[n][k] = *(const LAS bf16x8*)(lds + PG8_SB(b, h) + boff + n * 2048 + k * 1024); } while (0)
; #define PG8_MMA(ai, bj, At, Bt) do { __builtin_amdgcn_s_setprio(1); _Pragma("unroll") for (int m = 0; m < 4; ++m) _Pragma("unroll") for (int n = 0; n < 2; ++n) _Pragma("unroll") for (int k = 0; k < 2; ++k) \
;         acc[ai][bj][m][n] = __builtin_amdgcn_mfma_f32_16x16x32_bf16(Bt[n][k], At[m][k], acc[ai][bj][m][n], 0, 0, 0); __builtin_amdgcn_s_setprio(0); } while (0)
; #define PG8_WAIT_V(n) asm volatile("s_waitcnt vmcnt(" #n ")" ::: "memory")
; #define PG8_WAIT_L(n) asm volatile("s_waitcnt lgkmcnt(" #n ")" ::: "memory")
; template <class Epi, class Sched>
; __device__ __forceinline__ void gemm_phase(LAS unsigned char* lds, const Gemm g, const Sched& S, const Epi& E) {
;     ...
;             const bool last = (t == nt - 2);
;             const char* a1 = cA + (size_t)(t + 1) * kstep;
;             const char* a2 = last ? nA : cA + (size_t)(t + 2) * kstep; const char* b2 = last ? nB : cB + (size_t)(t + 2) * kstep;
;             const char* a3 = a2 + kstep; const char* b3 = b2 + kstep;
;             if constexpr (Epi::MIDK) { if (t == (nt >> 1)) { int fr_ = fr, fq_ = fq; asm volatile("" : "+v"(fr_), "+v"(fq_)); E.mid(acc, cur, wr, wc, fr_, fq_); } }
;             PG8_LDB(B0, 0, 0); PG8_LDB(B1, 0, 1); PG8_SCHED; PG8_LDA(At, 0, 0); PG8_STAGE(PG8_SA(1, 1), a1 + hsA, voffA);
;             PG8_WAIT_V(8); PG8_WAIT_L(0); PG8_BAR; PG8_MMA(0, 0, At, B0); PG8_MMA(0, 1, At, B1); PG8_BAR; PG8_SCHED;
;             PG8_LDA(At, 0, 1); PG8_STAGE(PG8_SB(0, 0), b2, voffB); PG8_STAGE(PG8_SB(0, 1), b2 + hsB, voffB); PG8_STAGE(PG8_SA(0, 0), a2, voffA);
;             PG8_WAIT_V(8); PG8_WAIT_L(0); PG8_BAR; PG8_MMA(1, 0, At, B0); PG8_MMA(1, 1, At, B1); PG8_BAR; PG8_SCHED;
.LBB0_912:
	s_add_i32 s96, s50, 2
	s_add_u32 s51, s0, 0xfffc0080
	s_addc_u32 s74, s1, -1
	s_add_i32 s75, 0, 0x10000
	s_cmp_eq_u32 s73, s50
	s_cselect_b32 s77, s39, s74
	s_cselect_b32 s76, s41, s51
	s_cselect_b32 s51, s82, s85
	s_cselect_b32 s50, s83, s84
	s_add_i32 s74, 0, 0x14000
	v_add_u32_e32 v142, s75, v184
	v_add_u32_e32 v168, s74, v184
	ds_read_b128 v[130:133], v142
	ds_read_b128 v[134:137], v142 offset:1024
	ds_read_b128 v[138:141], v142 offset:2048
	ds_read_b128 v[142:145], v142 offset:3072
	ds_read_b128 v[146:149], v168
	ds_read_b128 v[150:153], v168 offset:1024
	ds_read_b128 v[164:167], v168 offset:2048
	ds_read_b128 v[168:171], v168 offset:3072
	v_lshl_add_u64 v[180:181], s[0:1], 0, v[160:161]
	s_add_i32 m0, s11, 0xc000
	ds_read_b128 v[172:175], v185
	ds_read_b128 v[176:179], v185 offset:1024
	ds_read_b128 v[186:189], v185 offset:2048
	ds_read_b128 v[208:211], v185 offset:3072
	ds_read_b128 v[212:215], v185 offset:4096
	ds_read_b128 v[216:219], v185 offset:5120
	ds_read_b128 v[220:223], v185 offset:6144
	ds_read_b128 v[224:227], v185 offset:7168
	global_load_lds_dwordx4 v[180:181], off
	v_lshl_add_u64 v[180:181], s[0:1], 0, v[162:163]
	s_add_i32 m0, s11, 0xe000
	s_nop 0
	global_load_lds_dwordx4 v[180:181], off
	s_waitcnt vmcnt(8)
	s_waitcnt lgkmcnt(0)
	s_barrier
	s_waitcnt lgkmcnt(0)
	v_mfma_f32_16x16x32_bf16 v[122:125], v[130:133], v[172:175], v[122:125]
	v_mfma_f32_16x16x32_bf16 v[126:129], v[138:141], v[172:175], v[126:129]
	v_mfma_f32_16x16x32_bf16 v[110:113], v[130:133], v[186:189], v[110:113]
	v_mfma_f32_16x16x32_bf16 v[106:109], v[138:141], v[186:189], v[106:109]
	v_mfma_f32_16x16x32_bf16 v[94:97], v[130:133], v[212:215], v[94:97]
	v_mfma_f32_16x16x32_bf16 v[90:93], v[138:141], v[212:215], v[90:93]
	v_mfma_f32_16x16x32_bf16 v[78:81], v[130:133], v[220:223], v[78:81]
	v_mfma_f32_16x16x32_bf16 v[74:77], v[138:141], v[220:223], v[74:77]
	v_mfma_f32_16x16x32_bf16 v[122:125], v[134:137], v[176:179], v[122:125]
	v_mfma_f32_16x16x32_bf16 v[126:129], v[142:145], v[176:179], v[126:129]
	v_mfma_f32_16x16x32_bf16 v[110:113], v[134:137], v[208:211], v[110:113]
	v_mfma_f32_16x16x32_bf16 v[106:109], v[142:145], v[208:211], v[106:109]
	v_mfma_f32_16x16x32_bf16 v[94:97], v[134:137], v[216:219], v[94:97]
	v_mfma_f32_16x16x32_bf16 v[90:93], v[142:145], v[216:219], v[90:93]
	v_mfma_f32_16x16x32_bf16 v[78:81], v[134:137], v[224:227], v[78:81]
	v_mfma_f32_16x16x32_bf16 v[74:77], v[142:145], v[224:227], v[74:77]
	v_mfma_f32_16x16x32_bf16 v[118:121], v[146:149], v[172:175], v[118:121]
	v_mfma_f32_16x16x32_bf16 v[114:117], v[164:167], v[172:175], v[114:117]
	v_mfma_f32_16x16x32_bf16 v[102:105], v[146:149], v[186:189], v[102:105]
	v_mfma_f32_16x16x32_bf16 v[98:101], v[164:167], v[186:189], v[98:101]
	v_mfma_f32_16x16x32_bf16 v[86:89], v[146:149], v[212:215], v[86:89]
	v_mfma_f32_16x16x32_bf16 v[82:85], v[164:167], v[212:215], v[82:85]
	v_mfma_f32_16x16x32_bf16 v[70:73], v[146:149], v[220:223], v[70:73]
	v_mfma_f32_16x16x32_bf16 v[66:69], v[164:167], v[220:223], v[66:69]
	v_mfma_f32_16x16x32_bf16 v[118:121], v[150:153], v[176:179], v[118:121]
	v_mfma_f32_16x16x32_bf16 v[114:117], v[168:171], v[176:179], v[114:117]
	v_mfma_f32_16x16x32_bf16 v[102:105], v[150:153], v[208:211], v[102:105]
	v_mfma_f32_16x16x32_bf16 v[98:101], v[168:171], v[208:211], v[98:101]
	v_mfma_f32_16x16x32_bf16 v[86:89], v[150:153], v[216:219], v[86:89]
	v_mfma_f32_16x16x32_bf16 v[82:85], v[168:171], v[216:219], v[82:85]
	v_mfma_f32_16x16x32_bf16 v[70:73], v[150:153], v[224:227], v[70:73]
	v_mfma_f32_16x16x32_bf16 v[66:69], v[168:171], v[224:227], v[66:69]
	s_barrier
	s_add_i32 s75, s75, s7
	v_lshl_add_u64 v[180:181], s[50:51], 0, v[0:1]
	s_mov_b32 m0, s75
	ds_read_b128 v[172:175], v185 offset:16384
	ds_read_b128 v[176:179], v185 offset:17408
	ds_read_b128 v[186:189], v185 offset:18432
	ds_read_b128 v[208:211], v185 offset:19456
	ds_read_b128 v[212:215], v185 offset:20480
	ds_read_b128 v[216:219], v185 offset:21504
	ds_read_b128 v[220:223], v185 offset:22528
	ds_read_b128 v[224:227], v185 offset:23552
	global_load_lds_dwordx4 v[180:181], off
	s_add_i32 m0, s75, 0x2000
	s_add_u32 vcc_lo, s50, 0x40000
	v_lshl_add_u64 v[190:191], s[50:51], 0, v[154:155]
	s_addc_u32 vcc_hi, s51, 0
	s_add_i32 s74, s74, s7
	global_load_lds_dwordx4 v[190:191], off
	v_lshl_add_u64 v[228:229], vcc, 0, v[0:1]
	s_mov_b32 m0, s74
	v_lshl_add_u64 v[230:231], s[76:77], 0, v[156:157]
	global_load_lds_dwordx4 v[228:229], off
	v_lshl_add_u64 v[228:229], vcc, 0, v[154:155]
	s_add_i32 m0, s74, 0x2000
	s_nop 0
	global_load_lds_dwordx4 v[228:229], off
	v_lshl_add_u64 v[228:229], s[76:77], 0, v[158:159]
	s_mov_b32 m0, s11
	s_nop 0
	global_load_lds_dwordx4 v[228:229], off
	s_mov_b32 m0, s12
	s_nop 0
	global_load_lds_dwordx4 v[230:231], off
	s_waitcnt vmcnt(8)
	s_waitcnt lgkmcnt(0)
	s_barrier
; #define PG8_STAGE(bufoff, gbase, voff) do { _Pragma("unroll") for (int _i = 0; _i < 2; ++_i) \
;         __builtin_amdgcn_global_load_lds((const unsigned*)((const char*)(gbase) + (voff)[_i]), (LAS unsigned*)(lds + (bufoff) + ldsw + _i * 8192), 16, 0, 0); } while (0)
; #define PG8_LDA(dst, b, h) do { _Pragma("unroll") for (int m = 0; m < 4; ++m) _Pragma("unroll") for (int k = 0; k < 2; ++k) dst[m][k] = *(const LAS bf16x8*)(lds + PG8_SA(b, h) + aoff + m * 2048 + k * 1024); } while (0)
; #define PG8_LDB(dst, b, h) do { _Pragma("unroll") for (int n = 0; n < 2; ++n) _Pragma("unroll") for (int k = 0; k < 2; ++k) dst[n][k] = *(const LAS bf16x8*)(lds + PG8_SB(b, h) + boff + n * 2048 + k * 1024); } while (0)
; #define PG8_MMA(ai, bj, At, Bt) do { __builtin_amdgcn_s_setprio(1); _Pragma("unroll") for (int m = 0; m < 4; ++m) _Pragma("unroll") for (int n = 0; n < 2; ++n) _Pragma("unroll") for (int k = 0; k < 2; ++k) \
;         acc[ai][bj][m][n] = __builtin_amdgcn_mfma_f32_16x16x32_bf16(Bt[n][k], At[m][k], acc[ai][bj][m][n], 0, 0, 0); __builtin_amdgcn_s_setprio(0); } while (0)
; #define PG8_WAIT_V(n) asm volatile("s_waitcnt vmcnt(" #n ")" ::: "memory")
; #define PG8_WAIT_L(n) asm volatile("s_waitcnt lgkmcnt(" #n ")" ::: "memory")
; #define PG8_BAR __builtin_amdgcn_s_barrier()
; #define PG8_SCHED __builtin_amdgcn_sched_barrier(0)
; template <class Epi, class Sched>
; __device__ __forceinline__ void gemm_phase(LAS unsigned char* lds, const Gemm g, const Sched& S, const Epi& E) {
;     ...
;             PG8_WAIT_V(8); PG8_WAIT_L(0); PG8_BAR; PG8_MMA(1, 0, At, B0); PG8_MMA(1, 1, At, B1); PG8_BAR; PG8_SCHED;
;             PG8_LDB(B0, 1, 0); PG8_LDB(B1, 1, 1); PG8_SCHED; PG8_LDA(At, 1, 0); PG8_STAGE(PG8_SA(0, 1), a2 + hsA, voffA);
;             PG8_WAIT_V(8); PG8_WAIT_L(0); PG8_BAR; PG8_MMA(0, 0, At, B0); PG8_MMA(0, 1, At, B1); PG8_BAR; PG8_SCHED;
	s_waitcnt lgkmcnt(0)
	v_mfma_f32_16x16x32_bf16 v[62:65], v[130:133], v[172:175], v[62:65]
	v_mfma_f32_16x16x32_bf16 v[58:61], v[138:141], v[172:175], v[58:61]
	v_mfma_f32_16x16x32_bf16 v[46:49], v[130:133], v[186:189], v[46:49]
	v_mfma_f32_16x16x32_bf16 v[42:45], v[138:141], v[186:189], v[42:45]
	v_mfma_f32_16x16x32_bf16 v[30:33], v[130:133], v[212:215], v[30:33]
	v_mfma_f32_16x16x32_bf16 v[26:29], v[138:141], v[212:215], v[26:29]
	v_mfma_f32_16x16x32_bf16 v[14:17], v[130:133], v[220:223], v[14:17]
	v_mfma_f32_16x16x32_bf16 v[10:13], v[138:141], v[220:223], v[10:13]
	v_mfma_f32_16x16x32_bf16 v[62:65], v[134:137], v[176:179], v[62:65]
	v_mfma_f32_16x16x32_bf16 v[58:61], v[142:145], v[176:179], v[58:61]
	v_mfma_f32_16x16x32_bf16 v[46:49], v[134:137], v[208:211], v[46:49]
	v_mfma_f32_16x16x32_bf16 v[42:45], v[142:145], v[208:211], v[42:45]
	v_mfma_f32_16x16x32_bf16 v[30:33], v[134:137], v[216:219], v[30:33]
	v_mfma_f32_16x16x32_bf16 v[26:29], v[142:145], v[216:219], v[26:29]
	v_mfma_f32_16x16x32_bf16 v[14:17], v[134:137], v[224:227], v[14:17]
	v_mfma_f32_16x16x32_bf16 v[10:13], v[142:145], v[224:227], v[10:13]
	v_mfma_f32_16x16x32_bf16 v[54:57], v[146:149], v[172:175], v[54:57]
	v_mfma_f32_16x16x32_bf16 v[50:53], v[164:167], v[172:175], v[50:53]
	v_mfma_f32_16x16x32_bf16 v[38:41], v[146:149], v[186:189], v[38:41]
	v_mfma_f32_16x16x32_bf16 v[34:37], v[164:167], v[186:189], v[34:37]
	v_mfma_f32_16x16x32_bf16 v[22:25], v[146:149], v[212:215], v[22:25]
	v_mfma_f32_16x16x32_bf16 v[18:21], v[164:167], v[212:215], v[18:21]
	v_mfma_f32_16x16x32_bf16 v[6:9], v[146:149], v[220:223], v[6:9]
	v_mfma_f32_16x16x32_bf16 v[2:5], v[164:167], v[220:223], v[2:5]
	v_mfma_f32_16x16x32_bf16 v[54:57], v[150:153], v[176:179], v[54:57]
	v_mfma_f32_16x16x32_bf16 v[50:53], v[168:171], v[176:179], v[50:53]
	v_mfma_f32_16x16x32_bf16 v[38:41], v[150:153], v[208:211], v[38:41]
	v_mfma_f32_16x16x32_bf16 v[34:37], v[168:171], v[208:211], v[34:37]
	v_mfma_f32_16x16x32_bf16 v[22:25], v[150:153], v[216:219], v[22:25]
	v_mfma_f32_16x16x32_bf16 v[18:21], v[168:171], v[216:219], v[18:21]
	v_mfma_f32_16x16x32_bf16 v[6:9], v[150:153], v[224:227], v[6:9]
	v_mfma_f32_16x16x32_bf16 v[2:5], v[168:171], v[224:227], v[2:5]
	s_barrier
	s_add_i32 s74, 0, 0x18000
	s_add_i32 s75, 0, 0x1c000
	v_add_u32_e32 v142, s74, v184
	v_add_u32_e32 v168, s75, v184
	ds_read_b128 v[130:133], v142
	ds_read_b128 v[134:137], v142 offset:1024
	ds_read_b128 v[138:141], v142 offset:2048
	ds_read_b128 v[142:145], v142 offset:3072
	ds_read_b128 v[146:149], v168
	ds_read_b128 v[150:153], v168 offset:1024
	ds_read_b128 v[164:167], v168 offset:2048
	ds_read_b128 v[168:171], v168 offset:3072
	s_add_u32 s76, s76, 0x40000
	s_addc_u32 s77, s77, 0
	s_mov_b32 m0, s16
	v_lshl_add_u64 v[232:233], s[76:77], 0, v[158:159]
	ds_read_b128 v[172:175], v185 offset:32768
	ds_read_b128 v[176:179], v185 offset:33792
	ds_read_b128 v[186:189], v185 offset:34816
	ds_read_b128 v[208:211], v185 offset:35840
	ds_read_b128 v[212:215], v185 offset:36864
	ds_read_b128 v[216:219], v185 offset:37888
	ds_read_b128 v[220:223], v185 offset:38912
	ds_read_b128 v[224:227], v185 offset:39936
	global_load_lds_dwordx4 v[232:233], off
	v_lshl_add_u64 v[232:233], s[76:77], 0, v[156:157]
	s_mov_b32 m0, s24
	s_nop 0
	global_load_lds_dwordx4 v[232:233], off
	s_waitcnt vmcnt(8)
	s_waitcnt lgkmcnt(0)
	s_barrier
	s_waitcnt lgkmcnt(0)
	v_mfma_f32_16x16x32_bf16 v[122:125], v[130:133], v[172:175], v[122:125]
	v_mfma_f32_16x16x32_bf16 v[126:129], v[138:141], v[172:175], v[126:129]
	v_mfma_f32_16x16x32_bf16 v[110:113], v[130:133], v[186:189], v[110:113]
	v_mfma_f32_16x16x32_bf16 v[106:109], v[138:141], v[186:189], v[106:109]
	v_mfma_f32_16x16x32_bf16 v[94:97], v[130:133], v[212:215], v[94:97]
	v_mfma_f32_16x16x32_bf16 v[90:93], v[138:141], v[212:215], v[90:93]
	v_mfma_f32_16x16x32_bf16 v[78:81], v[130:133], v[220:223], v[78:81]
	v_mfma_f32_16x16x32_bf16 v[74:77], v[138:141], v[220:223], v[74:77]
	v_mfma_f32_16x16x32_bf16 v[122:125], v[134:137], v[176:179], v[122:125]
	v_mfma_f32_16x16x32_bf16 v[126:129], v[142:145], v[176:179], v[126:129]
	v_mfma_f32_16x16x32_bf16 v[110:113], v[134:137], v[208:211], v[110:113]
	v_mfma_f32_16x16x32_bf16 v[106:109], v[142:145], v[208:211], v[106:109]
	v_mfma_f32_16x16x32_bf16 v[94:97], v[134:137], v[216:219], v[94:97]
	v_mfma_f32_16x16x32_bf16 v[90:93], v[142:145], v[216:219], v[90:93]
	v_mfma_f32_16x16x32_bf16 v[78:81], v[134:137], v[224:227], v[78:81]
	v_mfma_f32_16x16x32_bf16 v[74:77], v[142:145], v[224:227], v[74:77]
	v_mfma_f32_16x16x32_bf16 v[118:121], v[146:149], v[172:175], v[118:121]
	v_mfma_f32_16x16x32_bf16 v[114:117], v[164:167], v[172:175], v[114:117]
	v_mfma_f32_16x16x32_bf16 v[102:105], v[146:149], v[186:189], v[102:105]
	v_mfma_f32_16x16x32_bf16 v[98:101], v[164:167], v[186:189], v[98:101]
	v_mfma_f32_16x16x32_bf16 v[86:89], v[146:149], v[212:215], v[86:89]
	v_mfma_f32_16x16x32_bf16 v[82:85], v[164:167], v[212:215], v[82:85]
	v_mfma_f32_16x16x32_bf16 v[70:73], v[146:149], v[220:223], v[70:73]
	v_mfma_f32_16x16x32_bf16 v[66:69], v[164:167], v[220:223], v[66:69]
	v_mfma_f32_16x16x32_bf16 v[118:121], v[150:153], v[176:179], v[118:121]
	v_mfma_f32_16x16x32_bf16 v[114:117], v[168:171], v[176:179], v[114:117]
	v_mfma_f32_16x16x32_bf16 v[102:105], v[150:153], v[208:211], v[102:105]
	v_mfma_f32_16x16x32_bf16 v[98:101], v[168:171], v[208:211], v[98:101]
	v_mfma_f32_16x16x32_bf16 v[86:89], v[150:153], v[216:219], v[86:89]
	v_mfma_f32_16x16x32_bf16 v[82:85], v[168:171], v[216:219], v[82:85]
	v_mfma_f32_16x16x32_bf16 v[70:73], v[150:153], v[224:227], v[70:73]
	v_mfma_f32_16x16x32_bf16 v[66:69], v[168:171], v[224:227], v[66:69]
	s_barrier
; #define PG8_STAGE(bufoff, gbase, voff) do { _Pragma("unroll") for (int _i = 0; _i < 2; ++_i) \
;         __builtin_amdgcn_global_load_lds((const unsigned*)((const char*)(gbase) + (voff)[_i]), (LAS unsigned*)(lds + (bufoff) + ldsw + _i * 8192), 16, 0, 0); } while (0)
; #define PG8_LDA(dst, b, h) do { _Pragma("unroll") for (int m = 0; m < 4; ++m) _Pragma("unroll") for (int k = 0; k < 2; ++k) dst[m][k] = *(const LAS bf16x8*)(lds + PG8_SA(b, h) + aoff + m * 2048 + k * 1024); } while (0)
; #define PG8_MMA(ai, bj, At, Bt) do { __builtin_amdgcn_s_setprio(1); _Pragma("unroll") for (int m = 0; m < 4; ++m) _Pragma("unroll") for (int n = 0; n < 2; ++n) _Pragma("unroll") for (int k = 0; k < 2; ++k) \
;         acc[ai][bj][m][n] = __builtin_amdgcn_mfma_f32_16x16x32_bf16(Bt[n][k], At[m][k], acc[ai][bj][m][n], 0, 0, 0); __builtin_amdgcn_s_setprio(0); } while (0)
; #define PG8_WAIT_V(n) asm volatile("s_waitcnt vmcnt(" #n ")" ::: "memory")
; #define PG8_WAIT_L(n) asm volatile("s_waitcnt lgkmcnt(" #n ")" ::: "memory")
; #define PG8_BAR __builtin_amdgcn_s_barrier()
; #define PG8_SCHED __builtin_amdgcn_sched_barrier(0)
; template <class Epi, class Sched>
; __device__ __forceinline__ void gemm_phase(LAS unsigned char* lds, const Gemm g, const Sched& S, const Epi& E) {
;     ...
;             PG8_LDA(At, 1, 1); PG8_STAGE(PG8_SB(1, 0), b3, voffB); PG8_STAGE(PG8_SB(1, 1), b3 + hsB, voffB); PG8_STAGE(PG8_SA(1, 0), a3, voffA);
;             PG8_WAIT_V(8); PG8_WAIT_L(0); PG8_BAR; PG8_MMA(1, 0, At, B0); PG8_MMA(1, 1, At, B1); PG8_BAR; PG8_SCHED;
;         }
	s_add_i32 s74, s74, s7
	v_lshl_add_u64 v[180:181], v[180:181], 0, s[18:19]
	s_mov_b32 m0, s74
	ds_read_b128 v[172:175], v185 offset:49152
	ds_read_b128 v[176:179], v185 offset:50176
	ds_read_b128 v[186:189], v185 offset:51200
	ds_read_b128 v[208:211], v185 offset:52224
	ds_read_b128 v[212:215], v185 offset:53248
	ds_read_b128 v[216:219], v185 offset:54272
	ds_read_b128 v[220:223], v185 offset:55296
	ds_read_b128 v[224:227], v185 offset:56320
	global_load_lds_dwordx4 v[180:181], off
	s_add_i32 m0, s74, 0x2000
	s_add_u32 s50, s50, 0x40080
	v_lshl_add_u64 v[180:181], v[190:191], 0, s[18:19]
	s_addc_u32 s51, s51, 0
	s_add_i32 s74, s75, s7
	global_load_lds_dwordx4 v[180:181], off
	v_lshl_add_u64 v[180:181], s[50:51], 0, v[0:1]
	s_mov_b32 m0, s74
	s_nop 0
	global_load_lds_dwordx4 v[180:181], off
	v_lshl_add_u64 v[180:181], s[50:51], 0, v[154:155]
	s_add_i32 m0, s74, 0x2000
	s_nop 0
	global_load_lds_dwordx4 v[180:181], off
	v_lshl_add_u64 v[180:181], v[228:229], 0, s[18:19]
	s_mov_b32 m0, s57
	s_nop 0
	global_load_lds_dwordx4 v[180:181], off
	v_lshl_add_u64 v[180:181], v[230:231], 0, s[18:19]
	s_mov_b32 m0, s64
	s_nop 0
	global_load_lds_dwordx4 v[180:181], off
	s_waitcnt vmcnt(8)
	s_waitcnt lgkmcnt(0)
	s_barrier
	s_waitcnt lgkmcnt(0)
	v_mfma_f32_16x16x32_bf16 v[62:65], v[130:133], v[172:175], v[62:65]
	v_mfma_f32_16x16x32_bf16 v[58:61], v[138:141], v[172:175], v[58:61]
	v_mfma_f32_16x16x32_bf16 v[46:49], v[130:133], v[186:189], v[46:49]
	v_mfma_f32_16x16x32_bf16 v[42:45], v[138:141], v[186:189], v[42:45]
	v_mfma_f32_16x16x32_bf16 v[30:33], v[130:133], v[212:215], v[30:33]
	v_mfma_f32_16x16x32_bf16 v[26:29], v[138:141], v[212:215], v[26:29]
	v_mfma_f32_16x16x32_bf16 v[14:17], v[130:133], v[220:223], v[14:17]
	v_mfma_f32_16x16x32_bf16 v[10:13], v[138:141], v[220:223], v[10:13]
	v_mfma_f32_16x16x32_bf16 v[62:65], v[134:137], v[176:179], v[62:65]
	v_mfma_f32_16x16x32_bf16 v[58:61], v[142:145], v[176:179], v[58:61]
	v_mfma_f32_16x16x32_bf16 v[46:49], v[134:137], v[208:211], v[46:49]
	v_mfma_f32_16x16x32_bf16 v[42:45], v[142:145], v[208:211], v[42:45]
	v_mfma_f32_16x16x32_bf16 v[30:33], v[134:137], v[216:219], v[30:33]
	v_mfma_f32_16x16x32_bf16 v[26:29], v[142:145], v[216:219], v[26:29]
	v_mfma_f32_16x16x32_bf16 v[14:17], v[134:137], v[224:227], v[14:17]
	v_mfma_f32_16x16x32_bf16 v[10:13], v[142:145], v[224:227], v[10:13]
	v_mfma_f32_16x16x32_bf16 v[54:57], v[146:149], v[172:175], v[54:57]
	v_mfma_f32_16x16x32_bf16 v[50:53], v[164:167], v[172:175], v[50:53]
	v_mfma_f32_16x16x32_bf16 v[38:41], v[146:149], v[186:189], v[38:41]
	v_mfma_f32_16x16x32_bf16 v[34:37], v[164:167], v[186:189], v[34:37]
	v_mfma_f32_16x16x32_bf16 v[22:25], v[146:149], v[212:215], v[22:25]
	v_mfma_f32_16x16x32_bf16 v[18:21], v[164:167], v[212:215], v[18:21]
	v_mfma_f32_16x16x32_bf16 v[6:9], v[146:149], v[220:223], v[6:9]
	v_mfma_f32_16x16x32_bf16 v[2:5], v[164:167], v[220:223], v[2:5]
	v_mfma_f32_16x16x32_bf16 v[54:57], v[150:153], v[176:179], v[54:57]
	v_mfma_f32_16x16x32_bf16 v[50:53], v[168:171], v[176:179], v[50:53]
	v_mfma_f32_16x16x32_bf16 v[38:41], v[150:153], v[208:211], v[38:41]
	v_mfma_f32_16x16x32_bf16 v[34:37], v[168:171], v[208:211], v[34:37]
	v_mfma_f32_16x16x32_bf16 v[22:25], v[150:153], v[216:219], v[22:25]
	v_mfma_f32_16x16x32_bf16 v[18:21], v[168:171], v[216:219], v[18:21]
	v_mfma_f32_16x16x32_bf16 v[6:9], v[150:153], v[224:227], v[6:9]
	v_mfma_f32_16x16x32_bf16 v[2:5], v[168:171], v[224:227], v[2:5]
	s_barrier
	s_add_u32 s0, s0, 0x100
	s_addc_u32 s1, s1, 0
	s_add_u32 s84, s84, 0x100
	s_addc_u32 s85, s85, 0
	s_cmp_ge_i32 s96, s30
	s_mov_b32 s50, s96
	s_cbranch_scc0 .LBB0_912
	v_readlane_b32 s82, v254, 45
	v_readlane_b32 s83, v254, 46
	v_readlane_b32 s96, v250, 43
